# NSA phase: per-section s_setprio flips removed, one static s_setprio 1 for waves 4-7 (younger half) per unit
# speedup vs baseline: 1.0064x; 1.0064x over previous
;     ...
;   for (int u = fetch_unit(ctr, slot); u < 1024; u = fetch_unit(ctr, slot)) {
;     const int rnd = u >> 8, b = (u & 255) >> 6, ti = u & 63;
;     const int tile = rnd == 0 ? 255 - ti : (rnd == 1 ? 128 + ti : (rnd == 2 ? 127 - ti : ti));
;     const int t0 = tile * 32, cur = t0 >> 6;
;     const h16* Pbat = P + (size_t)b * SEQ * IWP;
.LBB0_739:
	v_readfirstlane_b32 s0, v145
	s_cmp_lt_u32 s0, 0x100
	s_cbranch_scc1 .Lnsa_prio_skip
	s_setprio 1

; template <int MODE, int TM> ...
;     ...
;   __builtin_amdgcn_s_setprio(1);
; #pragma unroll
;   for (int t = 0; t < 2; ++t) {
;     if (!(TM & (1 << t))) continue;
;     const h16* Ks = t ? Ks1 : Ks0;
; #pragma unroll
;     for (int kt = 0; kt < 4; ++kt) {
;       S[t][kt] = f32x4{0.f, 0.f, 0.f, 0.f};
; #pragma unroll
;       for (int ks = 0; ks < 2; ++ks) {
;         h16x8 Kf = *(const h16x8*)(Ks + (kt * 16 + col) * KP + ks * 32 + q4 * 8);
;         S[t][kt] = __builtin_amdgcn_mfma_f32_16x16x32_f16(Kf, Q[ks], S[t][kt], 0, 0, 0);
;       }
;     }
;   }
;   __builtin_amdgcn_s_setprio(0);
;   const float* bt = biasT + hd * 800;
;   float addc[2] = {0.f, 0.f}, sclc[2] = {1.f, 1.f};
; #pragma unroll
;   for (int t = 0; t < 2; ++t) {
;     if (!(TM & (1 << t))) continue;
;     const int kbase = kbase0 + 64 * t;
;     if (far[t]) {
;       const bool ok = (MODE == M_SEL) ? selbit[t] : true;
;       addc[t] = ok ? bt[799] : -1e30f;
;       sclc[t] = SCL2;
;     } else {
;       addc[t] = 0.f;
;       sclc[t] = 1.f;
;       const int kx0 = kbase + q4 * 4;
;       const int d0 = (DK == 16) ? tq - 31 - 16 * kx0 : tq - kx0;
; #pragma unroll
;       for (int kt = 0; kt < 4; ++kt)
; #pragma unroll
;         for (int j = 0; j < 4; ++j) {
;           const int dist = d0 - DK * (kt * 16 + j);
;           const int kx = kx0 + kt * 16 + j;
;           bool valid = dist >= 0;
;           if (MODE == M_WIN) valid = valid && dist < 512 && kx >= 0;
;           if (MODE == M_SEL) valid = valid && selbit[t];
;           if (DK == 16) valid = valid && kx < NCMP;
;           const int dc = dist < 0 ? 0 : (dist > 799 ? 799 : dist);
;           S[t][kt][j] = valid ? S[t][kt][j] * SCL2 + bt[dc] : -1e30f;
.LBB0_775:
	s_lshl_b32 s3, s56, 1
	s_lshl_b32 s57, s56, 7
	s_lshl_b32 s42, s56, 11
	s_cmp_ge_i32 s42, s31
	s_cselect_b64 s[42:43], -1, 0
	s_or_b32 s3, s3, 1
	s_cmp_ge_u32 s3, s28
	s_nop 0
	ds_read_b128 v[32:35], v155 offset:12800
	ds_read_b128 v[28:31], v155 offset:12864
	s_mov_b64 s[50:51], -1
	s_cbranch_scc0 .LBB0_814
	s_waitcnt lgkmcnt(1)
	v_mfma_f32_16x16x32_f16 v[36:39], v[32:35], v[4:7], 0
	ds_read_b128 v[40:43], v155 offset:15360
	ds_read_b128 v[52:55], v155 offset:17920
	s_waitcnt lgkmcnt(2)
	v_mfma_f32_16x16x32_f16 v[48:51], v[28:31], v[8:11], v[36:39]
	s_nop 3
	ds_read_b128 v[36:39], v155 offset:15424
	s_waitcnt lgkmcnt(2)
	v_mfma_f32_16x16x32_f16 v[40:43], v[40:43], v[4:7], 0
	s_waitcnt lgkmcnt(0)
	v_mfma_f32_16x16x32_f16 v[44:47], v[36:39], v[8:11], v[40:43]
	ds_read_b128 v[36:39], v155 offset:17984
	v_mfma_f32_16x16x32_f16 v[40:43], v[52:55], v[4:7], 0
	ds_read_b128 v[52:55], v155 offset:20480
	s_waitcnt lgkmcnt(1)
	v_mfma_f32_16x16x32_f16 v[40:43], v[36:39], v[8:11], v[40:43]
	ds_read_b128 v[36:39], v155 offset:20544
	s_waitcnt lgkmcnt(1)
	v_mfma_f32_16x16x32_f16 v[52:55], v[52:55], v[4:7], 0
	s_waitcnt lgkmcnt(0)
	v_mfma_f32_16x16x32_f16 v[36:39], v[36:39], v[8:11], v[52:55]
	s_nop 0
	s_and_b64 vcc, exec, s[42:43]
	s_cbranch_vccz .LBB0_810
	v_or_b32_e32 v0, s57, v154
	v_lshlrev_b32_e32 v0, 4, v0
	s_nop 0
	v_sub_u32_e32 v54, v124, v0
	v_cmp_lt_i32_e32 vcc, -1, v54
	v_mov_b32_e32 v53, 0xf149f2ca
	v_mov_b32_e32 v52, 0xf149f2ca
	s_and_saveexec_b64 s[50:51], vcc
	s_cbranch_execz .LBB0_779
	v_min_u32_e32 v52, 0x31f, v54
	v_lshl_add_u32 v52, v52, 2, v157
	ds_read_b32 v52, v52

; template <int MODE, int TM> ...
;     ...
;   __builtin_amdgcn_s_setprio(1);
; #pragma unroll
;   for (int t = 0; t < 2; ++t) {
;     if (!(TM & (1 << t))) continue;
;     const h16* Ks = t ? Ks1 : Ks0;
; #pragma unroll
;     for (int kt = 0; kt < 4; ++kt) {
;       S[t][kt] = f32x4{0.f, 0.f, 0.f, 0.f};
; #pragma unroll
;       for (int ks = 0; ks < 2; ++ks) {
;         h16x8 Kf = *(const h16x8*)(Ks + (kt * 16 + col) * KP + ks * 32 + q4 * 8);
;         S[t][kt] = __builtin_amdgcn_mfma_f32_16x16x32_f16(Kf, Q[ks], S[t][kt], 0, 0, 0);
;       }
;     }
;   }
;   __builtin_amdgcn_s_setprio(0);
;   const float* bt = biasT + hd * 800;
;   float addc[2] = {0.f, 0.f}, sclc[2] = {1.f, 1.f};
; #pragma unroll
;   for (int t = 0; t < 2; ++t) {
;     if (!(TM & (1 << t))) continue;
;     const int kbase = kbase0 + 64 * t;
;     if (far[t]) {
;       const bool ok = (MODE == M_SEL) ? selbit[t] : true;
;       addc[t] = ok ? bt[799] : -1e30f;
;       sclc[t] = SCL2;
;     } else {
;       addc[t] = 0.f;
;       sclc[t] = 1.f;
;       const int kx0 = kbase + q4 * 4;
;       const int d0 = (DK == 16) ? tq - 31 - 16 * kx0 : tq - kx0;
; #pragma unroll
;       for (int kt = 0; kt < 4; ++kt)
; #pragma unroll
;         for (int j = 0; j < 4; ++j) {
;           const int dist = d0 - DK * (kt * 16 + j);
;           const int kx = kx0 + kt * 16 + j;
;           bool valid = dist >= 0;
;           if (MODE == M_WIN) valid = valid && dist < 512 && kx >= 0;
;           if (MODE == M_SEL) valid = valid && selbit[t];
;           if (DK == 16) valid = valid && kx < NCMP;
;           const int dc = dist < 0 ? 0 : (dist > 799 ? 799 : dist);
;           S[t][kt][j] = valid ? S[t][kt][j] * SCL2 + bt[dc] : -1e30f;
.LBB0_814:
	s_and_b64 vcc, exec, s[50:51]
	s_cbranch_vccz .LBB0_888
	s_waitcnt lgkmcnt(1)
	v_mfma_f32_16x16x32_f16 v[32:35], v[32:35], v[4:7], 0
	ds_read_b128 v[36:39], v155 offset:15360
	ds_read_b128 v[44:47], v155 offset:17920
	ds_read_b128 v[48:51], v155 offset:33280
	s_waitcnt lgkmcnt(3)
	v_mfma_f32_16x16x32_f16 v[40:43], v[28:31], v[8:11], v[32:35]
	ds_read_b128 v[28:31], v155 offset:15424
	ds_read_b128 v[52:55], v155 offset:35840
	ds_read_b128 v[56:59], v155 offset:38400
	ds_read_b128 v[60:63], v155 offset:40960
	s_waitcnt lgkmcnt(6)
	v_mfma_f32_16x16x32_f16 v[32:35], v[36:39], v[4:7], 0
	s_waitcnt lgkmcnt(3)
	v_mfma_f32_16x16x32_f16 v[36:39], v[28:31], v[8:11], v[32:35]
	ds_read_b128 v[28:31], v155 offset:17984
	v_mfma_f32_16x16x32_f16 v[32:35], v[44:47], v[4:7], 0
	ds_read_b128 v[44:47], v155 offset:20480
	s_waitcnt lgkmcnt(1)
	v_mfma_f32_16x16x32_f16 v[32:35], v[28:31], v[8:11], v[32:35]
	ds_read_b128 v[28:31], v155 offset:20544
	s_waitcnt lgkmcnt(1)
	v_mfma_f32_16x16x32_f16 v[44:47], v[44:47], v[4:7], 0
	s_waitcnt lgkmcnt(0)
	v_mfma_f32_16x16x32_f16 v[28:31], v[28:31], v[8:11], v[44:47]
	s_nop 5
	ds_read_b128 v[44:47], v155 offset:33344
	v_mfma_f32_16x16x32_f16 v[48:51], v[48:51], v[4:7], 0
	s_waitcnt lgkmcnt(0)
	v_mfma_f32_16x16x32_f16 v[44:47], v[44:47], v[8:11], v[48:51]
	s_nop 5
	ds_read_b128 v[48:51], v155 offset:35904
	v_mfma_f32_16x16x32_f16 v[52:55], v[52:55], v[4:7], 0
	s_waitcnt lgkmcnt(0)
	v_mfma_f32_16x16x32_f16 v[48:51], v[48:51], v[8:11], v[52:55]
	s_nop 5
	ds_read_b128 v[52:55], v155 offset:38464
	v_mfma_f32_16x16x32_f16 v[56:59], v[56:59], v[4:7], 0
	s_waitcnt lgkmcnt(0)
	v_mfma_f32_16x16x32_f16 v[52:55], v[52:55], v[8:11], v[56:59]
	s_nop 5
	ds_read_b128 v[56:59], v155 offset:41024
	v_mfma_f32_16x16x32_f16 v[60:63], v[60:63], v[4:7], 0
	s_waitcnt lgkmcnt(0)
	v_mfma_f32_16x16x32_f16 v[56:59], v[56:59], v[8:11], v[60:63]
	s_nop 0
	v_or_b32_e32 v0, s57, v154
	s_mov_b64 s[50:51], -1
	s_and_b64 vcc, exec, s[42:43]
	v_lshlrev_b32_e32 v77, 4, v0
	s_cbranch_vccz .LBB0_849
	v_sub_u32_e32 v0, v124, v77
	v_cmp_lt_i32_e32 vcc, -1, v0
	v_mov_b32_e32 v61, 0xf149f2ca
	v_mov_b32_e32 v60, 0xf149f2ca
	s_and_saveexec_b64 s[42:43], vcc
	s_cbranch_execz .LBB0_818
	v_min_u32_e32 v0, 0x31f, v0
	v_lshl_add_u32 v0, v0, 2, v157
	ds_read_b32 v60, v0

; template <int MODE, int TM> ...
;     ...
;   __builtin_amdgcn_s_setprio(1);
; #pragma unroll
;   for (int t = 0; t < 2; ++t) {
;     if (!(TM & (1 << t))) continue;
;     const h16* Ks = t ? Ks1 : Ks0;
; #pragma unroll
;     for (int kt = 0; kt < 4; ++kt) {
;       S[t][kt] = f32x4{0.f, 0.f, 0.f, 0.f};
; #pragma unroll
;       for (int ks = 0; ks < 2; ++ks) {
;         h16x8 Kf = *(const h16x8*)(Ks + (kt * 16 + col) * KP + ks * 32 + q4 * 8);
;         S[t][kt] = __builtin_amdgcn_mfma_f32_16x16x32_f16(Kf, Q[ks], S[t][kt], 0, 0, 0);
;       }
;     }
;   }
;   __builtin_amdgcn_s_setprio(0);
;   const float* bt = biasT + hd * 800;
;   float addc[2] = {0.f, 0.f}, sclc[2] = {1.f, 1.f};
; #pragma unroll
;   for (int t = 0; t < 2; ++t) {
;     if (!(TM & (1 << t))) continue;
;     const int kbase = kbase0 + 64 * t;
;     if (far[t]) {
;       const bool ok = (MODE == M_SEL) ? selbit[t] : true;
;       addc[t] = ok ? bt[799] : -1e30f;
;       sclc[t] = SCL2;
;     } else {
;       addc[t] = 0.f;
;       sclc[t] = 1.f;
;       const int kx0 = kbase + q4 * 4;
;       const int d0 = (DK == 16) ? tq - 31 - 16 * kx0 : tq - kx0;
; #pragma unroll
;       for (int kt = 0; kt < 4; ++kt)
; #pragma unroll
;         for (int j = 0; j < 4; ++j) {
;           const int dist = d0 - DK * (kt * 16 + j);
;           const int kx = kx0 + kt * 16 + j;
;           bool valid = dist >= 0;
;           if (MODE == M_WIN) valid = valid && dist < 512 && kx >= 0;
;           if (MODE == M_SEL) valid = valid && selbit[t];
;           if (DK == 16) valid = valid && kx < NCMP;
;           const int dc = dist < 0 ? 0 : (dist > 799 ? 799 : dist);
;           S[t][kt][j] = valid ? S[t][kt][j] * SCL2 + bt[dc] : -1e30f;
.LBB0_891:
	s_lshl_b32 s0, s2, 1
	s_lshl_b32 s3, s2, 7
	s_lshl_b32 s1, s2, 11
	s_cmp_ge_i32 s1, s31
	s_cselect_b64 s[42:43], -1, 0
	s_or_b32 s2, s0, 1
	s_cmp_lt_u32 s2, s28
	s_nop 0
	ds_read_b128 v[32:35], v155 offset:53760
	ds_read_b128 v[28:31], v155 offset:53824
	v_cndmask_b32_e64 v0, 0, 1, s[42:43]
	s_mov_b64 s[0:1], -1
	v_cmp_ne_u32_e64 s[42:43], 1, v0
	s_cbranch_scc1 .LBB0_931
	s_waitcnt lgkmcnt(1)
	v_mfma_f32_16x16x32_f16 v[36:39], v[32:35], v[4:7], 0
	ds_read_b128 v[44:47], v155 offset:56320
	ds_read_b128 v[48:51], v155 offset:58880
	ds_read_b128 v[52:55], v155 offset:61440
	s_waitcnt lgkmcnt(3)
	v_mfma_f32_16x16x32_f16 v[40:43], v[28:31], v[8:11], v[36:39]
	s_nop 2
	ds_read_b128 v[36:39], v155 offset:56384
	s_waitcnt lgkmcnt(3)
	v_mfma_f32_16x16x32_f16 v[44:47], v[44:47], v[4:7], 0
	s_waitcnt lgkmcnt(0)
	v_mfma_f32_16x16x32_f16 v[44:47], v[36:39], v[8:11], v[44:47]
	ds_read_b128 v[36:39], v155 offset:58944
	v_mfma_f32_16x16x32_f16 v[48:51], v[48:51], v[4:7], 0
	s_waitcnt lgkmcnt(0)
	v_mfma_f32_16x16x32_f16 v[48:51], v[36:39], v[8:11], v[48:51]
	ds_read_b128 v[36:39], v155 offset:61504
	v_mfma_f32_16x16x32_f16 v[52:55], v[52:55], v[4:7], 0
	s_waitcnt lgkmcnt(0)
	v_mfma_f32_16x16x32_f16 v[52:55], v[36:39], v[8:11], v[52:55]
	s_nop 0
	s_and_b64 vcc, exec, s[42:43]
	s_cbranch_vccnz .LBB0_926
	v_or_b32_e32 v0, s3, v154
	v_lshlrev_b32_e32 v0, 4, v0
	v_sub_u32_e32 v3, v124, v0
	v_cmp_lt_i32_e32 vcc, -1, v3
	v_mov_b32_e32 v37, 0xf149f2ca
	v_mov_b32_e32 v36, 0xf149f2ca
	s_and_saveexec_b64 s[0:1], vcc
	s_cbranch_execz .LBB0_895
	v_min_u32_e32 v3, 0x31f, v3
	v_lshl_add_u32 v3, v3, 2, v157
	ds_read_b32 v36, v3

; template <int MODE, int TM> ...
;     ...
;   __builtin_amdgcn_s_setprio(1);
; #pragma unroll
;   for (int t = 0; t < 2; ++t) {
;     if (!(TM & (1 << t))) continue;
;     const h16* Ks = t ? Ks1 : Ks0;
; #pragma unroll
;     for (int kt = 0; kt < 4; ++kt) {
;       S[t][kt] = f32x4{0.f, 0.f, 0.f, 0.f};
; #pragma unroll
;       for (int ks = 0; ks < 2; ++ks) {
;         h16x8 Kf = *(const h16x8*)(Ks + (kt * 16 + col) * KP + ks * 32 + q4 * 8);
;         S[t][kt] = __builtin_amdgcn_mfma_f32_16x16x32_f16(Kf, Q[ks], S[t][kt], 0, 0, 0);
;       }
;     }
;   }
;   __builtin_amdgcn_s_setprio(0);
;   const float* bt = biasT + hd * 800;
;   float addc[2] = {0.f, 0.f}, sclc[2] = {1.f, 1.f};
; #pragma unroll
;   for (int t = 0; t < 2; ++t) {
;     if (!(TM & (1 << t))) continue;
;     const int kbase = kbase0 + 64 * t;
;     if (far[t]) {
;       const bool ok = (MODE == M_SEL) ? selbit[t] : true;
;       addc[t] = ok ? bt[799] : -1e30f;
;       sclc[t] = SCL2;
;     } else {
;       addc[t] = 0.f;
;       sclc[t] = 1.f;
;       const int kx0 = kbase + q4 * 4;
;       const int d0 = (DK == 16) ? tq - 31 - 16 * kx0 : tq - kx0;
; #pragma unroll
;       for (int kt = 0; kt < 4; ++kt)
; #pragma unroll
;         for (int j = 0; j < 4; ++j) {
;           const int dist = d0 - DK * (kt * 16 + j);
;           const int kx = kx0 + kt * 16 + j;
;           bool valid = dist >= 0;
;           if (MODE == M_WIN) valid = valid && dist < 512 && kx >= 0;
;           if (MODE == M_SEL) valid = valid && selbit[t];
;           if (DK == 16) valid = valid && kx < NCMP;
;           const int dc = dist < 0 ? 0 : (dist > 799 ? 799 : dist);
;           S[t][kt][j] = valid ? S[t][kt][j] * SCL2 + bt[dc] : -1e30f;
.LBB0_931:
	s_and_b64 vcc, exec, s[0:1]
	s_cbranch_vccz .LBB0_766
	s_waitcnt lgkmcnt(1)
	v_mfma_f32_16x16x32_f16 v[32:35], v[32:35], v[4:7], 0
	ds_read_b128 v[36:39], v155 offset:56320
	ds_read_b128 v[40:43], v202 offset:5120
	ds_read_b128 v[44:47], v202 offset:7680
	s_waitcnt lgkmcnt(3)
	v_mfma_f32_16x16x32_f16 v[60:63], v[28:31], v[8:11], v[32:35]
	ds_read_b128 v[28:31], v155 offset:56384
	s_waitcnt lgkmcnt(3)
	v_mfma_f32_16x16x32_f16 v[32:35], v[36:39], v[4:7], 0
	ds_read_b128 v[36:39], v155 offset:58880
	s_waitcnt lgkmcnt(1)
	v_mfma_f32_16x16x32_f16 v[64:67], v[28:31], v[8:11], v[32:35]
	ds_read_b128 v[28:31], v155 offset:58944
	s_waitcnt lgkmcnt(1)
	v_mfma_f32_16x16x32_f16 v[32:35], v[36:39], v[4:7], 0
	ds_read_b128 v[36:39], v155 offset:61440
	s_waitcnt lgkmcnt(1)
	v_mfma_f32_16x16x32_f16 v[68:71], v[28:31], v[8:11], v[32:35]
	ds_read_b128 v[28:31], v155 offset:61504
	s_waitcnt lgkmcnt(1)
	v_mfma_f32_16x16x32_f16 v[32:35], v[36:39], v[4:7], 0
	ds_read_b128 v[36:39], v202
	s_waitcnt lgkmcnt(1)
	v_mfma_f32_16x16x32_f16 v[72:75], v[28:31], v[8:11], v[32:35]
	ds_read_b128 v[28:31], v202 offset:64
	s_waitcnt lgkmcnt(1)
	v_mfma_f32_16x16x32_f16 v[32:35], v[36:39], v[4:7], 0
	ds_read_b128 v[36:39], v202 offset:2560
	s_waitcnt lgkmcnt(1)
	v_mfma_f32_16x16x32_f16 v[32:35], v[28:31], v[8:11], v[32:35]
	ds_read_b128 v[28:31], v202 offset:2624
	s_waitcnt lgkmcnt(1)
	v_mfma_f32_16x16x32_f16 v[36:39], v[36:39], v[4:7], 0
	s_waitcnt lgkmcnt(0)
	v_mfma_f32_16x16x32_f16 v[36:39], v[28:31], v[8:11], v[36:39]
	ds_read_b128 v[28:31], v202 offset:5184
	v_mfma_f32_16x16x32_f16 v[40:43], v[40:43], v[4:7], 0
	s_waitcnt lgkmcnt(0)
	v_mfma_f32_16x16x32_f16 v[40:43], v[28:31], v[8:11], v[40:43]
	ds_read_b128 v[28:31], v202 offset:7744
	v_mfma_f32_16x16x32_f16 v[44:47], v[44:47], v[4:7], 0
	s_waitcnt lgkmcnt(0)
	v_mfma_f32_16x16x32_f16 v[44:47], v[28:31], v[8:11], v[44:47]
	s_nop 0
	v_or_b32_e32 v3, s3, v154
	s_mov_b64 s[0:1], -1
	s_and_b64 vcc, exec, s[42:43]
	v_lshlrev_b32_e32 v81, 4, v3
	s_cbranch_vccnz .LBB0_966
	v_sub_u32_e32 v0, v124, v81
	v_cmp_lt_i32_e32 vcc, -1, v0
	v_mov_b32_e32 v29, 0xf149f2ca
	v_mov_b32_e32 v28, 0xf149f2ca
	s_and_saveexec_b64 s[0:1], vcc
	s_cbranch_execz .LBB0_935
	v_min_u32_e32 v0, 0x31f, v0
	v_lshl_add_u32 v0, v0, 2, v157
	ds_read_b32 v28, v0

; template <int MODE, int TM> ...
;     ...
;   __builtin_amdgcn_s_setprio(1);
; #pragma unroll
;   for (int t = 0; t < 2; ++t) {
;     if (!(TM & (1 << t))) continue;
;     const h16* Ks = t ? Ks1 : Ks0;
; #pragma unroll
;     for (int kt = 0; kt < 4; ++kt) {
;       S[t][kt] = f32x4{0.f, 0.f, 0.f, 0.f};
; #pragma unroll
;       for (int ks = 0; ks < 2; ++ks) {
;         h16x8 Kf = *(const h16x8*)(Ks + (kt * 16 + col) * KP + ks * 32 + q4 * 8);
;         S[t][kt] = __builtin_amdgcn_mfma_f32_16x16x32_f16(Kf, Q[ks], S[t][kt], 0, 0, 0);
;       }
;     }
;   }
;   __builtin_amdgcn_s_setprio(0);
;   const float* bt = biasT + hd * 800;
;   float addc[2] = {0.f, 0.f}, sclc[2] = {1.f, 1.f};
; #pragma unroll
;   for (int t = 0; t < 2; ++t) {
;     if (!(TM & (1 << t))) continue;
;     const int kbase = kbase0 + 64 * t;
;     if (far[t]) {
;       const bool ok = (MODE == M_SEL) ? selbit[t] : true;
;       addc[t] = ok ? bt[799] : -1e30f;
;       sclc[t] = SCL2;
;     } else {
;       addc[t] = 0.f;
;       sclc[t] = 1.f;
;       const int kx0 = kbase + q4 * 4;
;       const int d0 = (DK == 16) ? tq - 31 - 16 * kx0 : tq - kx0;
; #pragma unroll
;       for (int kt = 0; kt < 4; ++kt)
; #pragma unroll
;         for (int j = 0; j < 4; ++j) {
;           const int dist = d0 - DK * (kt * 16 + j);
;           const int kx = kx0 + kt * 16 + j;
;           bool valid = dist >= 0;
;           if (MODE == M_WIN) valid = valid && dist < 512 && kx >= 0;
;           if (MODE == M_SEL) valid = valid && selbit[t];
;           if (DK == 16) valid = valid && kx < NCMP;
;           const int dc = dist < 0 ? 0 : (dist > 799 ? 799 : dist);
;           S[t][kt][j] = valid ? S[t][kt][j] * SCL2 + bt[dc] : -1e30f;
.LBB0_1047:
	s_lshl_b32 s2, s48, 1
	s_lshl_b32 s3, s48, 7
	s_lshl_b32 s42, s48, 11
	s_cmp_ge_i32 s42, s31
	s_cselect_b64 s[44:45], -1, 0
	s_or_b32 s2, s2, 1
	s_cmp_lt_u32 s2, s28
	s_cselect_b64 s[42:43], -1, 0
	s_cmp_ge_u32 s2, s28
	s_nop 0
	ds_read_b128 v[80:83], v155 offset:12800
	ds_read_b128 v[76:79], v155 offset:12864
	s_mov_b64 s[46:47], -1
	s_cbranch_scc0 .LBB0_1086
	s_waitcnt lgkmcnt(1)
	v_mfma_f32_16x16x32_f16 v[60:63], v[80:83], v[4:7], 0
	ds_read_b128 v[64:67], v155 offset:15360
	ds_read_b128 v[84:87], v155 offset:17920
	s_waitcnt lgkmcnt(2)
	v_mfma_f32_16x16x32_f16 v[68:71], v[76:79], v[8:11], v[60:63]
	s_nop 3
	ds_read_b128 v[60:63], v155 offset:15424
	s_waitcnt lgkmcnt(2)
	v_mfma_f32_16x16x32_f16 v[64:67], v[64:67], v[4:7], 0
	s_waitcnt lgkmcnt(0)
	v_mfma_f32_16x16x32_f16 v[72:75], v[60:63], v[8:11], v[64:67]
	ds_read_b128 v[60:63], v155 offset:17984
	v_mfma_f32_16x16x32_f16 v[64:67], v[84:87], v[4:7], 0
	ds_read_b128 v[84:87], v155 offset:20480
	s_waitcnt lgkmcnt(1)
	v_mfma_f32_16x16x32_f16 v[64:67], v[60:63], v[8:11], v[64:67]
	ds_read_b128 v[60:63], v155 offset:20544
	s_waitcnt lgkmcnt(1)
	v_mfma_f32_16x16x32_f16 v[84:87], v[84:87], v[4:7], 0
	s_waitcnt lgkmcnt(0)
	v_mfma_f32_16x16x32_f16 v[60:63], v[60:63], v[8:11], v[84:87]
	s_nop 0
	s_and_b64 vcc, exec, s[44:45]
	s_cbranch_vccz .LBB0_1082
	v_or_b32_e32 v0, s3, v154
	v_lshlrev_b32_e32 v0, 4, v0
	v_sub_u32_e32 v2, v124, v0
	v_cmp_lt_i32_e32 vcc, -1, v2
	v_mov_b32_e32 v85, 0xf149f2ca
	v_mov_b32_e32 v84, 0xf149f2ca
	s_and_saveexec_b64 s[46:47], vcc
	s_cbranch_execz .LBB0_1051
	v_min_u32_e32 v2, 0x31f, v2
	v_lshl_add_u32 v2, v2, 2, v157
	ds_read_b32 v84, v2

; #define LAS __attribute__((address_space(3)))
; template <int MODE, int TM> ...
;     ...
;   if (MODE == M_CMPB) {
; #pragma unroll
;     for (int t = 0; t < 2; ++t) {
;       if (!(TM & (1 << t))) continue;
; #pragma unroll
;       for (int kt = 0; kt < 4; ++kt) {
;         float h = 0.f;
; #pragma unroll
;         for (int j = 0; j < 4; ++j) {
;           float pv = __builtin_amdgcn_exp2f(S[t][kt][j] * sclc[t] + (addc[t] - st.m)) * st.l;
;           S[t][kt][j] = pv;
;           h += pv;
;         }
;         hq[t][kt] = h;
;         h3[t][kt] = S[t][kt][3];
;       }
;     ...
;   __builtin_amdgcn_s_setprio(1);
; #pragma unroll
;   for (int t = 0; t < 2; ++t) {
;     if (!(TM & (1 << t))) continue;
;     const h16* Vt = t ? Vt1 : Vt0;
; #pragma unroll
;     for (int ks = 0; ks < 2; ++ks) {
;       h16x8 Pf;
; #pragma unroll
;       for (int i = 0; i < 4; ++i) { Pf[i] = (h16)S[t][2 * ks][i]; Pf[4 + i] = (h16)S[t][2 * ks + 1][i]; }
; #pragma unroll
;       for (int nt = 0; nt < 4; ++nt) {
;         const h16* vp = Vt + (ks * 32 + q4 * 4 + (col >> 2)) * KP + nt * 16 + 4 * (col & 3);
;         const s16x4v r0 = __builtin_amdgcn_ds_read_tr16_b64_v4i16((LAS s16x4v*)vp);
;         const s16x4v r1 = __builtin_amdgcn_ds_read_tr16_b64_v4i16((LAS s16x4v*)(vp + 16 * KP));
;         const h16x4 v0 = __builtin_bit_cast(h16x4, r0), v1 = __builtin_bit_cast(h16x4, r1);
;         const h16x8 Vf = {v0[0], v0[1], v0[2], v0[3], v1[0], v1[1], v1[2], v1[3]};
;         O[nt] = __builtin_amdgcn_mfma_f32_16x16x32_f16(Vf, Pf, O[nt], 0, 0, 0);
;       }
;     }
;   }
;   __builtin_amdgcn_s_setprio(0);
.LBB0_1085:
	s_waitcnt lgkmcnt(0)
	v_sub_f32_e32 v0, v0, v125
	v_fma_f32 v3, s46, v69, v0
	v_fma_f32 v2, s46, v68, v0
	v_exp_f32_e32 v68, v3
	v_fma_f32 v3, s46, v70, v0
	v_exp_f32_e32 v70, v3
	v_fma_f32 v3, s46, v71, v0
	v_exp_f32_e32 v86, v3
	v_fma_f32 v3, s46, v72, v0
	v_exp_f32_e32 v2, v2
	v_exp_f32_e32 v3, v3
	v_fma_f32 v69, s46, v73, v0
	v_exp_f32_e32 v69, v69
	v_fma_f32 v71, s46, v74, v0
	v_exp_f32_e32 v71, v71
	v_fma_f32 v72, s46, v75, v0
	v_exp_f32_e32 v87, v72
	v_pk_mul_f32 v[72:73], v[114:115], v[2:3]
	v_pk_fma_f32 v[2:3], v[114:115], v[2:3], 0 op_sel_hi:[1,1,0]
	v_fma_f32 v65, s46, v65, v0
	v_pk_fma_f32 v[2:3], v[114:115], v[68:69], v[2:3]
	v_pk_mul_f32 v[74:75], v[114:115], v[68:69]
	v_pk_mul_f32 v[68:69], v[114:115], v[70:71]
	v_pk_fma_f32 v[2:3], v[114:115], v[70:71], v[2:3]
	v_exp_f32_e32 v70, v65
	v_fma_f32 v65, s46, v66, v0
	v_fma_f32 v64, s46, v64, v0
	v_exp_f32_e32 v66, v65
	v_fma_f32 v65, s46, v67, v0
	v_fma_f32 v60, s46, v60, v0
	v_pk_mul_f32 v[84:85], v[114:115], v[86:87]
	v_pk_fma_f32 v[2:3], v[114:115], v[86:87], v[2:3]
	v_exp_f32_e32 v64, v64
	v_exp_f32_e32 v86, v65
	v_exp_f32_e32 v65, v60
	v_fma_f32 v60, s46, v61, v0
	v_exp_f32_e32 v71, v60
	v_fma_f32 v60, s46, v62, v0
	v_exp_f32_e32 v67, v60
	v_fmac_f32_e32 v0, s46, v63
	v_exp_f32_e32 v87, v0
	v_pk_fma_f32 v[60:61], v[114:115], v[64:65], 0 op_sel_hi:[1,1,0]
	v_pk_mul_f32 v[94:95], v[114:115], v[64:65]
	v_pk_fma_f32 v[60:61], v[114:115], v[70:71], v[60:61]
	v_pk_mul_f32 v[88:89], v[114:115], v[86:87]
	v_pk_fma_f32 v[60:61], v[114:115], v[66:67], v[60:61]
	v_pk_mul_f32 v[98:99], v[114:115], v[70:71]
	v_pk_fma_f32 v[86:87], v[114:115], v[86:87], v[60:61]
	v_pk_mul_f32 v[100:101], v[114:115], v[66:67]
	s_nop 0
	v_cvt_pk_f16_f32 v63, v69, v85
	v_cvt_pk_f16_f32 v61, v68, v84
	ds_read_b64_tr_b16 v[66:67], v205 offset:25600
	ds_read_b64_tr_b16 v[64:65], v205 offset:23040
	ds_read_b64_tr_b16 v[68:69], v205 offset:23072
	ds_read_b64_tr_b16 v[70:71], v205 offset:25632
	v_cvt_pk_f16_f32 v62, v73, v75
	v_cvt_pk_f16_f32 v60, v72, v74
	ds_read_b64_tr_b16 v[72:73], v205 offset:23104
	ds_read_b64_tr_b16 v[74:75], v205 offset:25664
	ds_read_b64_tr_b16 v[90:91], v205 offset:23136
	ds_read_b64_tr_b16 v[92:93], v205 offset:25696
	s_waitcnt lgkmcnt(6)
	v_mfma_f32_16x16x32_f16 v[64:67], v[64:67], v[60:63], v[12:15]
	v_cvt_pk_f16_f32 v97, v101, v89
	v_cvt_pk_f16_f32 v96, v95, v99
	v_cvt_pk_f16_f32 v95, v100, v88
	s_waitcnt lgkmcnt(4)
	v_mfma_f32_16x16x32_f16 v[68:71], v[68:71], v[60:63], v[16:19]
	v_cvt_pk_f16_f32 v94, v94, v98
	s_mov_b64 s[46:47], 0
	s_waitcnt lgkmcnt(2)
	v_mfma_f32_16x16x32_f16 v[72:75], v[72:75], v[60:63], v[20:23]
	s_waitcnt lgkmcnt(0)
	v_mfma_f32_16x16x32_f16 v[90:93], v[90:93], v[60:63], v[24:27]
	ds_read_b64_tr_b16 v[60:61], v205 offset:28160
	ds_read_b64_tr_b16 v[62:63], v205 offset:30720
	s_waitcnt lgkmcnt(0)
	v_mfma_f32_16x16x32_f16 v[60:63], v[60:63], v[94:97], v[64:67]
	s_nop 2
	ds_read_b64_tr_b16 v[64:65], v205 offset:28192
	ds_read_b64_tr_b16 v[66:67], v205 offset:30752
	s_waitcnt lgkmcnt(0)
	v_mfma_f32_16x16x32_f16 v[64:67], v[64:67], v[94:97], v[68:71]
	s_nop 2
	ds_read_b64_tr_b16 v[68:69], v205 offset:28224
	ds_read_b64_tr_b16 v[70:71], v205 offset:30784
	s_waitcnt lgkmcnt(0)
	v_mfma_f32_16x16x32_f16 v[68:71], v[68:71], v[94:97], v[72:75]
	s_nop 2
	ds_read_b64_tr_b16 v[72:73], v205 offset:28256
	ds_read_b64_tr_b16 v[74:75], v205 offset:30816
	s_waitcnt lgkmcnt(0)
	v_mfma_f32_16x16x32_f16 v[72:75], v[72:75], v[94:97], v[90:93]
.LBB0_1086:
	s_and_b64 vcc, exec, s[46:47]
	s_cbranch_vccz .LBB0_1160
	s_waitcnt lgkmcnt(1)
	v_mfma_f32_16x16x32_f16 v[60:63], v[80:83], v[4:7], 0
	ds_read_b128 v[64:67], v155 offset:15360
	ds_read_b128 v[80:83], v155 offset:33280
	ds_read_b128 v[84:87], v155 offset:35840
	s_waitcnt lgkmcnt(3)
	v_mfma_f32_16x16x32_f16 v[68:71], v[76:79], v[8:11], v[60:63]
	ds_read_b128 v[76:79], v155 offset:17920
	ds_read_b128 v[88:91], v155 offset:38400
	ds_read_b128 v[92:95], v155 offset:40960
	ds_read_b128 v[60:63], v155 offset:15424
	s_waitcnt lgkmcnt(6)
	v_mfma_f32_16x16x32_f16 v[64:67], v[64:67], v[4:7], 0
	s_waitcnt lgkmcnt(0)
	v_mfma_f32_16x16x32_f16 v[72:75], v[60:63], v[8:11], v[64:67]
	ds_read_b128 v[60:63], v155 offset:17984
	v_mfma_f32_16x16x32_f16 v[64:67], v[76:79], v[4:7], 0
	ds_read_b128 v[76:79], v155 offset:20480
	s_waitcnt lgkmcnt(1)
	v_mfma_f32_16x16x32_f16 v[64:67], v[60:63], v[8:11], v[64:67]
	ds_read_b128 v[60:63], v155 offset:20544
	s_waitcnt lgkmcnt(1)
	v_mfma_f32_16x16x32_f16 v[76:79], v[76:79], v[4:7], 0
	s_waitcnt lgkmcnt(0)
	v_mfma_f32_16x16x32_f16 v[60:63], v[60:63], v[8:11], v[76:79]
	s_nop 5
	ds_read_b128 v[76:79], v155 offset:33344
	v_mfma_f32_16x16x32_f16 v[80:83], v[80:83], v[4:7], 0
	s_waitcnt lgkmcnt(0)
	v_mfma_f32_16x16x32_f16 v[76:79], v[76:79], v[8:11], v[80:83]
	s_nop 5
	ds_read_b128 v[80:83], v155 offset:35904
	v_mfma_f32_16x16x32_f16 v[84:87], v[84:87], v[4:7], 0
	s_waitcnt lgkmcnt(0)
	v_mfma_f32_16x16x32_f16 v[80:83], v[80:83], v[8:11], v[84:87]
	s_nop 5
	ds_read_b128 v[84:87], v155 offset:38464
	v_mfma_f32_16x16x32_f16 v[88:91], v[88:91], v[4:7], 0
	s_waitcnt lgkmcnt(0)
	v_mfma_f32_16x16x32_f16 v[84:87], v[84:87], v[8:11], v[88:91]
	s_nop 5
	ds_read_b128 v[88:91], v155 offset:41024
	v_mfma_f32_16x16x32_f16 v[92:95], v[92:95], v[4:7], 0
	s_waitcnt lgkmcnt(0)
	v_mfma_f32_16x16x32_f16 v[88:91], v[88:91], v[8:11], v[92:95]
	s_nop 0
	v_or_b32_e32 v0, s3, v154
	s_mov_b64 s[46:47], -1
	s_and_b64 vcc, exec, s[44:45]
	v_lshlrev_b32_e32 v2, 4, v0
	s_cbranch_vccz .LBB0_1121
	v_sub_u32_e32 v0, v124, v2
	v_cmp_lt_i32_e32 vcc, -1, v0
	v_mov_b32_e32 v93, 0xf149f2ca
	v_mov_b32_e32 v92, 0xf149f2ca
	s_and_saveexec_b64 s[44:45], vcc
	s_cbranch_execz .LBB0_1090
	v_min_u32_e32 v0, 0x31f, v0
	v_lshl_add_u32 v0, v0, 2, v157
	ds_read_b32 v92, v0

; #define LAS __attribute__((address_space(3)))
; template <int MODE, int TM> ...
;     ...
;   if (MODE == M_CMPB) {
; #pragma unroll
;     for (int t = 0; t < 2; ++t) {
;       if (!(TM & (1 << t))) continue;
; #pragma unroll
;       for (int kt = 0; kt < 4; ++kt) {
;         float h = 0.f;
; #pragma unroll
;         for (int j = 0; j < 4; ++j) {
;           float pv = __builtin_amdgcn_exp2f(S[t][kt][j] * sclc[t] + (addc[t] - st.m)) * st.l;
;           S[t][kt][j] = pv;
;           h += pv;
;         }
;         hq[t][kt] = h;
;         h3[t][kt] = S[t][kt][3];
;       }
;     ...
;   __builtin_amdgcn_s_setprio(1);
; #pragma unroll
;   for (int t = 0; t < 2; ++t) {
;     if (!(TM & (1 << t))) continue;
;     const h16* Vt = t ? Vt1 : Vt0;
; #pragma unroll
;     for (int ks = 0; ks < 2; ++ks) {
;       h16x8 Pf;
; #pragma unroll
;       for (int i = 0; i < 4; ++i) { Pf[i] = (h16)S[t][2 * ks][i]; Pf[4 + i] = (h16)S[t][2 * ks + 1][i]; }
; #pragma unroll
;       for (int nt = 0; nt < 4; ++nt) {
;         const h16* vp = Vt + (ks * 32 + q4 * 4 + (col >> 2)) * KP + nt * 16 + 4 * (col & 3);
;         const s16x4v r0 = __builtin_amdgcn_ds_read_tr16_b64_v4i16((LAS s16x4v*)vp);
;         const s16x4v r1 = __builtin_amdgcn_ds_read_tr16_b64_v4i16((LAS s16x4v*)(vp + 16 * KP));
;         const h16x4 v0 = __builtin_bit_cast(h16x4, r0), v1 = __builtin_bit_cast(h16x4, r1);
;         const h16x8 Vf = {v0[0], v0[1], v0[2], v0[3], v1[0], v1[1], v1[2], v1[3]};
;         O[nt] = __builtin_amdgcn_mfma_f32_16x16x32_f16(Vf, Pf, O[nt], 0, 0, 0);
;       }
;     }
;   }
;   __builtin_amdgcn_s_setprio(0);
.LBB0_1159:
	s_waitcnt lgkmcnt(0)
	v_sub_f32_e32 v0, v120, v125
	v_fma_f32 v3, s3, v69, v0
	v_fma_f32 v2, s3, v68, v0
	v_exp_f32_e32 v68, v3
	v_fma_f32 v3, s3, v70, v0
	v_exp_f32_e32 v70, v3
	v_fma_f32 v3, s3, v71, v0
	v_exp_f32_e32 v76, v3
	v_fma_f32 v3, s3, v72, v0
	v_exp_f32_e32 v2, v2
	v_exp_f32_e32 v3, v3
	v_fma_f32 v69, s3, v73, v0
	v_exp_f32_e32 v69, v69
	v_fma_f32 v71, s3, v74, v0
	v_exp_f32_e32 v71, v71
	v_fma_f32 v72, s3, v75, v0
	v_exp_f32_e32 v77, v72
	v_pk_mul_f32 v[72:73], v[114:115], v[2:3]
	v_pk_fma_f32 v[2:3], v[114:115], v[2:3], 0 op_sel_hi:[1,1,0]
	v_fma_f32 v65, s3, v65, v0
	v_pk_mul_f32 v[74:75], v[114:115], v[68:69]
	v_pk_fma_f32 v[2:3], v[114:115], v[68:69], v[2:3]
	v_exp_f32_e32 v68, v65
	v_fma_f32 v65, s3, v66, v0
	v_fma_f32 v64, s3, v64, v0
	v_exp_f32_e32 v66, v65
	v_fma_f32 v65, s3, v67, v0
	v_fma_f32 v60, s3, v60, v0
	v_pk_mul_f32 v[78:79], v[114:115], v[70:71]
	v_pk_fma_f32 v[2:3], v[114:115], v[70:71], v[2:3]
	v_exp_f32_e32 v64, v64
	v_exp_f32_e32 v70, v65
	v_exp_f32_e32 v65, v60
	v_fma_f32 v60, s3, v61, v0
	v_exp_f32_e32 v69, v60
	v_fma_f32 v60, s3, v62, v0
	v_exp_f32_e32 v67, v60
	v_fmac_f32_e32 v0, s3, v63
	v_exp_f32_e32 v71, v0
	v_pk_fma_f32 v[60:61], v[114:115], v[64:65], 0 op_sel_hi:[1,1,0]
	v_sub_f32_e32 v0, v121, v125
	v_pk_fma_f32 v[60:61], v[114:115], v[68:69], v[60:61]
	v_pk_mul_f32 v[80:81], v[114:115], v[64:65]
	v_pk_fma_f32 v[60:61], v[114:115], v[66:67], v[60:61]
	v_pk_mul_f32 v[122:123], v[114:115], v[66:67]
	v_pk_fma_f32 v[86:87], v[114:115], v[70:71], v[60:61]
	v_fma_f32 v61, s2, v93, v0
	v_exp_f32_e32 v62, v61
	v_fma_f32 v61, s2, v94, v0
	v_exp_f32_e32 v64, v61
	v_fma_f32 v61, s2, v95, v0
	v_fma_f32 v60, s2, v92, v0
	v_exp_f32_e32 v66, v61
	v_fma_f32 v61, s2, v96, v0
	v_exp_f32_e32 v60, v60
	v_exp_f32_e32 v61, v61
	v_fma_f32 v63, s2, v97, v0
	v_exp_f32_e32 v63, v63
	v_fma_f32 v65, s2, v98, v0
	v_exp_f32_e32 v65, v65
	v_fma_f32 v67, s2, v99, v0
	v_exp_f32_e32 v67, v67
	v_pk_mul_f32 v[98:99], v[114:115], v[60:61]
	v_pk_fma_f32 v[60:61], v[114:115], v[60:61], 0 op_sel_hi:[1,1,0]
	v_pk_mul_f32 v[120:121], v[114:115], v[62:63]
	v_pk_fma_f32 v[60:61], v[114:115], v[62:63], v[60:61]
	v_pk_mul_f32 v[184:185], v[114:115], v[64:65]
	v_pk_fma_f32 v[60:61], v[114:115], v[64:65], v[60:61]
	v_pk_mul_f32 v[96:97], v[114:115], v[66:67]
	v_pk_fma_f32 v[92:93], v[114:115], v[66:67], v[60:61]
	v_fma_f32 v60, s2, v100, v0
	v_exp_f32_e32 v62, v60
	v_fma_f32 v60, s2, v101, v0
	v_exp_f32_e32 v64, v60
	v_fma_f32 v60, s2, v102, v0
	v_exp_f32_e32 v66, v60
	v_fma_f32 v60, s2, v103, v0
	v_pk_mul_f32 v[82:83], v[114:115], v[68:69]
	v_exp_f32_e32 v68, v60
	v_fma_f32 v60, s2, v104, v0
	v_exp_f32_e32 v63, v60
	v_fma_f32 v60, s2, v105, v0
	v_exp_f32_e32 v65, v60
	v_fma_f32 v60, s2, v106, v0
	v_exp_f32_e32 v67, v60
	v_fmac_f32_e32 v0, s2, v107
	v_exp_f32_e32 v69, v0
	v_pk_mul_f32 v[88:89], v[114:115], v[70:71]
	v_pk_fma_f32 v[70:71], v[114:115], v[62:63], 0 op_sel_hi:[1,1,0]
	v_pk_mul_f32 v[60:61], v[114:115], v[62:63]
	v_pk_fma_f32 v[70:71], v[114:115], v[64:65], v[70:71]
	v_pk_mul_f32 v[62:63], v[114:115], v[64:65]
	v_pk_mul_f32 v[64:65], v[114:115], v[66:67]
	v_pk_fma_f32 v[66:67], v[114:115], v[66:67], v[70:71]
	v_pk_mul_f32 v[84:85], v[114:115], v[76:77]
	v_pk_fma_f32 v[2:3], v[114:115], v[76:77], v[2:3]
	v_pk_mul_f32 v[94:95], v[114:115], v[68:69]
	v_pk_fma_f32 v[90:91], v[114:115], v[68:69], v[66:67]
	s_nop 0
	v_cvt_pk_f16_f32 v68, v73, v75
	v_cvt_pk_f16_f32 v66, v72, v74
	ds_read_b64_tr_b16 v[72:73], v205 offset:25600
	ds_read_b64_tr_b16 v[70:71], v205 offset:23040
	ds_read_b64_tr_b16 v[74:75], v205 offset:23072
	v_cvt_pk_f16_f32 v69, v79, v85
	v_cvt_pk_f16_f32 v67, v78, v84
	ds_read_b64_tr_b16 v[76:77], v205 offset:25632
	s_waitcnt lgkmcnt(2)
	v_mfma_f32_16x16x32_f16 v[12:15], v[70:73], v[66:69], v[12:15]
	ds_read_b64_tr_b16 v[70:71], v205 offset:23104
	ds_read_b64_tr_b16 v[72:73], v205 offset:25664
	s_waitcnt lgkmcnt(0)
	v_mfma_f32_16x16x32_f16 v[20:23], v[70:73], v[66:69], v[20:23]
	ds_read_b64_tr_b16 v[70:71], v205 offset:23136
	ds_read_b64_tr_b16 v[72:73], v205 offset:25696
	s_waitcnt lgkmcnt(0)
	v_mfma_f32_16x16x32_f16 v[24:27], v[70:73], v[66:69], v[24:27]
	ds_read_b64_tr_b16 v[70:71], v205 offset:28160
	ds_read_b64_tr_b16 v[72:73], v205 offset:30720
	v_mfma_f32_16x16x32_f16 v[16:19], v[74:77], v[66:69], v[16:19]
	v_cvt_pk_f16_f32 v69, v123, v89
	v_cvt_pk_f16_f32 v68, v81, v83
	v_cvt_pk_f16_f32 v67, v122, v88
	v_cvt_pk_f16_f32 v66, v80, v82
	v_cvt_pk_f16_f32 v74, v61, v63
	v_cvt_pk_f16_f32 v75, v65, v95
	s_waitcnt lgkmcnt(0)
	v_mfma_f32_16x16x32_f16 v[12:15], v[70:73], v[66:69], v[12:15]
	ds_read_b64_tr_b16 v[70:71], v205 offset:28192
	ds_read_b64_tr_b16 v[72:73], v205 offset:30752
	s_waitcnt lgkmcnt(0)
	v_mfma_f32_16x16x32_f16 v[16:19], v[70:73], v[66:69], v[16:19]
	ds_read_b64_tr_b16 v[70:71], v205 offset:28224
	ds_read_b64_tr_b16 v[72:73], v205 offset:30784
	s_waitcnt lgkmcnt(0)
	v_mfma_f32_16x16x32_f16 v[20:23], v[70:73], v[66:69], v[20:23]
	ds_read_b64_tr_b16 v[70:71], v205 offset:28256
	ds_read_b64_tr_b16 v[72:73], v205 offset:30816
	s_waitcnt lgkmcnt(0)
	v_mfma_f32_16x16x32_f16 v[24:27], v[70:73], v[66:69], v[24:27]
	ds_read_b64_tr_b16 v[70:71], v205 offset:43520
	ds_read_b64_tr_b16 v[72:73], v205 offset:46080
	v_cvt_pk_f16_f32 v69, v185, v97
	v_cvt_pk_f16_f32 v68, v99, v121
	v_cvt_pk_f16_f32 v67, v184, v96
	v_cvt_pk_f16_f32 v66, v98, v120
	s_waitcnt lgkmcnt(0)
	s_nop 0
	v_mfma_f32_16x16x32_f16 v[12:15], v[70:73], v[66:69], v[12:15]
	ds_read_b64_tr_b16 v[70:71], v205 offset:43552
	ds_read_b64_tr_b16 v[72:73], v205 offset:46112
	s_waitcnt lgkmcnt(0)
	v_mfma_f32_16x16x32_f16 v[16:19], v[70:73], v[66:69], v[16:19]
	ds_read_b64_tr_b16 v[70:71], v205 offset:43584
	ds_read_b64_tr_b16 v[72:73], v205 offset:46144
	s_waitcnt lgkmcnt(0)
	v_mfma_f32_16x16x32_f16 v[20:23], v[70:73], v[66:69], v[20:23]
	ds_read_b64_tr_b16 v[70:71], v205 offset:43616
	ds_read_b64_tr_b16 v[72:73], v205 offset:46176
	s_waitcnt lgkmcnt(0)
	v_mfma_f32_16x16x32_f16 v[24:27], v[70:73], v[66:69], v[24:27]
	v_cvt_pk_f16_f32 v72, v60, v62
	ds_read_b64_tr_b16 v[60:61], v205 offset:48640
	ds_read_b64_tr_b16 v[62:63], v205 offset:51200
	v_cvt_pk_f16_f32 v73, v64, v94
	s_waitcnt lgkmcnt(0)
	s_nop 0
	v_mfma_f32_16x16x32_f16 v[60:63], v[60:63], v[72:75], v[12:15]
	s_nop 2
	ds_read_b64_tr_b16 v[12:13], v205 offset:48672
	ds_read_b64_tr_b16 v[14:15], v205 offset:51232
	s_waitcnt lgkmcnt(0)
	v_mfma_f32_16x16x32_f16 v[64:67], v[12:15], v[72:75], v[16:19]
	ds_read_b64_tr_b16 v[12:13], v205 offset:48704
	ds_read_b64_tr_b16 v[14:15], v205 offset:51264
	s_waitcnt lgkmcnt(0)
	v_mfma_f32_16x16x32_f16 v[68:71], v[12:15], v[72:75], v[20:23]
	ds_read_b64_tr_b16 v[12:13], v205 offset:48736
	ds_read_b64_tr_b16 v[14:15], v205 offset:51296
	s_waitcnt lgkmcnt(0)
	v_mfma_f32_16x16x32_f16 v[72:75], v[12:15], v[72:75], v[24:27]
; __device__ __forceinline__ float quadsum(float v) { v += dppf<0xB1>(v); v += dppf<0x4E>(v); return v; }
;     ...
;         float t3p = carry;
; #pragma unroll
;         for (int t = 0; t < 2; ++t) {
;           if (t == 1 && !two) break;
; #pragma unroll
;           for (int kt = 0; kt < 4; ++kt) {
;             const float qs = quadsum(hq[t][kt]);
;             const float t3 = quadsum(h3[t][kt]);
;             const float up = __shfl(t3, (lane + 48) & 63);
;             const float wrp = __shfl(t3p, (lane + 48) & 63);
;             const float pk = (q4 == 0) ? wrp : up;
;             if (hd == 0) impw[qw * 128 + (2 * i + t) * 16 + kt * 4 + q4] = qs + pk;
;             t3p = t3;
;           }
;         }
;         carry = t3p;
.LBB0_1160:
	s_nop 0
	v_add_f32_dpp v0, v84, v84 quad_perm:[1,0,3,2] row_mask:0xf bank_mask:0xf bound_ctrl:1
	ds_bpermute_b32 v14, v126, v127
	s_lshl_b32 s2, s48, 5
	v_add_f32_dpp v12, v0, v0 quad_perm:[2,3,0,1] row_mask:0xf bank_mask:0xf bound_ctrl:1
	ds_bpermute_b32 v13, v126, v12
	v_add_f32_dpp v2, v2, v2 quad_perm:[1,0,3,2] row_mask:0xf bank_mask:0xf bound_ctrl:1
	v_lshl_add_u32 v0, s2, 2, v210
	s_nop 0
	v_mov_b32_dpp v15, v2 quad_perm:[2,3,0,1] row_mask:0xf bank_mask:0xf bound_ctrl:1
	s_and_saveexec_b64 s[44:45], s[16:17]
	s_cbranch_execz .LBB0_1162
	v_add_f32_e32 v2, v2, v15
	s_waitcnt lgkmcnt(0)
	v_cndmask_b32_e64 v13, v13, v14, s[18:19]
	v_add_f32_e32 v2, v2, v13
	ds_write_b32 v0, v2

; template <int MODE, int TM> ...
;     ...
;   __builtin_amdgcn_s_setprio(1);
; #pragma unroll
;   for (int t = 0; t < 2; ++t) {
;     if (!(TM & (1 << t))) continue;
;     const h16* Ks = t ? Ks1 : Ks0;
; #pragma unroll
;     for (int kt = 0; kt < 4; ++kt) {
;       S[t][kt] = f32x4{0.f, 0.f, 0.f, 0.f};
; #pragma unroll
;       for (int ks = 0; ks < 2; ++ks) {
;         h16x8 Kf = *(const h16x8*)(Ks + (kt * 16 + col) * KP + ks * 32 + q4 * 8);
;         S[t][kt] = __builtin_amdgcn_mfma_f32_16x16x32_f16(Kf, Q[ks], S[t][kt], 0, 0, 0);
;       }
;     }
;   }
;   __builtin_amdgcn_s_setprio(0);
;   const float* bt = biasT + hd * 800;
;   float addc[2] = {0.f, 0.f}, sclc[2] = {1.f, 1.f};
; #pragma unroll
;   for (int t = 0; t < 2; ++t) {
;     if (!(TM & (1 << t))) continue;
;     const int kbase = kbase0 + 64 * t;
;     if (far[t]) {
;       const bool ok = (MODE == M_SEL) ? selbit[t] : true;
;       addc[t] = ok ? bt[799] : -1e30f;
;       sclc[t] = SCL2;
;     } else {
;       addc[t] = 0.f;
;       sclc[t] = 1.f;
;       const int kx0 = kbase + q4 * 4;
;       const int d0 = (DK == 16) ? tq - 31 - 16 * kx0 : tq - kx0;
; #pragma unroll
;       for (int kt = 0; kt < 4; ++kt)
; #pragma unroll
;         for (int j = 0; j < 4; ++j) {
;           const int dist = d0 - DK * (kt * 16 + j);
;           const int kx = kx0 + kt * 16 + j;
;           bool valid = dist >= 0;
;           if (MODE == M_WIN) valid = valid && dist < 512 && kx >= 0;
;           if (MODE == M_SEL) valid = valid && selbit[t];
;           if (DK == 16) valid = valid && kx < NCMP;
;           const int dc = dist < 0 ? 0 : (dist > 799 ? 799 : dist);
;           S[t][kt][j] = valid ? S[t][kt][j] * SCL2 + bt[dc] : -1e30f;
.LBB0_1181:
	s_lshl_b32 s0, s49, 1
	s_lshl_b32 s3, s49, 7
	s_lshl_b32 s1, s49, 11
	s_cmp_ge_i32 s1, s31
	s_cselect_b64 s[42:43], -1, 0
	s_or_b32 s2, s0, 1
	s_cmp_lt_u32 s2, s28
	s_cselect_b64 s[44:45], -1, 0
	s_nop 0
	ds_read_b128 v[80:83], v155 offset:53760
	ds_read_b128 v[76:79], v155 offset:53824
	v_cndmask_b32_e64 v0, 0, 1, s[42:43]
	s_mov_b64 s[0:1], -1
	s_and_b64 vcc, exec, s[44:45]
	v_cmp_ne_u32_e64 s[42:43], 1, v0
	s_cbranch_vccnz .LBB0_1221
	ds_read_b128 v[16:19], v155 offset:56320
	ds_read_b128 v[20:23], v155 offset:56384
	ds_read_b128 v[24:27], v155 offset:58880
	ds_read_b128 v[84:87], v155 offset:61440
	s_waitcnt lgkmcnt(5)
	v_mfma_f32_16x16x32_f16 v[12:15], v[80:83], v[4:7], 0
	s_waitcnt lgkmcnt(4)
	v_mfma_f32_16x16x32_f16 v[12:15], v[76:79], v[8:11], v[12:15]
	s_waitcnt lgkmcnt(3)
	v_mfma_f32_16x16x32_f16 v[16:19], v[16:19], v[4:7], 0
	s_waitcnt lgkmcnt(2)
	v_mfma_f32_16x16x32_f16 v[16:19], v[20:23], v[8:11], v[16:19]
	ds_read_b128 v[20:23], v155 offset:58944
	s_waitcnt lgkmcnt(2)
	v_mfma_f32_16x16x32_f16 v[24:27], v[24:27], v[4:7], 0
	s_waitcnt lgkmcnt(0)
	v_mfma_f32_16x16x32_f16 v[24:27], v[20:23], v[8:11], v[24:27]
	ds_read_b128 v[20:23], v155 offset:61504
	v_mfma_f32_16x16x32_f16 v[84:87], v[84:87], v[4:7], 0
	s_waitcnt lgkmcnt(0)
	v_mfma_f32_16x16x32_f16 v[84:87], v[20:23], v[8:11], v[84:87]
	s_nop 0
	s_and_b64 vcc, exec, s[42:43]
	s_cbranch_vccnz .LBB0_1216
	v_or_b32_e32 v0, s3, v154
	v_lshlrev_b32_e32 v0, 4, v0
	v_sub_u32_e32 v2, v124, v0
	v_cmp_lt_i32_e32 vcc, -1, v2
	v_mov_b32_e32 v21, 0xf149f2ca
	v_mov_b32_e32 v20, 0xf149f2ca
	s_and_saveexec_b64 s[0:1], vcc
	s_cbranch_execz .LBB0_1185
	v_min_u32_e32 v2, 0x31f, v2
	v_lshl_add_u32 v2, v2, 2, v157
	ds_read_b32 v20, v2

; #define LAS __attribute__((address_space(3)))
; template <int MODE, int TM> ...
;     ...
;   if (MODE == M_CMPB) {
; #pragma unroll
;     for (int t = 0; t < 2; ++t) {
;       if (!(TM & (1 << t))) continue;
; #pragma unroll
;       for (int kt = 0; kt < 4; ++kt) {
;         float h = 0.f;
; #pragma unroll
;         for (int j = 0; j < 4; ++j) {
;           float pv = __builtin_amdgcn_exp2f(S[t][kt][j] * sclc[t] + (addc[t] - st.m)) * st.l;
;           S[t][kt][j] = pv;
;           h += pv;
;         }
;         hq[t][kt] = h;
;         h3[t][kt] = S[t][kt][3];
;       }
;     ...
;   __builtin_amdgcn_s_setprio(1);
; #pragma unroll
;   for (int t = 0; t < 2; ++t) {
;     if (!(TM & (1 << t))) continue;
;     const h16* Vt = t ? Vt1 : Vt0;
; #pragma unroll
;     for (int ks = 0; ks < 2; ++ks) {
;       h16x8 Pf;
; #pragma unroll
;       for (int i = 0; i < 4; ++i) { Pf[i] = (h16)S[t][2 * ks][i]; Pf[4 + i] = (h16)S[t][2 * ks + 1][i]; }
; #pragma unroll
;       for (int nt = 0; nt < 4; ++nt) {
;         const h16* vp = Vt + (ks * 32 + q4 * 4 + (col >> 2)) * KP + nt * 16 + 4 * (col & 3);
;         const s16x4v r0 = __builtin_amdgcn_ds_read_tr16_b64_v4i16((LAS s16x4v*)vp);
;         const s16x4v r1 = __builtin_amdgcn_ds_read_tr16_b64_v4i16((LAS s16x4v*)(vp + 16 * KP));
;         const h16x4 v0 = __builtin_bit_cast(h16x4, r0), v1 = __builtin_bit_cast(h16x4, r1);
;         const h16x8 Vf = {v0[0], v0[1], v0[2], v0[3], v1[0], v1[1], v1[2], v1[3]};
;         O[nt] = __builtin_amdgcn_mfma_f32_16x16x32_f16(Vf, Pf, O[nt], 0, 0, 0);
;       }
;     }
;   }
;   __builtin_amdgcn_s_setprio(0);
.LBB0_1220:
	s_waitcnt lgkmcnt(0)
	v_sub_f32_e32 v0, v0, v125
	v_fma_f32 v3, s0, v21, v0
	v_exp_f32_e32 v12, v3
	v_fma_f32 v3, s0, v22, v0
	v_exp_f32_e32 v14, v3
	v_fma_f32 v3, s0, v23, v0
	v_fma_f32 v2, s0, v20, v0
	v_exp_f32_e32 v16, v3
	v_fma_f32 v3, s0, v88, v0
	v_exp_f32_e32 v2, v2
	v_exp_f32_e32 v3, v3
	v_fma_f32 v13, s0, v89, v0
	v_exp_f32_e32 v13, v13
	v_fma_f32 v15, s0, v90, v0
	v_exp_f32_e32 v15, v15
	v_fma_f32 v17, s0, v91, v0
	v_exp_f32_e32 v17, v17
	v_pk_mul_f32 v[18:19], v[114:115], v[2:3]
	v_pk_fma_f32 v[2:3], v[114:115], v[2:3], 0 op_sel_hi:[1,1,0]
	v_pk_mul_f32 v[20:21], v[114:115], v[12:13]
	v_pk_fma_f32 v[2:3], v[114:115], v[12:13], v[2:3]
	v_pk_mul_f32 v[12:13], v[114:115], v[14:15]
	v_pk_fma_f32 v[2:3], v[114:115], v[14:15], v[2:3]
	v_fma_f32 v15, s0, v93, v0
	v_pk_mul_f32 v[120:121], v[114:115], v[16:17]
	v_pk_fma_f32 v[2:3], v[114:115], v[16:17], v[2:3]
	v_exp_f32_e32 v16, v15
	v_fma_f32 v15, s0, v94, v0
	v_exp_f32_e32 v22, v15
	v_fma_f32 v15, s0, v95, v0
	v_fma_f32 v14, s0, v92, v0
	v_exp_f32_e32 v24, v15
	v_fma_f32 v15, s0, v96, v0
	v_exp_f32_e32 v14, v14
	v_exp_f32_e32 v15, v15
	v_fma_f32 v17, s0, v97, v0
	v_exp_f32_e32 v17, v17
	v_fma_f32 v23, s0, v98, v0
	v_exp_f32_e32 v23, v23
	v_fmac_f32_e32 v0, s0, v99
	v_exp_f32_e32 v25, v0
	v_pk_mul_f32 v[92:93], v[114:115], v[14:15]
	v_pk_fma_f32 v[14:15], v[114:115], v[14:15], 0 op_sel_hi:[1,1,0]
	v_pk_mul_f32 v[96:97], v[114:115], v[16:17]
	v_pk_fma_f32 v[14:15], v[114:115], v[16:17], v[14:15]
	v_pk_mul_f32 v[86:87], v[114:115], v[24:25]
	v_pk_fma_f32 v[14:15], v[114:115], v[22:23], v[14:15]
	v_pk_mul_f32 v[98:99], v[114:115], v[22:23]
	v_pk_fma_f32 v[84:85], v[114:115], v[24:25], v[14:15]
	s_nop 0
	v_cvt_pk_f16_f32 v15, v13, v121
	v_cvt_pk_f16_f32 v14, v19, v21
	v_cvt_pk_f16_f32 v13, v12, v120
	v_cvt_pk_f16_f32 v12, v18, v20
	ds_read_b64_tr_b16 v[18:19], v206 offset:2560
	ds_read_b64_tr_b16 v[22:23], v206 offset:2592
	ds_read_b64_tr_b16 v[16:17], v205 offset:64000
	ds_read_b64_tr_b16 v[20:21], v205 offset:64032
	ds_read_b64_tr_b16 v[24:25], v205 offset:64064
	ds_read_b64_tr_b16 v[26:27], v206 offset:2624
	ds_read_b64_tr_b16 v[88:89], v205 offset:64096
	ds_read_b64_tr_b16 v[90:91], v206 offset:2656
	s_waitcnt lgkmcnt(5)
	v_mfma_f32_16x16x32_f16 v[16:19], v[16:19], v[12:15], v[60:63]
	v_cvt_pk_f16_f32 v95, v99, v87
	v_cvt_pk_f16_f32 v94, v93, v97
	v_cvt_pk_f16_f32 v93, v98, v86
	s_waitcnt lgkmcnt(4)
	v_mfma_f32_16x16x32_f16 v[20:23], v[20:23], v[12:15], v[64:67]
	v_cvt_pk_f16_f32 v92, v92, v96
	s_mov_b64 s[0:1], 0
	s_waitcnt lgkmcnt(2)
	v_mfma_f32_16x16x32_f16 v[24:27], v[24:27], v[12:15], v[68:71]
	s_waitcnt lgkmcnt(0)
	v_mfma_f32_16x16x32_f16 v[88:91], v[88:91], v[12:15], v[72:75]
	ds_read_b64_tr_b16 v[12:13], v206 offset:5120
	ds_read_b64_tr_b16 v[14:15], v206 offset:7680
	s_waitcnt lgkmcnt(0)
	v_mfma_f32_16x16x32_f16 v[12:15], v[12:15], v[92:95], v[16:19]
	s_nop 2
	ds_read_b64_tr_b16 v[16:17], v206 offset:5152
	ds_read_b64_tr_b16 v[18:19], v206 offset:7712
	s_waitcnt lgkmcnt(0)
	v_mfma_f32_16x16x32_f16 v[16:19], v[16:19], v[92:95], v[20:23]
	s_nop 2
	ds_read_b64_tr_b16 v[20:21], v206 offset:5184
	ds_read_b64_tr_b16 v[22:23], v206 offset:7744
	s_waitcnt lgkmcnt(0)
	v_mfma_f32_16x16x32_f16 v[20:23], v[20:23], v[92:95], v[24:27]
	s_nop 2
	ds_read_b64_tr_b16 v[24:25], v206 offset:5216
	ds_read_b64_tr_b16 v[26:27], v206 offset:7776
	s_waitcnt lgkmcnt(0)
	v_mfma_f32_16x16x32_f16 v[24:27], v[24:27], v[92:95], v[88:91]
.LBB0_1221:
	s_and_b64 vcc, exec, s[0:1]
	s_cbranch_vccz .LBB0_1295
	s_waitcnt lgkmcnt(1)
	v_mfma_f32_16x16x32_f16 v[12:15], v[80:83], v[4:7], 0
	ds_read_b128 v[16:19], v155 offset:56320
	ds_read_b128 v[20:23], v155 offset:58880
	s_nop 1
	ds_read_b128 v[24:27], v202 offset:5120
	s_waitcnt lgkmcnt(3)
	v_mfma_f32_16x16x32_f16 v[92:95], v[76:79], v[8:11], v[12:15]
	ds_read_b128 v[76:79], v202 offset:7680
	s_nop 1
	ds_read_b128 v[12:15], v155 offset:56384
	s_waitcnt lgkmcnt(4)
	v_mfma_f32_16x16x32_f16 v[16:19], v[16:19], v[4:7], 0
	s_waitcnt lgkmcnt(0)
	v_mfma_f32_16x16x32_f16 v[96:99], v[12:15], v[8:11], v[16:19]
	ds_read_b128 v[12:15], v155 offset:58944
	v_mfma_f32_16x16x32_f16 v[16:19], v[20:23], v[4:7], 0
	ds_read_b128 v[20:23], v155 offset:61440
	s_waitcnt lgkmcnt(1)
	v_mfma_f32_16x16x32_f16 v[100:103], v[12:15], v[8:11], v[16:19]
	ds_read_b128 v[12:15], v155 offset:61504
	s_waitcnt lgkmcnt(1)
	v_mfma_f32_16x16x32_f16 v[16:19], v[20:23], v[4:7], 0
	ds_read_b128 v[20:23], v202
	s_waitcnt lgkmcnt(1)
	v_mfma_f32_16x16x32_f16 v[104:107], v[12:15], v[8:11], v[16:19]
	ds_read_b128 v[12:15], v202 offset:64
	s_waitcnt lgkmcnt(1)
	v_mfma_f32_16x16x32_f16 v[16:19], v[20:23], v[4:7], 0
	ds_read_b128 v[20:23], v202 offset:2560
	s_waitcnt lgkmcnt(1)
	v_mfma_f32_16x16x32_f16 v[12:15], v[12:15], v[8:11], v[16:19]
	s_nop 4
	ds_read_b128 v[16:19], v202 offset:2624
	s_waitcnt lgkmcnt(1)
	v_mfma_f32_16x16x32_f16 v[20:23], v[20:23], v[4:7], 0
	s_waitcnt lgkmcnt(0)
	v_mfma_f32_16x16x32_f16 v[16:19], v[16:19], v[8:11], v[20:23]
	s_nop 5
	ds_read_b128 v[20:23], v202 offset:5184
	v_mfma_f32_16x16x32_f16 v[24:27], v[24:27], v[4:7], 0
	s_waitcnt lgkmcnt(0)
	v_mfma_f32_16x16x32_f16 v[20:23], v[20:23], v[8:11], v[24:27]
	s_nop 5
	ds_read_b128 v[24:27], v202 offset:7744
	v_mfma_f32_16x16x32_f16 v[76:79], v[76:79], v[4:7], 0
	s_waitcnt lgkmcnt(0)
	v_mfma_f32_16x16x32_f16 v[76:79], v[24:27], v[8:11], v[76:79]
	s_nop 0
	v_or_b32_e32 v2, s3, v154
	s_mov_b64 s[0:1], -1
	s_and_b64 vcc, exec, s[42:43]
	v_lshlrev_b32_e32 v3, 4, v2
	s_cbranch_vccnz .LBB0_1256
	v_sub_u32_e32 v0, v124, v3
	v_cmp_lt_i32_e32 vcc, -1, v0
	v_mov_b32_e32 v25, 0xf149f2ca
	v_mov_b32_e32 v24, 0xf149f2ca
	s_and_saveexec_b64 s[0:1], vcc
	s_cbranch_execz .LBB0_1225
	v_min_u32_e32 v0, 0x31f, v0
	v_lshl_add_u32 v0, v0, 2, v157
	ds_read_b32 v24, v0

; #define LAS __attribute__((address_space(3)))
; template <int MODE, int TM> ...
;     ...
;   if (MODE == M_CMPB) {
; #pragma unroll
;     for (int t = 0; t < 2; ++t) {
;       if (!(TM & (1 << t))) continue;
; #pragma unroll
;       for (int kt = 0; kt < 4; ++kt) {
;         float h = 0.f;
; #pragma unroll
;         for (int j = 0; j < 4; ++j) {
;           float pv = __builtin_amdgcn_exp2f(S[t][kt][j] * sclc[t] + (addc[t] - st.m)) * st.l;
;           S[t][kt][j] = pv;
;           h += pv;
;         }
;         hq[t][kt] = h;
;         h3[t][kt] = S[t][kt][3];
;       }
;     ...
;   __builtin_amdgcn_s_setprio(1);
; #pragma unroll
;   for (int t = 0; t < 2; ++t) {
;     if (!(TM & (1 << t))) continue;
;     const h16* Vt = t ? Vt1 : Vt0;
; #pragma unroll
;     for (int ks = 0; ks < 2; ++ks) {
;       h16x8 Pf;
; #pragma unroll
;       for (int i = 0; i < 4; ++i) { Pf[i] = (h16)S[t][2 * ks][i]; Pf[4 + i] = (h16)S[t][2 * ks + 1][i]; }
; #pragma unroll
;       for (int nt = 0; nt < 4; ++nt) {
;         const h16* vp = Vt + (ks * 32 + q4 * 4 + (col >> 2)) * KP + nt * 16 + 4 * (col & 3);
;         const s16x4v r0 = __builtin_amdgcn_ds_read_tr16_b64_v4i16((LAS s16x4v*)vp);
;         const s16x4v r1 = __builtin_amdgcn_ds_read_tr16_b64_v4i16((LAS s16x4v*)(vp + 16 * KP));
;         const h16x4 v0 = __builtin_bit_cast(h16x4, r0), v1 = __builtin_bit_cast(h16x4, r1);
;         const h16x8 Vf = {v0[0], v0[1], v0[2], v0[3], v1[0], v1[1], v1[2], v1[3]};
;         O[nt] = __builtin_amdgcn_mfma_f32_16x16x32_f16(Vf, Pf, O[nt], 0, 0, 0);
;       }
;     }
;   }
;   __builtin_amdgcn_s_setprio(0);
.LBB0_1294:
	s_waitcnt lgkmcnt(0)
	v_sub_f32_e32 v0, v122, v125
	v_fma_f32 v3, s3, v25, v0
	v_exp_f32_e32 v12, v3
	v_fma_f32 v3, s3, v26, v0
	v_exp_f32_e32 v14, v3
	v_fma_f32 v3, s3, v27, v0
	v_fma_f32 v2, s3, v24, v0
	v_exp_f32_e32 v16, v3
	v_fma_f32 v3, s3, v80, v0
	v_exp_f32_e32 v2, v2
	v_exp_f32_e32 v3, v3
	v_fma_f32 v13, s3, v81, v0
	v_exp_f32_e32 v13, v13
	v_fma_f32 v15, s3, v82, v0
	v_exp_f32_e32 v15, v15
	v_fma_f32 v17, s3, v83, v0
	v_exp_f32_e32 v17, v17
	v_pk_mul_f32 v[18:19], v[114:115], v[2:3]
	v_pk_fma_f32 v[2:3], v[114:115], v[2:3], 0 op_sel_hi:[1,1,0]
	v_pk_mul_f32 v[22:23], v[114:115], v[12:13]
	v_pk_fma_f32 v[2:3], v[114:115], v[12:13], v[2:3]
	v_fma_f32 v13, s3, v85, v0
	v_pk_mul_f32 v[24:25], v[114:115], v[14:15]
	v_pk_fma_f32 v[2:3], v[114:115], v[14:15], v[2:3]
	v_exp_f32_e32 v14, v13
	v_fma_f32 v13, s3, v86, v0
	v_pk_mul_f32 v[120:121], v[114:115], v[16:17]
	v_pk_fma_f32 v[2:3], v[114:115], v[16:17], v[2:3]
	v_exp_f32_e32 v16, v13
	v_fma_f32 v13, s3, v87, v0
	v_fma_f32 v12, s3, v84, v0
	v_exp_f32_e32 v20, v13
	v_fma_f32 v13, s3, v88, v0
	v_exp_f32_e32 v12, v12
	v_exp_f32_e32 v13, v13
	v_fma_f32 v15, s3, v89, v0
	v_exp_f32_e32 v15, v15
	v_fma_f32 v17, s3, v90, v0
	v_exp_f32_e32 v17, v17
	v_fmac_f32_e32 v0, s3, v91
	v_exp_f32_e32 v21, v0
	v_pk_mul_f32 v[26:27], v[114:115], v[12:13]
	v_pk_fma_f32 v[12:13], v[114:115], v[12:13], 0 op_sel_hi:[1,1,0]
	v_sub_f32_e32 v0, v123, v125
	v_pk_fma_f32 v[12:13], v[114:115], v[14:15], v[12:13]
	v_pk_mul_f32 v[80:81], v[114:115], v[14:15]
	v_pk_fma_f32 v[12:13], v[114:115], v[16:17], v[12:13]
	v_pk_mul_f32 v[82:83], v[114:115], v[16:17]
	v_pk_fma_f32 v[84:85], v[114:115], v[20:21], v[12:13]
	v_fma_f32 v13, s2, v93, v0
	v_exp_f32_e32 v14, v13
	v_fma_f32 v13, s2, v94, v0
	v_exp_f32_e32 v16, v13
	v_fma_f32 v13, s2, v95, v0
	v_pk_mul_f32 v[86:87], v[114:115], v[20:21]
	v_fma_f32 v12, s2, v92, v0
	v_exp_f32_e32 v20, v13
	v_fma_f32 v13, s2, v96, v0
	v_exp_f32_e32 v12, v12
	v_exp_f32_e32 v13, v13
	v_fma_f32 v15, s2, v97, v0
	v_exp_f32_e32 v15, v15
	v_fma_f32 v17, s2, v98, v0
	v_exp_f32_e32 v17, v17
	v_fma_f32 v21, s2, v99, v0
	v_exp_f32_e32 v21, v21
	v_pk_mul_f32 v[96:97], v[114:115], v[12:13]
	v_pk_fma_f32 v[12:13], v[114:115], v[12:13], 0 op_sel_hi:[1,1,0]
	v_pk_mul_f32 v[98:99], v[114:115], v[14:15]
	v_pk_fma_f32 v[12:13], v[114:115], v[14:15], v[12:13]
	v_pk_mul_f32 v[122:123], v[114:115], v[16:17]
	v_pk_fma_f32 v[12:13], v[114:115], v[16:17], v[12:13]
	v_pk_mul_f32 v[94:95], v[114:115], v[20:21]
	v_pk_fma_f32 v[90:91], v[114:115], v[20:21], v[12:13]
	v_fma_f32 v12, s2, v100, v0
	v_exp_f32_e32 v14, v12
	v_fma_f32 v12, s2, v101, v0
	v_exp_f32_e32 v16, v12
	v_fma_f32 v12, s2, v102, v0
	v_exp_f32_e32 v20, v12
	v_fma_f32 v12, s2, v103, v0
	v_exp_f32_e32 v76, v12
	v_fma_f32 v12, s2, v104, v0
	v_exp_f32_e32 v15, v12
	v_fma_f32 v12, s2, v105, v0
	v_exp_f32_e32 v17, v12
	v_fma_f32 v12, s2, v106, v0
	v_exp_f32_e32 v21, v12
	v_fmac_f32_e32 v0, s2, v107
	v_exp_f32_e32 v77, v0
	v_pk_fma_f32 v[78:79], v[114:115], v[14:15], 0 op_sel_hi:[1,1,0]
	v_pk_mul_f32 v[12:13], v[114:115], v[14:15]
	v_pk_fma_f32 v[78:79], v[114:115], v[16:17], v[78:79]
	v_pk_mul_f32 v[14:15], v[114:115], v[16:17]
	v_pk_mul_f32 v[16:17], v[114:115], v[20:21]
	v_pk_fma_f32 v[20:21], v[114:115], v[20:21], v[78:79]
	v_pk_mul_f32 v[92:93], v[114:115], v[76:77]
	v_pk_fma_f32 v[88:89], v[114:115], v[76:77], v[20:21]
	s_nop 0
	v_cvt_pk_f16_f32 v21, v25, v121
	v_cvt_pk_f16_f32 v20, v19, v23
	v_cvt_pk_f16_f32 v19, v24, v120
	v_cvt_pk_f16_f32 v18, v18, v22
	ds_read_b64_tr_b16 v[24:25], v206 offset:2560
	ds_read_b64_tr_b16 v[78:79], v206 offset:2592
	ds_read_b64_tr_b16 v[22:23], v205 offset:64000
	ds_read_b64_tr_b16 v[76:77], v205 offset:64032
	s_waitcnt lgkmcnt(1)
	v_mfma_f32_16x16x32_f16 v[22:25], v[22:25], v[18:21], v[60:63]
	s_waitcnt lgkmcnt(0)
	v_mfma_f32_16x16x32_f16 v[60:63], v[76:79], v[18:21], v[64:67]
	s_nop 2
	ds_read_b64_tr_b16 v[64:65], v205 offset:64064
	ds_read_b64_tr_b16 v[66:67], v206 offset:2624
	s_waitcnt lgkmcnt(0)
	v_mfma_f32_16x16x32_f16 v[64:67], v[64:67], v[18:21], v[68:71]
	s_nop 2
	ds_read_b64_tr_b16 v[68:69], v205 offset:64096
	ds_read_b64_tr_b16 v[70:71], v206 offset:2656
	s_waitcnt lgkmcnt(0)
	v_mfma_f32_16x16x32_f16 v[18:21], v[68:71], v[18:21], v[72:75]
	s_nop 2
	ds_read_b64_tr_b16 v[74:75], v207 offset:2560
	ds_read_b64_tr_b16 v[72:73], v207
	ds_read_b64_tr_b16 v[76:77], v207 offset:32
	v_cvt_pk_f16_f32 v71, v83, v87
	v_cvt_pk_f16_f32 v70, v27, v81
	v_cvt_pk_f16_f32 v69, v82, v86
	v_cvt_pk_f16_f32 v68, v26, v80
	ds_read_b64_tr_b16 v[78:79], v207 offset:2592
	s_waitcnt lgkmcnt(2)
	v_mfma_f32_16x16x32_f16 v[22:25], v[72:75], v[68:71], v[22:25]
	ds_read_b64_tr_b16 v[72:73], v207 offset:64
	ds_read_b64_tr_b16 v[74:75], v207 offset:2624
	s_waitcnt lgkmcnt(0)
	v_mfma_f32_16x16x32_f16 v[64:67], v[72:75], v[68:71], v[64:67]
	ds_read_b64_tr_b16 v[72:73], v207 offset:96
	ds_read_b64_tr_b16 v[74:75], v207 offset:2656
	v_mfma_f32_16x16x32_f16 v[60:63], v[76:79], v[68:71], v[60:63]
	s_waitcnt lgkmcnt(0)
	v_mfma_f32_16x16x32_f16 v[18:21], v[72:75], v[68:71], v[18:21]
	ds_read_b64_tr_b16 v[74:75], v208 offset:2560
	ds_read_b64_tr_b16 v[72:73], v208
	ds_read_b64_tr_b16 v[76:77], v208 offset:32
	v_cvt_pk_f16_f32 v71, v123, v95
	v_cvt_pk_f16_f32 v70, v97, v99
	v_cvt_pk_f16_f32 v69, v122, v94
	v_cvt_pk_f16_f32 v68, v96, v98
	ds_read_b64_tr_b16 v[78:79], v208 offset:2592
	s_waitcnt lgkmcnt(2)
	v_mfma_f32_16x16x32_f16 v[22:25], v[72:75], v[68:71], v[22:25]
	ds_read_b64_tr_b16 v[72:73], v208 offset:64
	ds_read_b64_tr_b16 v[74:75], v208 offset:2624
	s_waitcnt lgkmcnt(0)
	v_mfma_f32_16x16x32_f16 v[64:67], v[72:75], v[68:71], v[64:67]
	ds_read_b64_tr_b16 v[72:73], v208 offset:96
	ds_read_b64_tr_b16 v[74:75], v208 offset:2656
	v_mfma_f32_16x16x32_f16 v[60:63], v[76:79], v[68:71], v[60:63]
	s_waitcnt lgkmcnt(0)
	v_mfma_f32_16x16x32_f16 v[68:71], v[72:75], v[68:71], v[18:21]
	v_cvt_pk_f16_f32 v74, v13, v15
	v_cvt_pk_f16_f32 v72, v12, v14
	ds_read_b64_tr_b16 v[12:13], v208 offset:5120
	ds_read_b64_tr_b16 v[14:15], v208 offset:7680
	v_cvt_pk_f16_f32 v75, v17, v93
	v_cvt_pk_f16_f32 v73, v16, v92
	ds_read_b64_tr_b16 v[16:17], v208 offset:5152
	ds_read_b64_tr_b16 v[18:19], v208 offset:7712
	s_waitcnt lgkmcnt(2)
	v_mfma_f32_16x16x32_f16 v[12:15], v[12:15], v[72:75], v[22:25]
	ds_read_b64_tr_b16 v[20:21], v208 offset:5184
	s_nop 1
	ds_read_b64_tr_b16 v[22:23], v208 offset:7744
	ds_read_b64_tr_b16 v[24:25], v208 offset:5216
	ds_read_b64_tr_b16 v[26:27], v208 offset:7776
	s_waitcnt lgkmcnt(4)
	v_mfma_f32_16x16x32_f16 v[16:19], v[16:19], v[72:75], v[60:63]
	s_waitcnt lgkmcnt(2)
	v_mfma_f32_16x16x32_f16 v[20:23], v[20:23], v[72:75], v[64:67]
	s_waitcnt lgkmcnt(0)
	v_mfma_f32_16x16x32_f16 v[24:27], v[24:27], v[72:75], v[68:71]
; __device__ __forceinline__ float quadsum(float v) { v += dppf<0xB1>(v); v += dppf<0x4E>(v); return v; }
;     ...
;         float t3p = carry;
; #pragma unroll
;         for (int t = 0; t < 2; ++t) {
;           if (t == 1 && !two) break;
; #pragma unroll
;           for (int kt = 0; kt < 4; ++kt) {
;             const float qs = quadsum(hq[t][kt]);
;             const float t3 = quadsum(h3[t][kt]);
;             const float up = __shfl(t3, (lane + 48) & 63);
;             const float wrp = __shfl(t3p, (lane + 48) & 63);
;             const float pk = (q4 == 0) ? wrp : up;
;             if (hd == 0) impw[qw * 128 + (2 * i + t) * 16 + kt * 4 + q4] = qs + pk;
;             t3p = t3;
;           }
;         }
;         carry = t3p;
.LBB0_1295:
	s_nop 0
	v_add_f32_dpp v0, v120, v120 quad_perm:[1,0,3,2] row_mask:0xf bank_mask:0xf bound_ctrl:1
	ds_bpermute_b32 v62, v126, v127
	s_lshl_b32 s0, s49, 5
	v_add_f32_dpp v60, v0, v0 quad_perm:[2,3,0,1] row_mask:0xf bank_mask:0xf bound_ctrl:1
	ds_bpermute_b32 v61, v126, v60
	v_add_f32_dpp v2, v2, v2 quad_perm:[1,0,3,2] row_mask:0xf bank_mask:0xf bound_ctrl:1
	v_lshl_add_u32 v0, s0, 2, v210
	s_nop 0
	v_mov_b32_dpp v63, v2 quad_perm:[2,3,0,1] row_mask:0xf bank_mask:0xf bound_ctrl:1
	s_and_saveexec_b64 s[0:1], s[16:17]
	s_cbranch_execz .LBB0_1297
	v_add_f32_e32 v2, v2, v63
	s_waitcnt lgkmcnt(0)
	v_cndmask_b32_e64 v61, v61, v62, s[18:19]
	v_add_f32_e32 v2, v2, v61
	ds_write_b32 v0, v2

; template <int MODE, int TM> ...
;     ...
;   __builtin_amdgcn_s_setprio(1);
; #pragma unroll
;   for (int t = 0; t < 2; ++t) {
;     if (!(TM & (1 << t))) continue;
;     const h16* Ks = t ? Ks1 : Ks0;
; #pragma unroll
;     for (int kt = 0; kt < 4; ++kt) {
;       S[t][kt] = f32x4{0.f, 0.f, 0.f, 0.f};
; #pragma unroll
;       for (int ks = 0; ks < 2; ++ks) {
;         h16x8 Kf = *(const h16x8*)(Ks + (kt * 16 + col) * KP + ks * 32 + q4 * 8);
;         S[t][kt] = __builtin_amdgcn_mfma_f32_16x16x32_f16(Kf, Q[ks], S[t][kt], 0, 0, 0);
;       }
;     }
;   }
;   __builtin_amdgcn_s_setprio(0);
;     ...
;         const int jb = 2 * i;
;         bool sb[2];
;         sb[0] = ((jb < 64 ? (slo >> jb) : (shi >> (jb - 64))) & 1ull) != 0;
;         sb[1] = (jb + 1 <= cur) && (((jb + 1 < 64 ? (slo >> (jb + 1)) : (shi >> (jb + 1 - 64))) & 1ull) != 0);
;         const bool far[2] = {t0 - (jb * 64 + 63) >= 799, t0 - (jb * 64 + 127) >= 799};
;         const bool n0 = __any(sb[0]) != 0, n1 = __any(sb[1]) != 0;
;         if (n0 && n1) attn_tile2<M_SEL, 3>(Q, O, st, KSB(i, 0), VTB(i, 0), KSB(i, 1), VTB(i, 1), biasT, tq, hd, jb * 64, far, sb, hpd, hpe, lane);
;         else if (n0) attn_tile2<M_SEL, 1>(Q, O, st, KSB(i, 0), VTB(i, 0), KSB(i, 1), VTB(i, 1), biasT, tq, hd, jb * 64, far, sb, hpd, hpe, lane);
;         else if (n1) attn_tile2<M_SEL, 2>(Q, O, st, KSB(i, 0), VTB(i, 0), KSB(i, 1), VTB(i, 1), biasT, tq, hd, jb * 64, far, sb, hpd, hpe, lane);
.LBB0_1439:
	s_lshl_b32 s2, s30, 1
	s_cmp_lt_u32 s30, 32
	s_cselect_b64 s[42:43], -1, 0
	s_sub_i32 s3, s2, 64
	s_and_b64 s[0:1], s[42:43], exec
	v_cndmask_b32_e64 v3, v47, v45, s[42:43]
	s_cselect_b32 s0, s2, s3
	v_cndmask_b32_e64 v2, v46, v44, s[42:43]
	s_cmp_lt_u32 s2, s28
	v_lshrrev_b64 v[80:81], s0, v[2:3]
	s_cselect_b64 s[0:1], -1, 0
	s_or_b32 s46, s2, 1
	s_sub_i32 s47, s2, 63
	s_and_b64 s[2:3], s[42:43], exec
	s_cselect_b32 s2, s46, s47
	s_lshl_b64 s[2:3], 1, s2
	v_and_b32_e32 v83, s3, v3
	v_and_b32_e32 v82, s2, v2
	v_cmp_ne_u64_e32 vcc, 0, v[82:83]
	s_lshl_b32 s2, s30, 7
	s_and_b64 s[46:47], s[0:1], vcc
	s_sub_i32 s0, s20, s2
	s_cmpk_lt_i32 s0, 0x35e
	v_and_b32_e32 v0, 1, v80
	s_cselect_b64 s[50:51], -1, 0
	s_cmpk_lt_i32 s0, 0x39e
	v_cmp_ne_u32_e32 vcc, 0, v0
	s_cselect_b64 s[48:49], -1, 0
	s_cmp_eq_u64 vcc, 0
	v_cndmask_b32_e64 v80, 0, 1, s[46:47]
	s_cselect_b64 s[0:1], -1, 0
	s_cmp_lg_u64 vcc, 0
	v_cmp_ne_u32_e32 vcc, 0, v80
	s_cselect_b64 s[56:57], -1, 0
	s_cmp_lg_u64 vcc, 0
	s_cselect_b64 s[52:53], -1, 0
	s_and_b64 s[56:57], s[56:57], s[52:53]
	s_andn2_b64 vcc, exec, s[56:57]
	s_cbranch_vccz .LBB0_1480
	s_and_b64 vcc, exec, s[0:1]
	s_cbranch_vccz .LBB0_1481
	v_mov_b64_e32 v[82:83], v[30:31]
	v_mov_b64_e32 v[86:87], v[34:35]
	v_mov_b64_e32 v[90:91], v[38:39]
	v_mov_b64_e32 v[94:95], v[42:43]
	s_mov_b64 s[0:1], 0
	s_and_b64 vcc, exec, s[52:53]
	v_mov_b32_e32 v188, v243
	v_mov_b32_e32 v244, v173
	v_mov_b64_e32 v[80:81], v[28:29]
	v_mov_b64_e32 v[84:85], v[32:33]
	v_mov_b64_e32 v[88:89], v[36:37]
	v_mov_b64_e32 v[92:93], v[40:41]
	s_mov_b64 s[52:53], 0
	s_cbranch_vccz .LBB0_1482
	s_nop 0
	ds_read_b128 v[80:83], v155 offset:33280
	ds_read_b128 v[84:87], v155 offset:33344
	ds_read_b128 v[88:91], v155 offset:35840
	ds_read_b128 v[92:95], v155 offset:35904
	ds_read_b128 v[96:99], v155 offset:38400
	s_waitcnt lgkmcnt(4)
	v_mfma_f32_16x16x32_f16 v[80:83], v[80:83], v[4:7], 0
	s_waitcnt lgkmcnt(2)
	v_mfma_f32_16x16x32_f16 v[88:91], v[88:91], v[4:7], 0
	v_mfma_f32_16x16x32_f16 v[84:87], v[84:87], v[8:11], v[80:83]
	s_waitcnt lgkmcnt(1)
	v_mfma_f32_16x16x32_f16 v[80:83], v[92:95], v[8:11], v[88:91]
	s_nop 4
	ds_read_b128 v[88:91], v155 offset:38464
	s_waitcnt lgkmcnt(1)
	v_mfma_f32_16x16x32_f16 v[92:95], v[96:99], v[4:7], 0
	ds_read_b128 v[96:99], v155 offset:40960
	s_waitcnt lgkmcnt(1)
	v_mfma_f32_16x16x32_f16 v[92:95], v[88:91], v[8:11], v[92:95]
	ds_read_b128 v[88:91], v155 offset:41024
	s_waitcnt lgkmcnt(1)
	v_mfma_f32_16x16x32_f16 v[96:99], v[96:99], v[4:7], 0
	s_waitcnt lgkmcnt(0)
	v_mfma_f32_16x16x32_f16 v[88:91], v[88:91], v[8:11], v[96:99]
	s_nop 0
	s_andn2_b64 vcc, exec, s[48:49]
	s_mov_b64 s[52:53], -1
	s_cbranch_vccnz .LBB0_1476
	v_or_b32_e32 v112, s2, v154
	s_nop 0
	v_sub_u32_e32 v98, v175, v112
	v_cmp_lt_i32_e32 vcc, -1, v98
	s_and_b64 s[56:57], vcc, s[46:47]
	v_mov_b32_e32 v97, 0xf149f2ca
	v_mov_b32_e32 v96, 0xf149f2ca
	s_and_saveexec_b64 s[52:53], s[56:57]
	s_cbranch_execz .LBB0_1445
	v_min_u32_e32 v96, 0x31f, v98
	v_lshl_add_u32 v96, v96, 2, v157
	ds_read_b32 v96, v96

; template <int MODE, int TM> ...
;     ...
;   __builtin_amdgcn_s_setprio(1);
; #pragma unroll
;   for (int t = 0; t < 2; ++t) {
;     if (!(TM & (1 << t))) continue;
;     const h16* Ks = t ? Ks1 : Ks0;
; #pragma unroll
;     for (int kt = 0; kt < 4; ++kt) {
;       S[t][kt] = f32x4{0.f, 0.f, 0.f, 0.f};
; #pragma unroll
;       for (int ks = 0; ks < 2; ++ks) {
;         h16x8 Kf = *(const h16x8*)(Ks + (kt * 16 + col) * KP + ks * 32 + q4 * 8);
;         S[t][kt] = __builtin_amdgcn_mfma_f32_16x16x32_f16(Kf, Q[ks], S[t][kt], 0, 0, 0);
;       }
;     }
;   }
;   __builtin_amdgcn_s_setprio(0);
;   const float* bt = biasT + hd * 800;
;   float addc[2] = {0.f, 0.f}, sclc[2] = {1.f, 1.f};
; #pragma unroll
;   for (int t = 0; t < 2; ++t) {
;     if (!(TM & (1 << t))) continue;
;     const int kbase = kbase0 + 64 * t;
;     if (far[t]) {
;       const bool ok = (MODE == M_SEL) ? selbit[t] : true;
;       addc[t] = ok ? bt[799] : -1e30f;
;       sclc[t] = SCL2;
;     } else {
;       addc[t] = 0.f;
;       sclc[t] = 1.f;
;       const int kx0 = kbase + q4 * 4;
;       const int d0 = (DK == 16) ? tq - 31 - 16 * kx0 : tq - kx0;
; #pragma unroll
;       for (int kt = 0; kt < 4; ++kt)
; #pragma unroll
;         for (int j = 0; j < 4; ++j) {
;           const int dist = d0 - DK * (kt * 16 + j);
;           const int kx = kx0 + kt * 16 + j;
;           bool valid = dist >= 0;
;           if (MODE == M_WIN) valid = valid && dist < 512 && kx >= 0;
;           if (MODE == M_SEL) valid = valid && selbit[t];
;           if (DK == 16) valid = valid && kx < NCMP;
;           const int dc = dist < 0 ? 0 : (dist > 799 ? 799 : dist);
;           S[t][kt][j] = valid ? S[t][kt][j] * SCL2 + bt[dc] : -1e30f;
.LBB0_1483:
	s_nop 0
	ds_read_b128 v[80:83], v155 offset:12800
	ds_read_b128 v[84:87], v155 offset:12864
	ds_read_b128 v[88:91], v155 offset:15360
	ds_read_b128 v[96:99], v155 offset:15424
	s_waitcnt lgkmcnt(3)
	v_mfma_f32_16x16x32_f16 v[80:83], v[80:83], v[4:7], 0
	s_waitcnt lgkmcnt(2)
	v_mfma_f32_16x16x32_f16 v[92:95], v[84:87], v[8:11], v[80:83]
	ds_read_b128 v[84:87], v155 offset:17984
	s_nop 4
	ds_read_b128 v[80:83], v155 offset:17920
	s_waitcnt lgkmcnt(3)
	v_mfma_f32_16x16x32_f16 v[88:91], v[88:91], v[4:7], 0
	s_waitcnt lgkmcnt(2)
	v_mfma_f32_16x16x32_f16 v[88:91], v[96:99], v[8:11], v[88:91]
	ds_read_b128 v[96:99], v155 offset:20480
	s_waitcnt lgkmcnt(1)
	v_mfma_f32_16x16x32_f16 v[80:83], v[80:83], v[4:7], 0
	v_mfma_f32_16x16x32_f16 v[84:87], v[84:87], v[8:11], v[80:83]
	s_nop 6
	ds_read_b128 v[80:83], v155 offset:20544
	s_waitcnt lgkmcnt(1)
	v_mfma_f32_16x16x32_f16 v[96:99], v[96:99], v[4:7], 0
	s_waitcnt lgkmcnt(0)
	v_mfma_f32_16x16x32_f16 v[80:83], v[80:83], v[8:11], v[96:99]
	s_nop 0
	s_mov_b64 s[0:1], -1
	s_and_b64 vcc, exec, s[50:51]
	s_cbranch_vccz .LBB0_1517
	v_or_b32_e32 v112, s2, v154
	s_nop 0
	v_sub_u32_e32 v98, v182, v112
	v_cmp_lt_i32_e64 s[0:1], -1, v98
	v_cmp_eq_u32_e32 vcc, 1, v0
	s_and_b64 s[52:53], s[0:1], vcc
	v_mov_b32_e32 v97, 0xf149f2ca
	v_mov_b32_e32 v96, 0xf149f2ca
	s_and_saveexec_b64 s[0:1], s[52:53]
	s_cbranch_execz .LBB0_1486
	v_min_u32_e32 v96, 0x31f, v98
	v_lshl_add_u32 v96, v96, 2, v157
	ds_read_b32 v96, v96

; #define LAS __attribute__((address_space(3)))
; template <int MODE, int TM> ...
;     ...
;     float mx = -1e30f;
; #pragma unroll
;     for (int t = 0; t < 2; ++t) {
;       if (!(TM & (1 << t))) continue;
;       float mt = -1e30f;
; #pragma unroll
;       for (int kt = 0; kt < 4; ++kt)
; #pragma unroll
;         for (int j = 0; j < 4; ++j) mt = fmaxf(mt, S[t][kt][j]);
;       mx = fmaxf(mx, mt * sclc[t] + addc[t]);
;     }
;     mx = max4q(mx);
;     const float mn = fmaxf(st.m, mx);
;     const float corr = __builtin_amdgcn_exp2f(st.m - mn);
;     st.m = mn;
;     const float mm = fmaxf(mn, -1e20f);
;     float ls = 0.f;
; #pragma unroll
;     for (int t = 0; t < 2; ++t) {
;       if (!(TM & (1 << t))) continue;
;       const float am = addc[t] - mm;
; #pragma unroll
;       for (int kt = 0; kt < 4; ++kt) {
;         const f32x4 e = S[t][kt] * sclc[t] + am;
; #pragma unroll
;         for (int j = 0; j < 4; ++j) {
;           float pv = __builtin_amdgcn_exp2f(e[j]);
;           S[t][kt][j] = pv;
;           ls += pv;
;         }
;       }
;     }
;     st.l = st.l * corr + ls;
;     if (MODE != M_CMPA) {
; #pragma unroll
;       for (int nt = 0; nt < 4; ++nt) O[nt] *= corr;
;     }
;   }
;     ...
;   for (int t = 0; t < 2; ++t) {
;     if (!(TM & (1 << t))) continue;
;     const h16* Vt = t ? Vt1 : Vt0;
; #pragma unroll
;     for (int ks = 0; ks < 2; ++ks) {
;       h16x8 Pf;
; #pragma unroll
;       for (int i = 0; i < 4; ++i) { Pf[i] = (h16)S[t][2 * ks][i]; Pf[4 + i] = (h16)S[t][2 * ks + 1][i]; }
; #pragma unroll
;       for (int nt = 0; nt < 4; ++nt) {
;         const h16* vp = Vt + (ks * 32 + q4 * 4 + (col >> 2)) * KP + nt * 16 + 4 * (col & 3);
;         const s16x4v r0 = __builtin_amdgcn_ds_read_tr16_b64_v4i16((LAS s16x4v*)vp);
;         const s16x4v r1 = __builtin_amdgcn_ds_read_tr16_b64_v4i16((LAS s16x4v*)(vp + 16 * KP));
;         const h16x4 v0 = __builtin_bit_cast(h16x4, r0), v1 = __builtin_bit_cast(h16x4, r1);
;         const h16x8 Vf = {v0[0], v0[1], v0[2], v0[3], v1[0], v1[1], v1[2], v1[3]};
;         O[nt] = __builtin_amdgcn_mfma_f32_16x16x32_f16(Vf, Pf, O[nt], 0, 0, 0);
;       }
;     }
;   }
;   __builtin_amdgcn_s_setprio(0);
.LBB0_1522:
	v_max3_f32 v96, v92, s67, v93
	v_max3_f32 v96, v96, v94, v95
	v_max3_f32 v96, v96, v88, v89
	v_max3_f32 v96, v96, v90, v91
	v_max3_f32 v96, v96, v84, v85
	v_max3_f32 v96, v96, v86, v87
	v_max3_f32 v96, v96, v80, v81
	v_max3_f32 v96, v96, v82, v83
	s_waitcnt lgkmcnt(0)
	v_fma_f32 v96, s0, v96, v112
	v_max_f32_e32 v96, 0xf149f2ca, v96
	v_mov_b32_e32 v97, v96
	s_nop 1
	v_permlane16_swap_b32_e32 v97, v96
	s_waitcnt lgkmcnt(0)
	v_max_f32_e32 v97, v97, v97
	v_max_f32_e32 v96, v96, v97
	v_mov_b32_e32 v97, v96
	s_nop 1
	v_permlane32_swap_b32_e32 v96, v97
	v_max3_f32 v244, v173, v96, v97
	v_max_f32_e32 v97, 0xe0ad78ec, v244
	v_sub_f32_e32 v97, v112, v97
	v_fma_f32 v92, s0, v92, v97
	v_fma_f32 v93, s0, v93, v97
	v_exp_f32_e32 v100, v92
	v_fma_f32 v94, s0, v94, v97
	v_exp_f32_e32 v101, v93
	v_fma_f32 v92, s0, v95, v97
	v_exp_f32_e32 v102, v94
	v_exp_f32_e32 v103, v92
	v_fma_f32 v88, s0, v88, v97
	v_add_f32_e32 v93, 0, v100
	v_exp_f32_e32 v98, v88
	v_fma_f32 v89, s0, v89, v97
	v_add_f32_e32 v88, v101, v93
	v_exp_f32_e32 v104, v89
	v_fma_f32 v89, s0, v90, v97
	v_add_f32_e32 v88, v102, v88
	v_exp_f32_e32 v99, v89
	v_fma_f32 v89, s0, v91, v97
	v_add_f32_e32 v88, v103, v88
	v_exp_f32_e32 v105, v89
	v_fma_f32 v84, s0, v84, v97
	v_add_f32_e32 v88, v98, v88
	v_exp_f32_e32 v108, v84
	v_fma_f32 v85, s0, v85, v97
	v_add_f32_e32 v84, v104, v88
	v_exp_f32_e32 v109, v85
	v_fma_f32 v85, s0, v86, v97
	v_add_f32_e32 v84, v99, v84
	v_exp_f32_e32 v110, v85
	v_fma_f32 v85, s0, v87, v97
	v_add_f32_e32 v84, v105, v84
	v_exp_f32_e32 v111, v85
	v_fma_f32 v80, s0, v80, v97
	v_add_f32_e32 v84, v108, v84
	v_exp_f32_e32 v112, v80
	v_fma_f32 v81, s0, v81, v97
	v_add_f32_e32 v80, v109, v84
	v_exp_f32_e32 v113, v81
	v_fma_f32 v81, s0, v82, v97
	v_add_f32_e32 v80, v110, v80
	v_exp_f32_e32 v114, v81
	v_fmac_f32_e32 v97, s0, v83
	v_sub_f32_e32 v96, v173, v244
	v_add_f32_e32 v80, v111, v80
	v_exp_f32_e32 v115, v97
	v_add_f32_e32 v80, v112, v80
	v_exp_f32_e32 v92, v96
	v_add_f32_e32 v80, v113, v80
	v_add_f32_e32 v80, v114, v80
	v_add_f32_e32 v188, v115, v80
	v_fmac_f32_e32 v188, v243, v92
	v_pk_mul_f32 v[82:83], v[30:31], v[92:93] op_sel_hi:[1,0]
	v_pk_mul_f32 v[80:81], v[28:29], v[92:93] op_sel_hi:[1,0]
	v_pk_mul_f32 v[86:87], v[34:35], v[92:93] op_sel_hi:[1,0]
	v_pk_mul_f32 v[84:85], v[32:33], v[92:93] op_sel_hi:[1,0]
	v_pk_mul_f32 v[90:91], v[38:39], v[92:93] op_sel_hi:[1,0]
	v_pk_mul_f32 v[88:89], v[36:37], v[92:93] op_sel_hi:[1,0]
	v_pk_mul_f32 v[94:95], v[42:43], v[92:93] op_sel_hi:[1,0]
	v_pk_mul_f32 v[92:93], v[40:41], v[92:93] op_sel_hi:[1,0]
	s_nop 0
	v_cvt_pk_f16_f32 v99, v99, v105
	v_cvt_pk_f16_f32 v98, v98, v104
	v_cvt_pk_f16_f32 v97, v102, v103
	v_cvt_pk_f16_f32 v96, v100, v101
	ds_read_b64_tr_b16 v[102:103], v205 offset:25600
	ds_read_b64_tr_b16 v[100:101], v205 offset:23040
	ds_read_b64_tr_b16 v[104:105], v205 offset:23072
	s_waitcnt lgkmcnt(1)
	v_mfma_f32_16x16x32_f16 v[80:83], v[100:103], v[96:99], v[80:83]
	ds_read_b64_tr_b16 v[106:107], v205 offset:25632
	ds_read_b64_tr_b16 v[100:101], v205 offset:23104
	ds_read_b64_tr_b16 v[102:103], v205 offset:25664
	s_mov_b64 s[52:53], -1
	s_waitcnt lgkmcnt(0)
	v_mfma_f32_16x16x32_f16 v[88:91], v[100:103], v[96:99], v[88:91]
	ds_read_b64_tr_b16 v[100:101], v205 offset:23136
	ds_read_b64_tr_b16 v[102:103], v205 offset:25696
	s_waitcnt lgkmcnt(0)
	v_mfma_f32_16x16x32_f16 v[92:95], v[100:103], v[96:99], v[92:95]
	ds_read_b64_tr_b16 v[100:101], v205 offset:28160
	ds_read_b64_tr_b16 v[102:103], v205 offset:30720
	v_mfma_f32_16x16x32_f16 v[84:87], v[104:107], v[96:99], v[84:87]
	v_cvt_pk_f16_f32 v99, v114, v115
	v_cvt_pk_f16_f32 v98, v112, v113
	v_cvt_pk_f16_f32 v97, v110, v111
	v_cvt_pk_f16_f32 v96, v108, v109
	s_waitcnt lgkmcnt(0)
	s_nop 0
	v_mfma_f32_16x16x32_f16 v[80:83], v[100:103], v[96:99], v[80:83]
	ds_read_b64_tr_b16 v[100:101], v205 offset:28192
	ds_read_b64_tr_b16 v[102:103], v205 offset:30752
	s_waitcnt lgkmcnt(0)
	v_mfma_f32_16x16x32_f16 v[84:87], v[100:103], v[96:99], v[84:87]
	ds_read_b64_tr_b16 v[100:101], v205 offset:28224
	ds_read_b64_tr_b16 v[102:103], v205 offset:30784
	s_waitcnt lgkmcnt(0)
	v_mfma_f32_16x16x32_f16 v[88:91], v[100:103], v[96:99], v[88:91]
	ds_read_b64_tr_b16 v[100:101], v205 offset:28256
	ds_read_b64_tr_b16 v[102:103], v205 offset:30816
	s_waitcnt lgkmcnt(0)
	v_mfma_f32_16x16x32_f16 v[92:95], v[100:103], v[96:99], v[92:95]
	s_branch .LBB0_1603

; #define LAS __attribute__((address_space(3)))
; template <int MODE, int TM> ...
;     ...
;     float mx = -1e30f;
; #pragma unroll
;     for (int t = 0; t < 2; ++t) {
;       if (!(TM & (1 << t))) continue;
;       float mt = -1e30f;
; #pragma unroll
;       for (int kt = 0; kt < 4; ++kt)
; #pragma unroll
;         for (int j = 0; j < 4; ++j) mt = fmaxf(mt, S[t][kt][j]);
;       mx = fmaxf(mx, mt * sclc[t] + addc[t]);
;     }
;     mx = max4q(mx);
;     const float mn = fmaxf(st.m, mx);
;     const float corr = __builtin_amdgcn_exp2f(st.m - mn);
;     st.m = mn;
;     const float mm = fmaxf(mn, -1e20f);
;     float ls = 0.f;
; #pragma unroll
;     for (int t = 0; t < 2; ++t) {
;       if (!(TM & (1 << t))) continue;
;       const float am = addc[t] - mm;
; #pragma unroll
;       for (int kt = 0; kt < 4; ++kt) {
;         const f32x4 e = S[t][kt] * sclc[t] + am;
; #pragma unroll
;         for (int j = 0; j < 4; ++j) {
;           float pv = __builtin_amdgcn_exp2f(e[j]);
;           S[t][kt][j] = pv;
;           ls += pv;
;         }
;       }
;     }
;     st.l = st.l * corr + ls;
;     if (MODE != M_CMPA) {
; #pragma unroll
;       for (int nt = 0; nt < 4; ++nt) O[nt] *= corr;
;     }
;   }
;     ...
;   for (int t = 0; t < 2; ++t) {
;     if (!(TM & (1 << t))) continue;
;     const h16* Vt = t ? Vt1 : Vt0;
; #pragma unroll
;     for (int ks = 0; ks < 2; ++ks) {
;       h16x8 Pf;
; #pragma unroll
;       for (int i = 0; i < 4; ++i) { Pf[i] = (h16)S[t][2 * ks][i]; Pf[4 + i] = (h16)S[t][2 * ks + 1][i]; }
; #pragma unroll
;       for (int nt = 0; nt < 4; ++nt) {
;         const h16* vp = Vt + (ks * 32 + q4 * 4 + (col >> 2)) * KP + nt * 16 + 4 * (col & 3);
;         const s16x4v r0 = __builtin_amdgcn_ds_read_tr16_b64_v4i16((LAS s16x4v*)vp);
;         const s16x4v r1 = __builtin_amdgcn_ds_read_tr16_b64_v4i16((LAS s16x4v*)(vp + 16 * KP));
;         const h16x4 v0 = __builtin_bit_cast(h16x4, r0), v1 = __builtin_bit_cast(h16x4, r1);
;         const h16x8 Vf = {v0[0], v0[1], v0[2], v0[3], v1[0], v1[1], v1[2], v1[3]};
;         O[nt] = __builtin_amdgcn_mfma_f32_16x16x32_f16(Vf, Pf, O[nt], 0, 0, 0);
;       }
;     }
;   }
;   __builtin_amdgcn_s_setprio(0);
.LBB0_1524:
	v_max3_f32 v96, v84, s67, v85
	v_max3_f32 v96, v96, v86, v87
	v_max3_f32 v96, v96, v80, v81
	v_max3_f32 v96, v96, v82, v83
	v_max3_f32 v96, v96, v92, v93
	v_max3_f32 v96, v96, v94, v95
	v_max3_f32 v96, v96, v88, v89
	v_max3_f32 v96, v96, v90, v91
	s_waitcnt lgkmcnt(0)
	v_fma_f32 v96, s3, v96, v112
	v_max_f32_e32 v96, 0xf149f2ca, v96
	v_mov_b32_e32 v97, v96
	s_nop 1
	v_permlane16_swap_b32_e32 v97, v96
	s_waitcnt lgkmcnt(0)
	v_max_f32_e32 v97, v97, v97
	v_max_f32_e32 v96, v96, v97
	v_mov_b32_e32 v97, v96
	s_nop 1
	v_permlane32_swap_b32_e32 v96, v97
	v_max3_f32 v244, v173, v96, v97
	v_max_f32_e32 v97, 0xe0ad78ec, v244
	v_sub_f32_e32 v97, v112, v97
	v_fma_f32 v80, s3, v80, v97
	v_exp_f32_e32 v98, v80
	v_fma_f32 v80, s3, v81, v97
	v_exp_f32_e32 v104, v80
	v_fma_f32 v80, s3, v82, v97
	v_exp_f32_e32 v99, v80
	v_fma_f32 v80, s3, v83, v97
	v_exp_f32_e32 v105, v80
	v_fma_f32 v80, s3, v92, v97
	v_exp_f32_e32 v108, v80
	v_fma_f32 v80, s3, v93, v97
	v_fma_f32 v84, s3, v84, v97
	v_exp_f32_e32 v109, v80
	v_fma_f32 v80, s3, v94, v97
	v_fma_f32 v85, s3, v85, v97
	v_exp_f32_e32 v100, v84
	v_exp_f32_e32 v110, v80
	v_fma_f32 v80, s3, v95, v97
	v_exp_f32_e32 v101, v85
	v_fma_f32 v84, s3, v86, v97
	v_exp_f32_e32 v111, v80
	v_fma_f32 v80, s3, v88, v97
	v_exp_f32_e32 v102, v84
	v_fma_f32 v84, s3, v87, v97
	v_exp_f32_e32 v112, v80
	v_fma_f32 v80, s3, v89, v97
	v_exp_f32_e32 v103, v84
	v_exp_f32_e32 v113, v80
	v_fma_f32 v80, s3, v90, v97
	v_exp_f32_e32 v114, v80
	v_add_f32_e32 v80, 0, v100
	v_add_f32_e32 v80, v101, v80
	v_add_f32_e32 v80, v102, v80
	v_add_f32_e32 v80, v103, v80
	v_add_f32_e32 v80, v98, v80
	v_add_f32_e32 v80, v104, v80
	v_add_f32_e32 v80, v99, v80
	v_add_f32_e32 v80, v105, v80
	v_add_f32_e32 v80, v108, v80
	v_add_f32_e32 v80, v109, v80
	v_fmac_f32_e32 v97, s3, v91
	v_add_f32_e32 v80, v110, v80
	v_sub_f32_e32 v96, v173, v244
	v_exp_f32_e32 v115, v97
	v_add_f32_e32 v80, v111, v80
	v_add_f32_e32 v80, v112, v80
	v_exp_f32_e32 v92, v96
	v_add_f32_e32 v80, v113, v80
	v_add_f32_e32 v80, v114, v80
	v_add_f32_e32 v188, v115, v80
	v_fmac_f32_e32 v188, v243, v92
	v_pk_mul_f32 v[82:83], v[30:31], v[92:93] op_sel_hi:[1,0]
	v_pk_mul_f32 v[80:81], v[28:29], v[92:93] op_sel_hi:[1,0]
	v_pk_mul_f32 v[86:87], v[34:35], v[92:93] op_sel_hi:[1,0]
	v_pk_mul_f32 v[84:85], v[32:33], v[92:93] op_sel_hi:[1,0]
	v_pk_mul_f32 v[90:91], v[38:39], v[92:93] op_sel_hi:[1,0]
	v_pk_mul_f32 v[88:89], v[36:37], v[92:93] op_sel_hi:[1,0]
	v_pk_mul_f32 v[94:95], v[42:43], v[92:93] op_sel_hi:[1,0]
	v_pk_mul_f32 v[92:93], v[40:41], v[92:93] op_sel_hi:[1,0]
	s_nop 0
	v_cvt_pk_f16_f32 v99, v99, v105
	v_cvt_pk_f16_f32 v98, v98, v104
	v_cvt_pk_f16_f32 v97, v102, v103
	v_cvt_pk_f16_f32 v96, v100, v101
	ds_read_b64_tr_b16 v[102:103], v205 offset:46080
	ds_read_b64_tr_b16 v[100:101], v205 offset:43520
	ds_read_b64_tr_b16 v[104:105], v205 offset:43552
	s_waitcnt lgkmcnt(1)
	v_mfma_f32_16x16x32_f16 v[80:83], v[100:103], v[96:99], v[80:83]
	ds_read_b64_tr_b16 v[106:107], v205 offset:46112
	ds_read_b64_tr_b16 v[100:101], v205 offset:43584
	ds_read_b64_tr_b16 v[102:103], v205 offset:46144
	s_mov_b64 s[52:53], -1
	s_waitcnt lgkmcnt(0)
	v_mfma_f32_16x16x32_f16 v[88:91], v[100:103], v[96:99], v[88:91]
	ds_read_b64_tr_b16 v[100:101], v205 offset:43616
	ds_read_b64_tr_b16 v[102:103], v205 offset:46176
	s_waitcnt lgkmcnt(0)
	v_mfma_f32_16x16x32_f16 v[92:95], v[100:103], v[96:99], v[92:95]
	ds_read_b64_tr_b16 v[100:101], v205 offset:48640
	ds_read_b64_tr_b16 v[102:103], v205 offset:51200
	v_mfma_f32_16x16x32_f16 v[84:87], v[104:107], v[96:99], v[84:87]
	v_cvt_pk_f16_f32 v99, v114, v115
	v_cvt_pk_f16_f32 v98, v112, v113
	v_cvt_pk_f16_f32 v97, v110, v111
	v_cvt_pk_f16_f32 v96, v108, v109
	s_waitcnt lgkmcnt(0)
	s_nop 0
	v_mfma_f32_16x16x32_f16 v[80:83], v[100:103], v[96:99], v[80:83]
	ds_read_b64_tr_b16 v[100:101], v205 offset:48672
	ds_read_b64_tr_b16 v[102:103], v205 offset:51232
	s_waitcnt lgkmcnt(0)
	v_mfma_f32_16x16x32_f16 v[84:87], v[100:103], v[96:99], v[84:87]
	ds_read_b64_tr_b16 v[100:101], v205 offset:48704
	ds_read_b64_tr_b16 v[102:103], v205 offset:51264
	s_waitcnt lgkmcnt(0)
	v_mfma_f32_16x16x32_f16 v[88:91], v[100:103], v[96:99], v[88:91]
	ds_read_b64_tr_b16 v[100:101], v205 offset:48736
	ds_read_b64_tr_b16 v[102:103], v205 offset:51296
	s_waitcnt lgkmcnt(0)
	v_mfma_f32_16x16x32_f16 v[92:95], v[100:103], v[96:99], v[92:95]
	s_and_b64 vcc, exec, s[0:1]
	s_cbranch_vccnz .LBB0_1483

; template <int MODE, int TM> ...
;     ...
;   __builtin_amdgcn_s_setprio(1);
; #pragma unroll
;   for (int t = 0; t < 2; ++t) {
;     if (!(TM & (1 << t))) continue;
;     const h16* Ks = t ? Ks1 : Ks0;
; #pragma unroll
;     for (int kt = 0; kt < 4; ++kt) {
;       S[t][kt] = f32x4{0.f, 0.f, 0.f, 0.f};
; #pragma unroll
;       for (int ks = 0; ks < 2; ++ks) {
;         h16x8 Kf = *(const h16x8*)(Ks + (kt * 16 + col) * KP + ks * 32 + q4 * 8);
;         S[t][kt] = __builtin_amdgcn_mfma_f32_16x16x32_f16(Kf, Q[ks], S[t][kt], 0, 0, 0);
;       }
;     }
;   }
;   __builtin_amdgcn_s_setprio(0);
;   const float* bt = biasT + hd * 800;
;   float addc[2] = {0.f, 0.f}, sclc[2] = {1.f, 1.f};
; #pragma unroll
;   for (int t = 0; t < 2; ++t) {
;     if (!(TM & (1 << t))) continue;
;     const int kbase = kbase0 + 64 * t;
;     if (far[t]) {
;       const bool ok = (MODE == M_SEL) ? selbit[t] : true;
;       addc[t] = ok ? bt[799] : -1e30f;
;       sclc[t] = SCL2;
;     } else {
;       addc[t] = 0.f;
;       sclc[t] = 1.f;
;       const int kx0 = kbase + q4 * 4;
;       const int d0 = (DK == 16) ? tq - 31 - 16 * kx0 : tq - kx0;
; #pragma unroll
;       for (int kt = 0; kt < 4; ++kt)
; #pragma unroll
;         for (int j = 0; j < 4; ++j) {
;           const int dist = d0 - DK * (kt * 16 + j);
;           const int kx = kx0 + kt * 16 + j;
;           bool valid = dist >= 0;
;           if (MODE == M_WIN) valid = valid && dist < 512 && kx >= 0;
;           if (MODE == M_SEL) valid = valid && selbit[t];
;           if (DK == 16) valid = valid && kx < NCMP;
;           const int dc = dist < 0 ? 0 : (dist > 799 ? 799 : dist);
;           S[t][kt][j] = valid ? S[t][kt][j] * SCL2 + bt[dc] : -1e30f;
.LBB0_1526:
	s_nop 0
	ds_read_b128 v[80:83], v155 offset:12800
	ds_read_b128 v[84:87], v155 offset:12864
	ds_read_b128 v[88:91], v155 offset:15360
	ds_read_b128 v[96:99], v155 offset:15424
	ds_read_b128 v[100:103], v155 offset:33280
	ds_read_b128 v[104:107], v155 offset:35840
	s_waitcnt lgkmcnt(5)
	v_mfma_f32_16x16x32_f16 v[80:83], v[80:83], v[4:7], 0
	ds_read_b128 v[108:111], v155 offset:38400
	ds_read_b128 v[112:115], v155 offset:40960
	s_waitcnt lgkmcnt(6)
	v_mfma_f32_16x16x32_f16 v[92:95], v[84:87], v[8:11], v[80:83]
	ds_read_b128 v[84:87], v155 offset:17984
	s_nop 2
	ds_read_b128 v[80:83], v155 offset:17920
	s_waitcnt lgkmcnt(7)
	v_mfma_f32_16x16x32_f16 v[88:91], v[88:91], v[4:7], 0
	s_waitcnt lgkmcnt(6)
	v_mfma_f32_16x16x32_f16 v[88:91], v[96:99], v[8:11], v[88:91]
	ds_read_b128 v[96:99], v155 offset:20480
	s_waitcnt lgkmcnt(1)
	v_mfma_f32_16x16x32_f16 v[80:83], v[80:83], v[4:7], 0
	v_mfma_f32_16x16x32_f16 v[84:87], v[84:87], v[8:11], v[80:83]
	s_nop 6
	ds_read_b128 v[80:83], v155 offset:20544
	s_waitcnt lgkmcnt(1)
	v_mfma_f32_16x16x32_f16 v[96:99], v[96:99], v[4:7], 0
	s_waitcnt lgkmcnt(0)
	v_mfma_f32_16x16x32_f16 v[80:83], v[80:83], v[8:11], v[96:99]
	s_nop 5
	ds_read_b128 v[96:99], v155 offset:33344
	v_mfma_f32_16x16x32_f16 v[100:103], v[100:103], v[4:7], 0
	s_waitcnt lgkmcnt(0)
	v_mfma_f32_16x16x32_f16 v[96:99], v[96:99], v[8:11], v[100:103]
	s_nop 5
	ds_read_b128 v[100:103], v155 offset:35904
	v_mfma_f32_16x16x32_f16 v[104:107], v[104:107], v[4:7], 0
	s_waitcnt lgkmcnt(0)
	v_mfma_f32_16x16x32_f16 v[100:103], v[100:103], v[8:11], v[104:107]
	s_nop 5
	ds_read_b128 v[104:107], v155 offset:38464
	v_mfma_f32_16x16x32_f16 v[108:111], v[108:111], v[4:7], 0
	s_waitcnt lgkmcnt(0)
	v_mfma_f32_16x16x32_f16 v[104:107], v[104:107], v[8:11], v[108:111]
	s_nop 5
	ds_read_b128 v[108:111], v155 offset:41024
	v_mfma_f32_16x16x32_f16 v[112:115], v[112:115], v[4:7], 0
	s_waitcnt lgkmcnt(0)
	v_mfma_f32_16x16x32_f16 v[108:111], v[108:111], v[8:11], v[112:115]
	s_nop 0
	v_or_b32_e32 v244, s2, v154
	s_mov_b64 s[0:1], -1
	s_and_b64 vcc, exec, s[50:51]
	s_cbranch_vccz .LBB0_1560
	s_nop 0
	v_sub_u32_e32 v114, v182, v244
	v_cmp_lt_i32_e64 s[0:1], -1, v114
	v_cmp_eq_u32_e32 vcc, 1, v0
	s_and_b64 s[2:3], s[0:1], vcc
	v_mov_b32_e32 v113, 0xf149f2ca
	v_mov_b32_e32 v112, 0xf149f2ca
	s_and_saveexec_b64 s[0:1], s[2:3]
	s_cbranch_execz .LBB0_1529
	v_min_u32_e32 v112, 0x31f, v114
	v_lshl_add_u32 v112, v112, 2, v157
	ds_read_b32 v112, v112

; #define LAS __attribute__((address_space(3)))
; template <int MODE, int TM> ...
;     ...
;     float mx = -1e30f;
; #pragma unroll
;     for (int t = 0; t < 2; ++t) {
;       if (!(TM & (1 << t))) continue;
;       float mt = -1e30f;
; #pragma unroll
;       for (int kt = 0; kt < 4; ++kt)
; #pragma unroll
;         for (int j = 0; j < 4; ++j) mt = fmaxf(mt, S[t][kt][j]);
;       mx = fmaxf(mx, mt * sclc[t] + addc[t]);
;     }
;     mx = max4q(mx);
;     const float mn = fmaxf(st.m, mx);
;     const float corr = __builtin_amdgcn_exp2f(st.m - mn);
;     st.m = mn;
;     const float mm = fmaxf(mn, -1e20f);
;     float ls = 0.f;
; #pragma unroll
;     for (int t = 0; t < 2; ++t) {
;       if (!(TM & (1 << t))) continue;
;       const float am = addc[t] - mm;
; #pragma unroll
;       for (int kt = 0; kt < 4; ++kt) {
;         const f32x4 e = S[t][kt] * sclc[t] + am;
; #pragma unroll
;         for (int j = 0; j < 4; ++j) {
;           float pv = __builtin_amdgcn_exp2f(e[j]);
;           S[t][kt][j] = pv;
;           ls += pv;
;         }
;       }
;     }
;     st.l = st.l * corr + ls;
;     if (MODE != M_CMPA) {
; #pragma unroll
;       for (int nt = 0; nt < 4; ++nt) O[nt] *= corr;
;     }
;   }
;     ...
;   for (int t = 0; t < 2; ++t) {
;     if (!(TM & (1 << t))) continue;
;     const h16* Vt = t ? Vt1 : Vt0;
; #pragma unroll
;     for (int ks = 0; ks < 2; ++ks) {
;       h16x8 Pf;
; #pragma unroll
;       for (int i = 0; i < 4; ++i) { Pf[i] = (h16)S[t][2 * ks][i]; Pf[4 + i] = (h16)S[t][2 * ks + 1][i]; }
; #pragma unroll
;       for (int nt = 0; nt < 4; ++nt) {
;         const h16* vp = Vt + (ks * 32 + q4 * 4 + (col >> 2)) * KP + nt * 16 + 4 * (col & 3);
;         const s16x4v r0 = __builtin_amdgcn_ds_read_tr16_b64_v4i16((LAS s16x4v*)vp);
;         const s16x4v r1 = __builtin_amdgcn_ds_read_tr16_b64_v4i16((LAS s16x4v*)(vp + 16 * KP));
;         const h16x4 v0 = __builtin_bit_cast(h16x4, r0), v1 = __builtin_bit_cast(h16x4, r1);
;         const h16x8 Vf = {v0[0], v0[1], v0[2], v0[3], v1[0], v1[1], v1[2], v1[3]};
;         O[nt] = __builtin_amdgcn_mfma_f32_16x16x32_f16(Vf, Pf, O[nt], 0, 0, 0);
;       }
;     }
;   }
;   __builtin_amdgcn_s_setprio(0);
.LBB0_1602:
	s_waitcnt lgkmcnt(0)
	v_max3_f32 v0, v92, s67, v93
	v_max3_f32 v96, v112, s67, v113
	v_max3_f32 v0, v0, v94, v95
	v_max3_f32 v96, v96, v114, v115
	v_max3_f32 v0, v0, v88, v89
	v_max3_f32 v96, v96, v116, v117
	v_max3_f32 v0, v0, v90, v91
	v_max3_f32 v96, v96, v118, v119
	v_max3_f32 v0, v0, v84, v85
	v_max3_f32 v96, v96, v120, v121
	v_max3_f32 v0, v0, v86, v87
	v_max3_f32 v96, v96, v122, v123
	v_max3_f32 v0, v0, v80, v81
	v_max3_f32 v96, v96, v124, v125
	v_max3_f32 v0, v0, v82, v83
	v_max3_f32 v96, v96, v126, v127
	v_fma_f32 v0, s2, v0, v188
	v_fma_f32 v96, s3, v96, v189
	v_max3_f32 v0, v0, s67, v96
	v_mov_b32_e32 v96, v0
	s_nop 1
	v_permlane16_swap_b32_e32 v96, v0
	s_waitcnt lgkmcnt(0)
	v_max_f32_e32 v96, v96, v96
	v_max_f32_e32 v0, v0, v96
	v_mov_b32_e32 v96, v0
	s_nop 1
	v_permlane32_swap_b32_e32 v0, v96
	v_max3_f32 v244, v173, v0, v96
	v_max_f32_e32 v0, 0xe0ad78ec, v244
	v_sub_f32_e32 v96, v188, v0
	v_fma_f32 v92, s2, v92, v96
	v_exp_f32_e32 v92, v92
	v_fma_f32 v93, s2, v93, v96
	v_exp_f32_e32 v93, v93
	v_fma_f32 v94, s2, v94, v96
	v_exp_f32_e32 v94, v94
	v_fma_f32 v95, s2, v95, v96
	v_exp_f32_e32 v95, v95
	v_fma_f32 v88, s2, v88, v96
	v_add_f32_e32 v98, 0, v92
	v_exp_f32_e32 v88, v88
	v_fma_f32 v89, s2, v89, v96
	v_add_f32_e32 v98, v93, v98
	v_exp_f32_e32 v89, v89
	v_fma_f32 v90, s2, v90, v96
	v_add_f32_e32 v98, v94, v98
	v_exp_f32_e32 v90, v90
	v_fma_f32 v91, s2, v91, v96
	v_add_f32_e32 v98, v95, v98
	v_exp_f32_e32 v91, v91
	v_fma_f32 v84, s2, v84, v96
	v_add_f32_e32 v98, v88, v98
	v_exp_f32_e32 v99, v84
	v_fma_f32 v85, s2, v85, v96
	v_add_f32_e32 v84, v89, v98
	v_exp_f32_e32 v98, v85
	v_fma_f32 v85, s2, v86, v96
	v_add_f32_e32 v84, v90, v84
	v_exp_f32_e32 v100, v85
	v_fma_f32 v85, s2, v87, v96
	v_add_f32_e32 v84, v91, v84
	v_exp_f32_e32 v101, v85
	v_fma_f32 v80, s2, v80, v96
	v_add_f32_e32 v84, v99, v84
	v_exp_f32_e32 v102, v80
	v_fma_f32 v81, s2, v81, v96
	v_add_f32_e32 v80, v98, v84
	v_exp_f32_e32 v103, v81
	v_fma_f32 v81, s2, v82, v96
	v_add_f32_e32 v80, v100, v80
	v_exp_f32_e32 v104, v81
	v_fmac_f32_e32 v96, s2, v83
	v_sub_f32_e32 v0, v189, v0
	v_add_f32_e32 v80, v101, v80
	v_exp_f32_e32 v96, v96
	v_fma_f32 v81, s3, v112, v0
	v_add_f32_e32 v80, v102, v80
	v_exp_f32_e32 v105, v81
	v_fma_f32 v81, s3, v113, v0
	v_add_f32_e32 v80, v103, v80
	v_exp_f32_e32 v106, v81
	v_fma_f32 v81, s3, v114, v0
	v_add_f32_e32 v80, v104, v80
	v_exp_f32_e32 v107, v81
	v_fma_f32 v81, s3, v115, v0
	v_add_f32_e32 v80, v96, v80
	v_exp_f32_e32 v108, v81
	v_fma_f32 v81, s3, v116, v0
	v_add_f32_e32 v80, v105, v80
	v_exp_f32_e32 v109, v81
	v_fma_f32 v81, s3, v117, v0
	v_add_f32_e32 v80, v106, v80
	v_exp_f32_e32 v110, v81
	v_fma_f32 v81, s3, v118, v0
	v_add_f32_e32 v80, v107, v80
	v_exp_f32_e32 v111, v81
	v_fma_f32 v81, s3, v119, v0
	v_add_f32_e32 v80, v108, v80
	v_exp_f32_e32 v112, v81
	v_fma_f32 v81, s3, v120, v0
	v_add_f32_e32 v80, v109, v80
	v_exp_f32_e32 v113, v81
	v_fma_f32 v81, s3, v121, v0
	v_add_f32_e32 v80, v110, v80
	v_exp_f32_e32 v114, v81
	v_fma_f32 v81, s3, v122, v0
	v_add_f32_e32 v80, v111, v80
	v_exp_f32_e32 v115, v81
	v_fma_f32 v81, s3, v123, v0
	v_add_f32_e32 v80, v112, v80
	v_exp_f32_e32 v116, v81
	v_fma_f32 v81, s3, v124, v0
	v_add_f32_e32 v80, v113, v80
	v_exp_f32_e32 v117, v81
	v_fma_f32 v81, s3, v125, v0
	v_add_f32_e32 v80, v114, v80
	v_exp_f32_e32 v118, v81
	v_fma_f32 v81, s3, v126, v0
	v_add_f32_e32 v80, v115, v80
	v_exp_f32_e32 v119, v81
	v_fmac_f32_e32 v0, s3, v127
	v_sub_f32_e32 v97, v173, v244
	v_add_f32_e32 v80, v116, v80
	v_exp_f32_e32 v120, v0
	v_add_f32_e32 v80, v117, v80
	v_exp_f32_e32 v0, v97
	v_add_f32_e32 v80, v118, v80
	v_add_f32_e32 v80, v119, v80
	v_add_f32_e32 v188, v120, v80
	v_fmac_f32_e32 v188, v243, v0
	v_pk_mul_f32 v[30:31], v[30:31], v[0:1] op_sel_hi:[1,0]
	v_pk_mul_f32 v[28:29], v[28:29], v[0:1] op_sel_hi:[1,0]
	v_pk_mul_f32 v[34:35], v[34:35], v[0:1] op_sel_hi:[1,0]
	v_pk_mul_f32 v[32:33], v[32:33], v[0:1] op_sel_hi:[1,0]
	v_pk_mul_f32 v[38:39], v[38:39], v[0:1] op_sel_hi:[1,0]
	v_pk_mul_f32 v[36:37], v[36:37], v[0:1] op_sel_hi:[1,0]
	v_pk_mul_f32 v[42:43], v[42:43], v[0:1] op_sel_hi:[1,0]
	v_pk_mul_f32 v[40:41], v[40:41], v[0:1] op_sel_hi:[1,0]
	s_nop 0
	v_cvt_pk_f16_f32 v82, v88, v89
	ds_read_b64_tr_b16 v[86:87], v205 offset:25600
	ds_read_b64_tr_b16 v[84:85], v205 offset:23040
	ds_read_b64_tr_b16 v[88:89], v205 offset:23072
	v_cvt_pk_f16_f32 v83, v90, v91
	v_cvt_pk_f16_f32 v81, v94, v95
	v_cvt_pk_f16_f32 v80, v92, v93
	ds_read_b64_tr_b16 v[90:91], v205 offset:25632
	v_cvt_pk_f16_f32 v95, v119, v120
	s_waitcnt lgkmcnt(2)
; #define LAS __attribute__((address_space(3)))
; template <int MODE, int TM> ...
;     ...
;   for (int t = 0; t < 2; ++t) {
;     if (!(TM & (1 << t))) continue;
;     const h16* Vt = t ? Vt1 : Vt0;
; #pragma unroll
;     for (int ks = 0; ks < 2; ++ks) {
;       h16x8 Pf;
; #pragma unroll
;       for (int i = 0; i < 4; ++i) { Pf[i] = (h16)S[t][2 * ks][i]; Pf[4 + i] = (h16)S[t][2 * ks + 1][i]; }
; #pragma unroll
;       for (int nt = 0; nt < 4; ++nt) {
;         const h16* vp = Vt + (ks * 32 + q4 * 4 + (col >> 2)) * KP + nt * 16 + 4 * (col & 3);
;         const s16x4v r0 = __builtin_amdgcn_ds_read_tr16_b64_v4i16((LAS s16x4v*)vp);
;         const s16x4v r1 = __builtin_amdgcn_ds_read_tr16_b64_v4i16((LAS s16x4v*)(vp + 16 * KP));
;         const h16x4 v0 = __builtin_bit_cast(h16x4, r0), v1 = __builtin_bit_cast(h16x4, r1);
;         const h16x8 Vf = {v0[0], v0[1], v0[2], v0[3], v1[0], v1[1], v1[2], v1[3]};
;         O[nt] = __builtin_amdgcn_mfma_f32_16x16x32_f16(Vf, Pf, O[nt], 0, 0, 0);
;       }
;     }
;   }
;   __builtin_amdgcn_s_setprio(0);
	v_mfma_f32_16x16x32_f16 v[28:31], v[84:87], v[80:83], v[28:31]
	ds_read_b64_tr_b16 v[84:85], v205 offset:23104
	ds_read_b64_tr_b16 v[86:87], v205 offset:25664
	v_cvt_pk_f16_f32 v94, v117, v118
	v_cvt_pk_f16_f32 v93, v115, v116
	s_waitcnt lgkmcnt(0)
	v_mfma_f32_16x16x32_f16 v[36:39], v[84:87], v[80:83], v[36:39]
	ds_read_b64_tr_b16 v[84:85], v205 offset:23136
	ds_read_b64_tr_b16 v[86:87], v205 offset:25696
	v_cvt_pk_f16_f32 v92, v113, v114
	s_mov_b64 s[52:53], -1
	s_waitcnt lgkmcnt(0)
	v_mfma_f32_16x16x32_f16 v[40:43], v[84:87], v[80:83], v[40:43]
	ds_read_b64_tr_b16 v[84:85], v205 offset:28160
	ds_read_b64_tr_b16 v[86:87], v205 offset:30720
	v_mfma_f32_16x16x32_f16 v[32:35], v[88:91], v[80:83], v[32:35]
	v_cvt_pk_f16_f32 v83, v104, v96
	v_cvt_pk_f16_f32 v82, v102, v103
	v_cvt_pk_f16_f32 v81, v100, v101
	v_cvt_pk_f16_f32 v80, v99, v98
	s_waitcnt lgkmcnt(0)
	s_nop 0
	v_mfma_f32_16x16x32_f16 v[28:31], v[84:87], v[80:83], v[28:31]
	ds_read_b64_tr_b16 v[84:85], v205 offset:28192
	ds_read_b64_tr_b16 v[86:87], v205 offset:30752
	s_waitcnt lgkmcnt(0)
	v_mfma_f32_16x16x32_f16 v[32:35], v[84:87], v[80:83], v[32:35]
	ds_read_b64_tr_b16 v[84:85], v205 offset:28224
	ds_read_b64_tr_b16 v[86:87], v205 offset:30784
	s_waitcnt lgkmcnt(0)
	v_mfma_f32_16x16x32_f16 v[36:39], v[84:87], v[80:83], v[36:39]
	ds_read_b64_tr_b16 v[84:85], v205 offset:28256
	ds_read_b64_tr_b16 v[86:87], v205 offset:30816
	s_waitcnt lgkmcnt(0)
	v_mfma_f32_16x16x32_f16 v[40:43], v[84:87], v[80:83], v[40:43]
	ds_read_b64_tr_b16 v[84:85], v205 offset:43520
	ds_read_b64_tr_b16 v[86:87], v205 offset:46080
	v_cvt_pk_f16_f32 v83, v111, v112
	v_cvt_pk_f16_f32 v82, v109, v110
	v_cvt_pk_f16_f32 v81, v107, v108
	v_cvt_pk_f16_f32 v80, v105, v106
	s_waitcnt lgkmcnt(0)
	s_nop 0
	v_mfma_f32_16x16x32_f16 v[28:31], v[84:87], v[80:83], v[28:31]
	ds_read_b64_tr_b16 v[84:85], v205 offset:43552
	ds_read_b64_tr_b16 v[86:87], v205 offset:46112
	s_waitcnt lgkmcnt(0)
	v_mfma_f32_16x16x32_f16 v[32:35], v[84:87], v[80:83], v[32:35]
	ds_read_b64_tr_b16 v[84:85], v205 offset:43584
	ds_read_b64_tr_b16 v[86:87], v205 offset:46144
	s_waitcnt lgkmcnt(0)
	v_mfma_f32_16x16x32_f16 v[36:39], v[84:87], v[80:83], v[36:39]
	ds_read_b64_tr_b16 v[84:85], v205 offset:43616
	ds_read_b64_tr_b16 v[86:87], v205 offset:46176
	s_waitcnt lgkmcnt(0)
	v_mfma_f32_16x16x32_f16 v[40:43], v[84:87], v[80:83], v[40:43]
	ds_read_b64_tr_b16 v[80:81], v205 offset:48640
	ds_read_b64_tr_b16 v[82:83], v205 offset:51200
	s_waitcnt lgkmcnt(0)
	v_mfma_f32_16x16x32_f16 v[80:83], v[80:83], v[92:95], v[28:31]
	s_nop 2
	ds_read_b64_tr_b16 v[28:29], v205 offset:48672
	ds_read_b64_tr_b16 v[30:31], v205 offset:51232
	s_waitcnt lgkmcnt(0)
	v_mfma_f32_16x16x32_f16 v[84:87], v[28:31], v[92:95], v[32:35]
	ds_read_b64_tr_b16 v[28:29], v205 offset:48704
	ds_read_b64_tr_b16 v[30:31], v205 offset:51264
	s_waitcnt lgkmcnt(0)
	v_mfma_f32_16x16x32_f16 v[88:91], v[28:31], v[92:95], v[36:39]
	ds_read_b64_tr_b16 v[28:29], v205 offset:48736
	ds_read_b64_tr_b16 v[30:31], v205 offset:51296
	s_waitcnt lgkmcnt(0)
	v_mfma_f32_16x16x32_f16 v[92:95], v[28:31], v[92:95], v[40:43]
.LBB0_1603:
	s_and_b64 vcc, exec, s[52:53]
	s_cbranch_vccz .LBB0_1605
	s_nop 0

; template <int MODE, int TM> ...
;     ...
;   __builtin_amdgcn_s_setprio(1);
; #pragma unroll
;   for (int t = 0; t < 2; ++t) {
;     if (!(TM & (1 << t))) continue;
;     const h16* Ks = t ? Ks1 : Ks0;
; #pragma unroll
;     for (int kt = 0; kt < 4; ++kt) {
;       S[t][kt] = f32x4{0.f, 0.f, 0.f, 0.f};
; #pragma unroll
;       for (int ks = 0; ks < 2; ++ks) {
;         h16x8 Kf = *(const h16x8*)(Ks + (kt * 16 + col) * KP + ks * 32 + q4 * 8);
;         S[t][kt] = __builtin_amdgcn_mfma_f32_16x16x32_f16(Kf, Q[ks], S[t][kt], 0, 0, 0);
;       }
;     }
;   }
;   __builtin_amdgcn_s_setprio(0);
;     ...
;         const int jb = 2 * i;
;         bool sb[2];
;         sb[0] = ((jb < 64 ? (slo >> jb) : (shi >> (jb - 64))) & 1ull) != 0;
;         sb[1] = (jb + 1 <= cur) && (((jb + 1 < 64 ? (slo >> (jb + 1)) : (shi >> (jb + 1 - 64))) & 1ull) != 0);
;         const bool far[2] = {t0 - (jb * 64 + 63) >= 799, t0 - (jb * 64 + 127) >= 799};
;         const bool n0 = __any(sb[0]) != 0, n1 = __any(sb[1]) != 0;
;         if (n0 && n1) attn_tile2<M_SEL, 3>(Q, O, st, KSB(i, 0), VTB(i, 0), KSB(i, 1), VTB(i, 1), biasT, tq, hd, jb * 64, far, sb, hpd, hpe, lane);
;         else if (n0) attn_tile2<M_SEL, 1>(Q, O, st, KSB(i, 0), VTB(i, 0), KSB(i, 1), VTB(i, 1), biasT, tq, hd, jb * 64, far, sb, hpd, hpe, lane);
;         else if (n1) attn_tile2<M_SEL, 2>(Q, O, st, KSB(i, 0), VTB(i, 0), KSB(i, 1), VTB(i, 1), biasT, tq, hd, jb * 64, far, sb, hpd, hpe, lane);
.LBB0_1618:
	s_lshl_b32 s2, s31, 1
	s_sub_i32 s3, s2, 64
	s_and_b64 s[0:1], s[42:43], exec
	s_cselect_b32 s0, s2, s3
	s_cmp_lt_u32 s2, s28
	v_lshrrev_b64 v[28:29], s0, v[2:3]
	s_cselect_b64 s[0:1], -1, 0
	s_or_b32 s44, s2, 1
	s_sub_i32 s45, s2, 63
	s_and_b64 s[2:3], s[42:43], exec
	s_cselect_b32 s2, s44, s45
	s_lshl_b64 s[2:3], 1, s2
	v_and_b32_e32 v3, s3, v3
	v_and_b32_e32 v2, s2, v2
	v_cmp_ne_u64_e32 vcc, 0, v[2:3]
	s_lshl_b32 s2, s31, 7
	s_and_b64 s[42:43], s[0:1], vcc
	s_sub_i32 s0, s20, s2
	s_cmpk_lt_i32 s0, 0x35e
	v_and_b32_e32 v0, 1, v28
	s_cselect_b64 s[46:47], -1, 0
	s_cmpk_lt_i32 s0, 0x39e
	v_cmp_ne_u32_e32 vcc, 0, v0
	s_cselect_b64 s[44:45], -1, 0
	s_cmp_eq_u64 vcc, 0
	v_cndmask_b32_e64 v2, 0, 1, s[42:43]
	s_cselect_b64 s[0:1], -1, 0
	s_cmp_lg_u64 vcc, 0
	v_cmp_ne_u32_e32 vcc, 0, v2
	s_cselect_b64 s[50:51], -1, 0
	s_cmp_lg_u64 vcc, 0
	s_cselect_b64 s[48:49], -1, 0
	s_and_b64 s[50:51], s[50:51], s[48:49]
	s_and_b64 vcc, exec, s[50:51]
	s_cbranch_vccnz .LBB0_1660
	s_and_b64 vcc, exec, s[0:1]
	s_cbranch_vccz .LBB0_1661
	v_mov_b64_e32 v[28:29], v[80:81]
	v_mov_b64_e32 v[32:33], v[84:85]
	v_mov_b64_e32 v[36:37], v[88:89]
	v_mov_b64_e32 v[40:41], v[92:93]
	s_mov_b64 s[0:1], 0
	s_and_b64 vcc, exec, s[48:49]
	v_mov_b32_e32 v243, v188
	v_mov_b32_e32 v173, v244
	v_mov_b64_e32 v[30:31], v[82:83]
	v_mov_b64_e32 v[34:35], v[86:87]
	v_mov_b64_e32 v[38:39], v[90:91]
	v_mov_b64_e32 v[42:43], v[94:95]
	s_mov_b64 s[48:49], 0
	s_cbranch_vccz .LBB0_1662
	s_nop 0
	ds_read_b128 v[28:31], v202
	ds_read_b128 v[32:35], v202 offset:64
	ds_read_b128 v[36:39], v202 offset:2560
	ds_read_b128 v[40:43], v202 offset:2624
	ds_read_b128 v[96:99], v202 offset:5120
	s_waitcnt lgkmcnt(4)
	v_mfma_f32_16x16x32_f16 v[28:31], v[28:31], v[4:7], 0
	s_waitcnt lgkmcnt(2)
	v_mfma_f32_16x16x32_f16 v[36:39], v[36:39], v[4:7], 0
	v_mfma_f32_16x16x32_f16 v[32:35], v[32:35], v[8:11], v[28:31]
	s_waitcnt lgkmcnt(1)
	v_mfma_f32_16x16x32_f16 v[28:31], v[40:43], v[8:11], v[36:39]
	s_nop 4
	ds_read_b128 v[36:39], v202 offset:5184
	s_waitcnt lgkmcnt(1)
	v_mfma_f32_16x16x32_f16 v[40:43], v[96:99], v[4:7], 0
	ds_read_b128 v[96:99], v202 offset:7680
	s_waitcnt lgkmcnt(1)
	v_mfma_f32_16x16x32_f16 v[40:43], v[36:39], v[8:11], v[40:43]
	ds_read_b128 v[36:39], v202 offset:7744
	s_waitcnt lgkmcnt(1)
	v_mfma_f32_16x16x32_f16 v[96:99], v[96:99], v[4:7], 0
	s_waitcnt lgkmcnt(0)
	v_mfma_f32_16x16x32_f16 v[36:39], v[36:39], v[8:11], v[96:99]
	s_nop 0
	s_andn2_b64 vcc, exec, s[44:45]
	s_mov_b64 s[48:49], -1
	s_cbranch_vccnz .LBB0_1655
	v_or_b32_e32 v2, s2, v154
	v_sub_u32_e32 v3, v175, v2
	v_cmp_lt_i32_e32 vcc, -1, v3
	s_and_b64 s[50:51], vcc, s[42:43]
	v_mov_b32_e32 v97, 0xf149f2ca
	v_mov_b32_e32 v96, 0xf149f2ca
	s_and_saveexec_b64 s[48:49], s[50:51]
	s_cbranch_execz .LBB0_1624
	v_min_u32_e32 v3, 0x31f, v3
	v_lshl_add_u32 v3, v3, 2, v157
	ds_read_b32 v96, v3

; template <int MODE, int TM> ...
;     ...
;   __builtin_amdgcn_s_setprio(1);
; #pragma unroll
;   for (int t = 0; t < 2; ++t) {
;     if (!(TM & (1 << t))) continue;
;     const h16* Ks = t ? Ks1 : Ks0;
; #pragma unroll
;     for (int kt = 0; kt < 4; ++kt) {
;       S[t][kt] = f32x4{0.f, 0.f, 0.f, 0.f};
; #pragma unroll
;       for (int ks = 0; ks < 2; ++ks) {
;         h16x8 Kf = *(const h16x8*)(Ks + (kt * 16 + col) * KP + ks * 32 + q4 * 8);
;         S[t][kt] = __builtin_amdgcn_mfma_f32_16x16x32_f16(Kf, Q[ks], S[t][kt], 0, 0, 0);
;       }
;     }
;   }
;   __builtin_amdgcn_s_setprio(0);
;   const float* bt = biasT + hd * 800;
;   float addc[2] = {0.f, 0.f}, sclc[2] = {1.f, 1.f};
; #pragma unroll
;   for (int t = 0; t < 2; ++t) {
;     if (!(TM & (1 << t))) continue;
;     const int kbase = kbase0 + 64 * t;
;     if (far[t]) {
;       const bool ok = (MODE == M_SEL) ? selbit[t] : true;
;       addc[t] = ok ? bt[799] : -1e30f;
;       sclc[t] = SCL2;
;     } else {
;       addc[t] = 0.f;
;       sclc[t] = 1.f;
;       const int kx0 = kbase + q4 * 4;
;       const int d0 = (DK == 16) ? tq - 31 - 16 * kx0 : tq - kx0;
; #pragma unroll
;       for (int kt = 0; kt < 4; ++kt)
; #pragma unroll
;         for (int j = 0; j < 4; ++j) {
;           const int dist = d0 - DK * (kt * 16 + j);
;           const int kx = kx0 + kt * 16 + j;
;           bool valid = dist >= 0;
;           if (MODE == M_WIN) valid = valid && dist < 512 && kx >= 0;
;           if (MODE == M_SEL) valid = valid && selbit[t];
;           if (DK == 16) valid = valid && kx < NCMP;
;           const int dc = dist < 0 ? 0 : (dist > 799 ? 799 : dist);
;           S[t][kt][j] = valid ? S[t][kt][j] * SCL2 + bt[dc] : -1e30f;
.LBB0_1663:
	s_nop 0
	ds_read_b128 v[28:31], v155 offset:53760
	ds_read_b128 v[32:35], v155 offset:53824
	ds_read_b128 v[36:39], v155 offset:56320
	ds_read_b128 v[96:99], v155 offset:56384
	s_waitcnt lgkmcnt(3)
	v_mfma_f32_16x16x32_f16 v[28:31], v[28:31], v[4:7], 0
	s_waitcnt lgkmcnt(2)
	v_mfma_f32_16x16x32_f16 v[40:43], v[32:35], v[8:11], v[28:31]
	ds_read_b128 v[32:35], v155 offset:58944
	s_nop 4
	ds_read_b128 v[28:31], v155 offset:58880
	s_waitcnt lgkmcnt(3)
	v_mfma_f32_16x16x32_f16 v[36:39], v[36:39], v[4:7], 0
	s_waitcnt lgkmcnt(2)
	v_mfma_f32_16x16x32_f16 v[36:39], v[96:99], v[8:11], v[36:39]
	ds_read_b128 v[96:99], v155 offset:61440
	s_waitcnt lgkmcnt(1)
	v_mfma_f32_16x16x32_f16 v[28:31], v[28:31], v[4:7], 0
	v_mfma_f32_16x16x32_f16 v[32:35], v[32:35], v[8:11], v[28:31]
	s_nop 6
	ds_read_b128 v[28:31], v155 offset:61504
	s_waitcnt lgkmcnt(1)
	v_mfma_f32_16x16x32_f16 v[96:99], v[96:99], v[4:7], 0
	s_waitcnt lgkmcnt(0)
	v_mfma_f32_16x16x32_f16 v[28:31], v[28:31], v[8:11], v[96:99]
	s_nop 0
	s_andn2_b64 vcc, exec, s[46:47]
	s_mov_b64 s[0:1], -1
	s_cbranch_vccnz .LBB0_1697
	v_or_b32_e32 v2, s2, v154
	v_sub_u32_e32 v3, v182, v2
	v_cmp_lt_i32_e64 s[0:1], -1, v3
	v_cmp_eq_u32_e32 vcc, 1, v0
	s_and_b64 s[48:49], s[0:1], vcc
	v_mov_b32_e32 v97, 0xf149f2ca
	v_mov_b32_e32 v96, 0xf149f2ca
	s_and_saveexec_b64 s[0:1], s[48:49]
	s_cbranch_execz .LBB0_1666
	v_min_u32_e32 v3, 0x31f, v3
	v_lshl_add_u32 v3, v3, 2, v157
	ds_read_b32 v96, v3

; #define LAS __attribute__((address_space(3)))
; template <int MODE, int TM> ...
;     ...
;     float mx = -1e30f;
; #pragma unroll
;     for (int t = 0; t < 2; ++t) {
;       if (!(TM & (1 << t))) continue;
;       float mt = -1e30f;
; #pragma unroll
;       for (int kt = 0; kt < 4; ++kt)
; #pragma unroll
;         for (int j = 0; j < 4; ++j) mt = fmaxf(mt, S[t][kt][j]);
;       mx = fmaxf(mx, mt * sclc[t] + addc[t]);
;     }
;     mx = max4q(mx);
;     const float mn = fmaxf(st.m, mx);
;     const float corr = __builtin_amdgcn_exp2f(st.m - mn);
;     st.m = mn;
;     const float mm = fmaxf(mn, -1e20f);
;     float ls = 0.f;
; #pragma unroll
;     for (int t = 0; t < 2; ++t) {
;       if (!(TM & (1 << t))) continue;
;       const float am = addc[t] - mm;
; #pragma unroll
;       for (int kt = 0; kt < 4; ++kt) {
;         const f32x4 e = S[t][kt] * sclc[t] + am;
; #pragma unroll
;         for (int j = 0; j < 4; ++j) {
;           float pv = __builtin_amdgcn_exp2f(e[j]);
;           S[t][kt][j] = pv;
;           ls += pv;
;         }
;       }
;     }
;     st.l = st.l * corr + ls;
;     if (MODE != M_CMPA) {
; #pragma unroll
;       for (int nt = 0; nt < 4; ++nt) O[nt] *= corr;
;     }
;   }
;     ...
;   for (int t = 0; t < 2; ++t) {
;     if (!(TM & (1 << t))) continue;
;     const h16* Vt = t ? Vt1 : Vt0;
; #pragma unroll
;     for (int ks = 0; ks < 2; ++ks) {
;       h16x8 Pf;
; #pragma unroll
;       for (int i = 0; i < 4; ++i) { Pf[i] = (h16)S[t][2 * ks][i]; Pf[4 + i] = (h16)S[t][2 * ks + 1][i]; }
; #pragma unroll
;       for (int nt = 0; nt < 4; ++nt) {
;         const h16* vp = Vt + (ks * 32 + q4 * 4 + (col >> 2)) * KP + nt * 16 + 4 * (col & 3);
;         const s16x4v r0 = __builtin_amdgcn_ds_read_tr16_b64_v4i16((LAS s16x4v*)vp);
;         const s16x4v r1 = __builtin_amdgcn_ds_read_tr16_b64_v4i16((LAS s16x4v*)(vp + 16 * KP));
;         const h16x4 v0 = __builtin_bit_cast(h16x4, r0), v1 = __builtin_bit_cast(h16x4, r1);
;         const h16x8 Vf = {v0[0], v0[1], v0[2], v0[3], v1[0], v1[1], v1[2], v1[3]};
;         O[nt] = __builtin_amdgcn_mfma_f32_16x16x32_f16(Vf, Pf, O[nt], 0, 0, 0);
;       }
;     }
;   }
;   __builtin_amdgcn_s_setprio(0);
.LBB0_1702:
	v_max3_f32 v3, v40, s67, v41
	v_max3_f32 v3, v3, v42, v43
	v_max3_f32 v3, v3, v36, v37
	v_max3_f32 v3, v3, v38, v39
	v_max3_f32 v3, v3, v32, v33
	v_max3_f32 v3, v3, v34, v35
	v_max3_f32 v3, v3, v28, v29
	v_max3_f32 v3, v3, v30, v31
	s_waitcnt lgkmcnt(0)
	v_fma_f32 v3, s0, v3, v2
	v_max_f32_e32 v3, 0xf149f2ca, v3
	v_mov_b32_e32 v96, v3
	s_nop 1
	v_permlane16_swap_b32_e32 v96, v3
	s_waitcnt lgkmcnt(0)
	v_max_f32_e32 v96, v96, v96
	v_max_f32_e32 v3, v3, v96
	v_mov_b32_e32 v96, v3
	s_nop 1
	v_permlane32_swap_b32_e32 v3, v96
	v_max3_f32 v173, v244, v3, v96
	v_max_f32_e32 v96, 0xe0ad78ec, v173
	v_sub_f32_e32 v2, v2, v96
	v_fma_f32 v40, s0, v40, v2
	v_fma_f32 v41, s0, v41, v2
	v_exp_f32_e32 v96, v40
	v_fma_f32 v42, s0, v42, v2
	v_exp_f32_e32 v100, v41
	v_fma_f32 v40, s0, v43, v2
	v_exp_f32_e32 v97, v42
	v_exp_f32_e32 v101, v40
	v_fma_f32 v36, s0, v36, v2
	v_add_f32_e32 v41, 0, v96
	v_exp_f32_e32 v98, v36
	v_fma_f32 v37, s0, v37, v2
	v_add_f32_e32 v36, v100, v41
	v_exp_f32_e32 v102, v37
	v_fma_f32 v37, s0, v38, v2
	v_add_f32_e32 v36, v97, v36
	v_exp_f32_e32 v99, v37
	v_fma_f32 v37, s0, v39, v2
	v_add_f32_e32 v36, v101, v36
	v_exp_f32_e32 v103, v37
	v_fma_f32 v32, s0, v32, v2
	v_add_f32_e32 v36, v98, v36
	v_exp_f32_e32 v108, v32
	v_fma_f32 v33, s0, v33, v2
	v_add_f32_e32 v32, v102, v36
	v_exp_f32_e32 v109, v33
	v_fma_f32 v33, s0, v34, v2
	v_add_f32_e32 v32, v99, v32
	v_exp_f32_e32 v110, v33
	v_fma_f32 v33, s0, v35, v2
	v_add_f32_e32 v32, v103, v32
	v_exp_f32_e32 v111, v33
	v_fma_f32 v28, s0, v28, v2
	v_add_f32_e32 v32, v108, v32
	v_exp_f32_e32 v112, v28
	v_fma_f32 v29, s0, v29, v2
	v_add_f32_e32 v28, v109, v32
	v_exp_f32_e32 v113, v29
	v_fma_f32 v29, s0, v30, v2
	v_add_f32_e32 v28, v110, v28
	v_exp_f32_e32 v114, v29
	v_fmac_f32_e32 v2, s0, v31
	v_sub_f32_e32 v3, v244, v173
	v_add_f32_e32 v28, v111, v28
	v_exp_f32_e32 v115, v2
	v_add_f32_e32 v28, v112, v28
	v_exp_f32_e32 v2, v3
	v_add_f32_e32 v3, v113, v28
	v_add_f32_e32 v3, v114, v3
	v_add_f32_e32 v243, v115, v3
	v_fmac_f32_e32 v243, v188, v2
	v_pk_mul_f32 v[30:31], v[82:83], v[2:3] op_sel_hi:[1,0]
	v_pk_mul_f32 v[28:29], v[80:81], v[2:3] op_sel_hi:[1,0]
	v_pk_mul_f32 v[34:35], v[86:87], v[2:3] op_sel_hi:[1,0]
	v_pk_mul_f32 v[32:33], v[84:85], v[2:3] op_sel_hi:[1,0]
	v_pk_mul_f32 v[38:39], v[90:91], v[2:3] op_sel_hi:[1,0]
	v_pk_mul_f32 v[36:37], v[88:89], v[2:3] op_sel_hi:[1,0]
	v_pk_mul_f32 v[42:43], v[94:95], v[2:3] op_sel_hi:[1,0]
	v_pk_mul_f32 v[40:41], v[92:93], v[2:3] op_sel_hi:[1,0]
	s_nop 0
	v_cvt_pk_f16_f32 v99, v99, v103
	v_cvt_pk_f16_f32 v98, v98, v102
	v_cvt_pk_f16_f32 v97, v97, v101
	v_cvt_pk_f16_f32 v96, v96, v100
	ds_read_b64_tr_b16 v[102:103], v206 offset:2560
	ds_read_b64_tr_b16 v[106:107], v206 offset:2592
	ds_read_b64_tr_b16 v[100:101], v205 offset:64000
	ds_read_b64_tr_b16 v[104:105], v205 offset:64032
	s_waitcnt lgkmcnt(1)
	v_mfma_f32_16x16x32_f16 v[28:31], v[100:103], v[96:99], v[28:31]
	ds_read_b64_tr_b16 v[100:101], v205 offset:64064
	ds_read_b64_tr_b16 v[102:103], v206 offset:2624
	s_mov_b64 s[48:49], -1
	s_waitcnt lgkmcnt(0)
	v_mfma_f32_16x16x32_f16 v[36:39], v[100:103], v[96:99], v[36:39]
	ds_read_b64_tr_b16 v[100:101], v205 offset:64096
	ds_read_b64_tr_b16 v[102:103], v206 offset:2656
	s_waitcnt lgkmcnt(0)
	v_mfma_f32_16x16x32_f16 v[40:43], v[100:103], v[96:99], v[40:43]
	ds_read_b64_tr_b16 v[100:101], v206 offset:5120
	ds_read_b64_tr_b16 v[102:103], v206 offset:7680
	v_mfma_f32_16x16x32_f16 v[32:35], v[104:107], v[96:99], v[32:35]
	v_cvt_pk_f16_f32 v99, v114, v115
	v_cvt_pk_f16_f32 v98, v112, v113
	v_cvt_pk_f16_f32 v97, v110, v111
	v_cvt_pk_f16_f32 v96, v108, v109
	s_waitcnt lgkmcnt(0)
	s_nop 0
	v_mfma_f32_16x16x32_f16 v[28:31], v[100:103], v[96:99], v[28:31]
	ds_read_b64_tr_b16 v[100:101], v206 offset:5152
	ds_read_b64_tr_b16 v[102:103], v206 offset:7712
	s_waitcnt lgkmcnt(0)
	v_mfma_f32_16x16x32_f16 v[32:35], v[100:103], v[96:99], v[32:35]
	ds_read_b64_tr_b16 v[100:101], v206 offset:5184
	ds_read_b64_tr_b16 v[102:103], v206 offset:7744
	s_waitcnt lgkmcnt(0)
	v_mfma_f32_16x16x32_f16 v[36:39], v[100:103], v[96:99], v[36:39]
	ds_read_b64_tr_b16 v[100:101], v206 offset:5216
	ds_read_b64_tr_b16 v[102:103], v206 offset:7776
	s_waitcnt lgkmcnt(0)
	v_mfma_f32_16x16x32_f16 v[40:43], v[100:103], v[96:99], v[40:43]
	s_branch .LBB0_1783

; #define LAS __attribute__((address_space(3)))
; template <int MODE, int TM> ...
;     ...
;     float mx = -1e30f;
; #pragma unroll
;     for (int t = 0; t < 2; ++t) {
;       if (!(TM & (1 << t))) continue;
;       float mt = -1e30f;
; #pragma unroll
;       for (int kt = 0; kt < 4; ++kt)
; #pragma unroll
;         for (int j = 0; j < 4; ++j) mt = fmaxf(mt, S[t][kt][j]);
;       mx = fmaxf(mx, mt * sclc[t] + addc[t]);
;     }
;     mx = max4q(mx);
;     const float mn = fmaxf(st.m, mx);
;     const float corr = __builtin_amdgcn_exp2f(st.m - mn);
;     st.m = mn;
;     const float mm = fmaxf(mn, -1e20f);
;     float ls = 0.f;
; #pragma unroll
;     for (int t = 0; t < 2; ++t) {
;       if (!(TM & (1 << t))) continue;
;       const float am = addc[t] - mm;
; #pragma unroll
;       for (int kt = 0; kt < 4; ++kt) {
;         const f32x4 e = S[t][kt] * sclc[t] + am;
; #pragma unroll
;         for (int j = 0; j < 4; ++j) {
;           float pv = __builtin_amdgcn_exp2f(e[j]);
;           S[t][kt][j] = pv;
;           ls += pv;
;         }
;       }
;     }
;     st.l = st.l * corr + ls;
;     if (MODE != M_CMPA) {
; #pragma unroll
;       for (int nt = 0; nt < 4; ++nt) O[nt] *= corr;
;     }
;   }
;     ...
;   for (int t = 0; t < 2; ++t) {
;     if (!(TM & (1 << t))) continue;
;     const h16* Vt = t ? Vt1 : Vt0;
; #pragma unroll
;     for (int ks = 0; ks < 2; ++ks) {
;       h16x8 Pf;
; #pragma unroll
;       for (int i = 0; i < 4; ++i) { Pf[i] = (h16)S[t][2 * ks][i]; Pf[4 + i] = (h16)S[t][2 * ks + 1][i]; }
; #pragma unroll
;       for (int nt = 0; nt < 4; ++nt) {
;         const h16* vp = Vt + (ks * 32 + q4 * 4 + (col >> 2)) * KP + nt * 16 + 4 * (col & 3);
;         const s16x4v r0 = __builtin_amdgcn_ds_read_tr16_b64_v4i16((LAS s16x4v*)vp);
;         const s16x4v r1 = __builtin_amdgcn_ds_read_tr16_b64_v4i16((LAS s16x4v*)(vp + 16 * KP));
;         const h16x4 v0 = __builtin_bit_cast(h16x4, r0), v1 = __builtin_bit_cast(h16x4, r1);
;         const h16x8 Vf = {v0[0], v0[1], v0[2], v0[3], v1[0], v1[1], v1[2], v1[3]};
;         O[nt] = __builtin_amdgcn_mfma_f32_16x16x32_f16(Vf, Pf, O[nt], 0, 0, 0);
;       }
;     }
;   }
;   __builtin_amdgcn_s_setprio(0);
.LBB0_1704:
	v_max3_f32 v3, v32, s67, v33
	v_max3_f32 v3, v3, v34, v35
	v_max3_f32 v3, v3, v28, v29
	v_max3_f32 v3, v3, v30, v31
	v_max3_f32 v3, v3, v40, v41
	v_max3_f32 v3, v3, v42, v43
	v_max3_f32 v3, v3, v36, v37
	v_max3_f32 v3, v3, v38, v39
	s_waitcnt lgkmcnt(0)
	v_fma_f32 v3, s3, v3, v2
	v_max_f32_e32 v3, 0xf149f2ca, v3
	v_mov_b32_e32 v96, v3
	s_nop 1
	v_permlane16_swap_b32_e32 v96, v3
	s_waitcnt lgkmcnt(0)
	v_max_f32_e32 v96, v96, v96
	v_max_f32_e32 v3, v3, v96
	v_mov_b32_e32 v96, v3
	s_nop 1
	v_permlane32_swap_b32_e32 v3, v96
	v_max3_f32 v173, v244, v3, v96
	v_max_f32_e32 v96, 0xe0ad78ec, v173
	v_sub_f32_e32 v2, v2, v96
	v_fma_f32 v28, s3, v28, v2
	v_exp_f32_e32 v98, v28
	v_fma_f32 v28, s3, v29, v2
	v_exp_f32_e32 v102, v28
	v_fma_f32 v28, s3, v30, v2
	v_exp_f32_e32 v99, v28
	v_fma_f32 v28, s3, v31, v2
	v_exp_f32_e32 v103, v28
	v_fma_f32 v28, s3, v40, v2
	v_exp_f32_e32 v108, v28
	v_fma_f32 v28, s3, v41, v2
	v_fma_f32 v32, s3, v32, v2
	v_exp_f32_e32 v109, v28
	v_fma_f32 v28, s3, v42, v2
	v_fma_f32 v33, s3, v33, v2
	v_exp_f32_e32 v96, v32
	v_exp_f32_e32 v110, v28
	v_fma_f32 v28, s3, v43, v2
	v_exp_f32_e32 v100, v33
	v_fma_f32 v32, s3, v34, v2
	v_exp_f32_e32 v111, v28
	v_fma_f32 v28, s3, v36, v2
	v_exp_f32_e32 v97, v32
	v_fma_f32 v32, s3, v35, v2
	v_exp_f32_e32 v112, v28
	v_fma_f32 v28, s3, v37, v2
	v_exp_f32_e32 v101, v32
	v_exp_f32_e32 v113, v28
	v_fma_f32 v28, s3, v38, v2
	v_fmac_f32_e32 v2, s3, v39
	v_exp_f32_e32 v115, v2
	v_add_f32_e32 v2, 0, v96
	v_add_f32_e32 v2, v100, v2
	v_add_f32_e32 v2, v97, v2
	v_add_f32_e32 v2, v101, v2
	v_add_f32_e32 v2, v98, v2
	v_add_f32_e32 v2, v102, v2
	v_add_f32_e32 v2, v99, v2
	v_add_f32_e32 v2, v103, v2
	v_add_f32_e32 v2, v108, v2
	v_add_f32_e32 v2, v109, v2
	v_exp_f32_e32 v114, v28
	v_add_f32_e32 v2, v110, v2
	v_sub_f32_e32 v3, v244, v173
	v_add_f32_e32 v2, v111, v2
	v_add_f32_e32 v28, v112, v2
	v_exp_f32_e32 v2, v3
	v_add_f32_e32 v3, v113, v28
	v_add_f32_e32 v3, v114, v3
	v_add_f32_e32 v243, v115, v3
	v_fmac_f32_e32 v243, v188, v2
	v_pk_mul_f32 v[30:31], v[82:83], v[2:3] op_sel_hi:[1,0]
	v_pk_mul_f32 v[28:29], v[80:81], v[2:3] op_sel_hi:[1,0]
	v_pk_mul_f32 v[34:35], v[86:87], v[2:3] op_sel_hi:[1,0]
	v_pk_mul_f32 v[32:33], v[84:85], v[2:3] op_sel_hi:[1,0]
	v_pk_mul_f32 v[38:39], v[90:91], v[2:3] op_sel_hi:[1,0]
	v_pk_mul_f32 v[36:37], v[88:89], v[2:3] op_sel_hi:[1,0]
	v_pk_mul_f32 v[42:43], v[94:95], v[2:3] op_sel_hi:[1,0]
	v_pk_mul_f32 v[40:41], v[92:93], v[2:3] op_sel_hi:[1,0]
	s_nop 0
	v_cvt_pk_f16_f32 v99, v99, v103
	v_cvt_pk_f16_f32 v98, v98, v102
	v_cvt_pk_f16_f32 v97, v97, v101
	v_cvt_pk_f16_f32 v96, v96, v100
	ds_read_b64_tr_b16 v[102:103], v208 offset:2560
	ds_read_b64_tr_b16 v[100:101], v208
	ds_read_b64_tr_b16 v[104:105], v208 offset:32
	s_waitcnt lgkmcnt(1)
	v_mfma_f32_16x16x32_f16 v[28:31], v[100:103], v[96:99], v[28:31]
	ds_read_b64_tr_b16 v[106:107], v208 offset:2592
	ds_read_b64_tr_b16 v[100:101], v208 offset:64
	ds_read_b64_tr_b16 v[102:103], v208 offset:2624
	s_mov_b64 s[48:49], -1
	s_waitcnt lgkmcnt(0)
	v_mfma_f32_16x16x32_f16 v[36:39], v[100:103], v[96:99], v[36:39]
	ds_read_b64_tr_b16 v[100:101], v208 offset:96
	ds_read_b64_tr_b16 v[102:103], v208 offset:2656
	s_waitcnt lgkmcnt(0)
	v_mfma_f32_16x16x32_f16 v[40:43], v[100:103], v[96:99], v[40:43]
	ds_read_b64_tr_b16 v[100:101], v208 offset:5120
	ds_read_b64_tr_b16 v[102:103], v208 offset:7680
	v_mfma_f32_16x16x32_f16 v[32:35], v[104:107], v[96:99], v[32:35]
	v_cvt_pk_f16_f32 v99, v114, v115
	v_cvt_pk_f16_f32 v98, v112, v113
	v_cvt_pk_f16_f32 v97, v110, v111
	v_cvt_pk_f16_f32 v96, v108, v109
	s_waitcnt lgkmcnt(0)
	s_nop 0
	v_mfma_f32_16x16x32_f16 v[28:31], v[100:103], v[96:99], v[28:31]
	ds_read_b64_tr_b16 v[100:101], v208 offset:5152
	ds_read_b64_tr_b16 v[102:103], v208 offset:7712
	s_waitcnt lgkmcnt(0)
	v_mfma_f32_16x16x32_f16 v[32:35], v[100:103], v[96:99], v[32:35]
	ds_read_b64_tr_b16 v[100:101], v208 offset:5184
	ds_read_b64_tr_b16 v[102:103], v208 offset:7744
	s_waitcnt lgkmcnt(0)
	v_mfma_f32_16x16x32_f16 v[36:39], v[100:103], v[96:99], v[36:39]
	ds_read_b64_tr_b16 v[100:101], v208 offset:5216
	ds_read_b64_tr_b16 v[102:103], v208 offset:7776
	s_waitcnt lgkmcnt(0)
	v_mfma_f32_16x16x32_f16 v[40:43], v[100:103], v[96:99], v[40:43]
	s_and_b64 vcc, exec, s[0:1]
	s_cbranch_vccnz .LBB0_1663

; template <int MODE, int TM> ...
;     ...
;   __builtin_amdgcn_s_setprio(1);
; #pragma unroll
;   for (int t = 0; t < 2; ++t) {
;     if (!(TM & (1 << t))) continue;
;     const h16* Ks = t ? Ks1 : Ks0;
; #pragma unroll
;     for (int kt = 0; kt < 4; ++kt) {
;       S[t][kt] = f32x4{0.f, 0.f, 0.f, 0.f};
; #pragma unroll
;       for (int ks = 0; ks < 2; ++ks) {
;         h16x8 Kf = *(const h16x8*)(Ks + (kt * 16 + col) * KP + ks * 32 + q4 * 8);
;         S[t][kt] = __builtin_amdgcn_mfma_f32_16x16x32_f16(Kf, Q[ks], S[t][kt], 0, 0, 0);
;       }
;     }
;   }
;   __builtin_amdgcn_s_setprio(0);
;   const float* bt = biasT + hd * 800;
;   float addc[2] = {0.f, 0.f}, sclc[2] = {1.f, 1.f};
; #pragma unroll
;   for (int t = 0; t < 2; ++t) {
;     if (!(TM & (1 << t))) continue;
;     const int kbase = kbase0 + 64 * t;
;     if (far[t]) {
;       const bool ok = (MODE == M_SEL) ? selbit[t] : true;
;       addc[t] = ok ? bt[799] : -1e30f;
;       sclc[t] = SCL2;
;     } else {
;       addc[t] = 0.f;
;       sclc[t] = 1.f;
;       const int kx0 = kbase + q4 * 4;
;       const int d0 = (DK == 16) ? tq - 31 - 16 * kx0 : tq - kx0;
; #pragma unroll
;       for (int kt = 0; kt < 4; ++kt)
; #pragma unroll
;         for (int j = 0; j < 4; ++j) {
;           const int dist = d0 - DK * (kt * 16 + j);
;           const int kx = kx0 + kt * 16 + j;
;           bool valid = dist >= 0;
;           if (MODE == M_WIN) valid = valid && dist < 512 && kx >= 0;
;           if (MODE == M_SEL) valid = valid && selbit[t];
;           if (DK == 16) valid = valid && kx < NCMP;
;           const int dc = dist < 0 ? 0 : (dist > 799 ? 799 : dist);
;           S[t][kt][j] = valid ? S[t][kt][j] * SCL2 + bt[dc] : -1e30f;
.LBB0_1706:
	s_nop 0
	ds_read_b128 v[28:31], v155 offset:53760
	ds_read_b128 v[32:35], v155 offset:53824
	ds_read_b128 v[36:39], v155 offset:56320
	ds_read_b128 v[96:99], v155 offset:56384
	ds_read_b128 v[100:103], v202
	ds_read_b128 v[104:107], v202 offset:2560
	s_waitcnt lgkmcnt(5)
	v_mfma_f32_16x16x32_f16 v[28:31], v[28:31], v[4:7], 0
	ds_read_b128 v[108:111], v202 offset:5120
	ds_read_b128 v[112:115], v202 offset:7680
	s_waitcnt lgkmcnt(6)
	v_mfma_f32_16x16x32_f16 v[40:43], v[32:35], v[8:11], v[28:31]
	ds_read_b128 v[32:35], v155 offset:58944
	s_nop 2
	ds_read_b128 v[28:31], v155 offset:58880
	s_waitcnt lgkmcnt(7)
	v_mfma_f32_16x16x32_f16 v[36:39], v[36:39], v[4:7], 0
	s_waitcnt lgkmcnt(6)
	v_mfma_f32_16x16x32_f16 v[36:39], v[96:99], v[8:11], v[36:39]
	ds_read_b128 v[96:99], v155 offset:61440
	s_waitcnt lgkmcnt(1)
	v_mfma_f32_16x16x32_f16 v[28:31], v[28:31], v[4:7], 0
	v_mfma_f32_16x16x32_f16 v[32:35], v[32:35], v[8:11], v[28:31]
	s_nop 6
	ds_read_b128 v[28:31], v155 offset:61504
	s_waitcnt lgkmcnt(1)
	v_mfma_f32_16x16x32_f16 v[96:99], v[96:99], v[4:7], 0
	s_waitcnt lgkmcnt(0)
	v_mfma_f32_16x16x32_f16 v[28:31], v[28:31], v[8:11], v[96:99]
	s_nop 5
	ds_read_b128 v[96:99], v202 offset:64
	v_mfma_f32_16x16x32_f16 v[100:103], v[100:103], v[4:7], 0
	s_waitcnt lgkmcnt(0)
	v_mfma_f32_16x16x32_f16 v[96:99], v[96:99], v[8:11], v[100:103]
	s_nop 5
	ds_read_b128 v[100:103], v202 offset:2624
	v_mfma_f32_16x16x32_f16 v[104:107], v[104:107], v[4:7], 0
	s_waitcnt lgkmcnt(0)
	v_mfma_f32_16x16x32_f16 v[100:103], v[100:103], v[8:11], v[104:107]
	s_nop 5
	ds_read_b128 v[104:107], v202 offset:5184
	v_mfma_f32_16x16x32_f16 v[108:111], v[108:111], v[4:7], 0
	s_waitcnt lgkmcnt(0)
	v_mfma_f32_16x16x32_f16 v[104:107], v[104:107], v[8:11], v[108:111]
	s_nop 5
	ds_read_b128 v[108:111], v202 offset:7744
	v_mfma_f32_16x16x32_f16 v[112:115], v[112:115], v[4:7], 0
	s_waitcnt lgkmcnt(0)
	v_mfma_f32_16x16x32_f16 v[108:111], v[108:111], v[8:11], v[112:115]
	s_nop 0
	v_or_b32_e32 v173, s2, v154
	s_andn2_b64 vcc, exec, s[46:47]
	s_mov_b64 s[0:1], -1
	s_cbranch_vccnz .LBB0_1740
	v_sub_u32_e32 v2, v182, v173
	v_cmp_lt_i32_e64 s[0:1], -1, v2
	v_cmp_eq_u32_e32 vcc, 1, v0
	s_and_b64 s[2:3], s[0:1], vcc
	v_mov_b32_e32 v113, 0xf149f2ca
	v_mov_b32_e32 v112, 0xf149f2ca
	s_and_saveexec_b64 s[0:1], s[2:3]
	s_cbranch_execz .LBB0_1709
	v_min_u32_e32 v2, 0x31f, v2
	v_lshl_add_u32 v2, v2, 2, v157
	ds_read_b32 v112, v2

; #define LAS __attribute__((address_space(3)))
; template <int MODE, int TM> ...
;     ...
;     float mx = -1e30f;
; #pragma unroll
;     for (int t = 0; t < 2; ++t) {
;       if (!(TM & (1 << t))) continue;
;       float mt = -1e30f;
; #pragma unroll
;       for (int kt = 0; kt < 4; ++kt)
; #pragma unroll
;         for (int j = 0; j < 4; ++j) mt = fmaxf(mt, S[t][kt][j]);
;       mx = fmaxf(mx, mt * sclc[t] + addc[t]);
;     }
;     mx = max4q(mx);
;     const float mn = fmaxf(st.m, mx);
;     const float corr = __builtin_amdgcn_exp2f(st.m - mn);
;     st.m = mn;
;     const float mm = fmaxf(mn, -1e20f);
;     float ls = 0.f;
; #pragma unroll
;     for (int t = 0; t < 2; ++t) {
;       if (!(TM & (1 << t))) continue;
;       const float am = addc[t] - mm;
; #pragma unroll
;       for (int kt = 0; kt < 4; ++kt) {
;         const f32x4 e = S[t][kt] * sclc[t] + am;
; #pragma unroll
;         for (int j = 0; j < 4; ++j) {
;           float pv = __builtin_amdgcn_exp2f(e[j]);
;           S[t][kt][j] = pv;
;           ls += pv;
;         }
;       }
;     }
;     st.l = st.l * corr + ls;
;     if (MODE != M_CMPA) {
; #pragma unroll
;       for (int nt = 0; nt < 4; ++nt) O[nt] *= corr;
;     }
;   }
;     ...
;   for (int t = 0; t < 2; ++t) {
;     if (!(TM & (1 << t))) continue;
;     const h16* Vt = t ? Vt1 : Vt0;
; #pragma unroll
;     for (int ks = 0; ks < 2; ++ks) {
;       h16x8 Pf;
; #pragma unroll
;       for (int i = 0; i < 4; ++i) { Pf[i] = (h16)S[t][2 * ks][i]; Pf[4 + i] = (h16)S[t][2 * ks + 1][i]; }
; #pragma unroll
;       for (int nt = 0; nt < 4; ++nt) {
;         const h16* vp = Vt + (ks * 32 + q4 * 4 + (col >> 2)) * KP + nt * 16 + 4 * (col & 3);
;         const s16x4v r0 = __builtin_amdgcn_ds_read_tr16_b64_v4i16((LAS s16x4v*)vp);
;         const s16x4v r1 = __builtin_amdgcn_ds_read_tr16_b64_v4i16((LAS s16x4v*)(vp + 16 * KP));
;         const h16x4 v0 = __builtin_bit_cast(h16x4, r0), v1 = __builtin_bit_cast(h16x4, r1);
;         const h16x8 Vf = {v0[0], v0[1], v0[2], v0[3], v1[0], v1[1], v1[2], v1[3]};
;         O[nt] = __builtin_amdgcn_mfma_f32_16x16x32_f16(Vf, Pf, O[nt], 0, 0, 0);
;       }
;     }
;   }
;   __builtin_amdgcn_s_setprio(0);
.LBB0_1782:
	s_waitcnt lgkmcnt(0)
	v_max3_f32 v0, v40, s67, v41
	v_max3_f32 v96, v112, s67, v113
	v_max3_f32 v0, v0, v42, v43
	v_max3_f32 v96, v96, v114, v115
	v_max3_f32 v0, v0, v36, v37
	v_max3_f32 v96, v96, v116, v117
	v_max3_f32 v0, v0, v38, v39
	v_max3_f32 v96, v96, v118, v119
	v_max3_f32 v0, v0, v32, v33
	v_max3_f32 v96, v96, v120, v121
	v_max3_f32 v0, v0, v34, v35
	v_max3_f32 v96, v96, v122, v123
	v_max3_f32 v0, v0, v28, v29
	v_max3_f32 v96, v96, v124, v125
	v_max3_f32 v0, v0, v30, v31
	v_max3_f32 v96, v96, v126, v127
	v_fma_f32 v0, s2, v0, v2
	v_fma_f32 v96, s3, v96, v3
	v_max3_f32 v0, v0, s67, v96
	v_mov_b32_e32 v96, v0
	s_nop 1
	v_permlane16_swap_b32_e32 v96, v0
	s_waitcnt lgkmcnt(0)
	v_max_f32_e32 v96, v96, v96
	v_max_f32_e32 v0, v0, v96
	v_mov_b32_e32 v96, v0
	s_nop 1
	v_permlane32_swap_b32_e32 v0, v96
	v_max3_f32 v173, v244, v0, v96
	v_max_f32_e32 v0, 0xe0ad78ec, v173
	v_sub_f32_e32 v2, v2, v0
	v_fma_f32 v40, s2, v40, v2
	v_exp_f32_e32 v96, v40
	v_fma_f32 v41, s2, v41, v2
	v_exp_f32_e32 v98, v41
	v_fma_f32 v41, s2, v42, v2
	v_exp_f32_e32 v99, v41
	v_fma_f32 v41, s2, v43, v2
	v_exp_f32_e32 v100, v41
	v_fma_f32 v36, s2, v36, v2
	v_add_f32_e32 v97, 0, v96
	v_exp_f32_e32 v101, v36
	v_fma_f32 v37, s2, v37, v2
	v_add_f32_e32 v36, v98, v97
	v_exp_f32_e32 v97, v37
	v_fma_f32 v37, s2, v38, v2
	v_add_f32_e32 v36, v99, v36
	v_exp_f32_e32 v102, v37
	v_fma_f32 v37, s2, v39, v2
	v_add_f32_e32 v36, v100, v36
	v_exp_f32_e32 v103, v37
	v_fma_f32 v32, s2, v32, v2
	v_add_f32_e32 v36, v101, v36
	v_exp_f32_e32 v104, v32
	v_fma_f32 v33, s2, v33, v2
	v_add_f32_e32 v32, v97, v36
	v_exp_f32_e32 v105, v33
	v_fma_f32 v33, s2, v34, v2
	v_add_f32_e32 v32, v102, v32
	v_exp_f32_e32 v106, v33
	v_fma_f32 v33, s2, v35, v2
	v_add_f32_e32 v32, v103, v32
	v_exp_f32_e32 v107, v33
	v_fma_f32 v28, s2, v28, v2
	v_add_f32_e32 v32, v104, v32
	v_exp_f32_e32 v108, v28
	v_fma_f32 v29, s2, v29, v2
	v_add_f32_e32 v28, v105, v32
	v_exp_f32_e32 v109, v29
	v_fma_f32 v29, s2, v30, v2
	v_add_f32_e32 v28, v106, v28
	v_exp_f32_e32 v110, v29
	v_fmac_f32_e32 v2, s2, v31
	v_sub_f32_e32 v0, v3, v0
	v_add_f32_e32 v28, v107, v28
	v_exp_f32_e32 v2, v2
	v_fma_f32 v3, s3, v112, v0
	v_add_f32_e32 v28, v108, v28
	v_exp_f32_e32 v3, v3
	v_fma_f32 v29, s3, v113, v0
	v_add_f32_e32 v28, v109, v28
	v_exp_f32_e32 v111, v29
	v_fma_f32 v29, s3, v114, v0
	v_add_f32_e32 v28, v110, v28
	v_exp_f32_e32 v112, v29
	v_fma_f32 v29, s3, v115, v0
	v_add_f32_e32 v28, v2, v28
	v_exp_f32_e32 v113, v29
	v_fma_f32 v29, s3, v116, v0
	v_add_f32_e32 v28, v3, v28
	v_exp_f32_e32 v114, v29
	v_fma_f32 v29, s3, v117, v0
	v_add_f32_e32 v28, v111, v28
	v_exp_f32_e32 v115, v29
	v_fma_f32 v29, s3, v118, v0
	v_add_f32_e32 v28, v112, v28
	v_exp_f32_e32 v116, v29
	v_fma_f32 v29, s3, v119, v0
	v_add_f32_e32 v28, v113, v28
	v_exp_f32_e32 v117, v29
	v_fma_f32 v29, s3, v120, v0
	v_add_f32_e32 v28, v114, v28
	v_exp_f32_e32 v118, v29
	v_fma_f32 v29, s3, v121, v0
	v_add_f32_e32 v28, v115, v28
	v_exp_f32_e32 v119, v29
	v_fma_f32 v29, s3, v122, v0
	v_add_f32_e32 v28, v116, v28
	v_exp_f32_e32 v120, v29
	v_fma_f32 v29, s3, v123, v0
	v_add_f32_e32 v28, v117, v28
	v_exp_f32_e32 v121, v29
	v_fma_f32 v29, s3, v124, v0
	v_add_f32_e32 v28, v118, v28
	v_exp_f32_e32 v122, v29
	v_fma_f32 v29, s3, v125, v0
	v_add_f32_e32 v28, v119, v28
	v_exp_f32_e32 v123, v29
	v_fma_f32 v29, s3, v126, v0
	v_add_f32_e32 v28, v120, v28
	v_exp_f32_e32 v124, v29
	v_fmac_f32_e32 v0, s3, v127
	v_sub_f32_e32 v40, v244, v173
	v_add_f32_e32 v28, v121, v28
	v_exp_f32_e32 v125, v0
	v_add_f32_e32 v28, v122, v28
	v_exp_f32_e32 v0, v40
	v_add_f32_e32 v28, v123, v28
	v_add_f32_e32 v28, v124, v28
	v_add_f32_e32 v243, v125, v28
	v_fmac_f32_e32 v243, v188, v0
	v_pk_mul_f32 v[30:31], v[82:83], v[0:1] op_sel_hi:[1,0]
	v_pk_mul_f32 v[28:29], v[80:81], v[0:1] op_sel_hi:[1,0]
	v_pk_mul_f32 v[34:35], v[86:87], v[0:1] op_sel_hi:[1,0]
	v_pk_mul_f32 v[32:33], v[84:85], v[0:1] op_sel_hi:[1,0]
	v_pk_mul_f32 v[38:39], v[90:91], v[0:1] op_sel_hi:[1,0]
	v_pk_mul_f32 v[36:37], v[88:89], v[0:1] op_sel_hi:[1,0]
	v_pk_mul_f32 v[42:43], v[94:95], v[0:1] op_sel_hi:[1,0]
	v_pk_mul_f32 v[40:41], v[92:93], v[0:1] op_sel_hi:[1,0]
	s_nop 0
	ds_read_b64_tr_b16 v[86:87], v206 offset:2560
	ds_read_b64_tr_b16 v[90:91], v206 offset:2592
	ds_read_b64_tr_b16 v[84:85], v205 offset:64000
	ds_read_b64_tr_b16 v[88:89], v205 offset:64032
	v_cvt_pk_f16_f32 v83, v102, v103
	v_cvt_pk_f16_f32 v82, v101, v97
	v_cvt_pk_f16_f32 v81, v99, v100
	v_cvt_pk_f16_f32 v80, v96, v98
	s_mov_b64 s[48:49], -1
	s_waitcnt lgkmcnt(1)
; #define LAS __attribute__((address_space(3)))
; template <int MODE, int TM> ...
;     ...
;   __builtin_amdgcn_s_setprio(1);
; #pragma unroll
;   for (int t = 0; t < 2; ++t) {
;     if (!(TM & (1 << t))) continue;
;     const h16* Vt = t ? Vt1 : Vt0;
; #pragma unroll
;     for (int ks = 0; ks < 2; ++ks) {
;       h16x8 Pf;
; #pragma unroll
;       for (int i = 0; i < 4; ++i) { Pf[i] = (h16)S[t][2 * ks][i]; Pf[4 + i] = (h16)S[t][2 * ks + 1][i]; }
; #pragma unroll
;       for (int nt = 0; nt < 4; ++nt) {
;         const h16* vp = Vt + (ks * 32 + q4 * 4 + (col >> 2)) * KP + nt * 16 + 4 * (col & 3);
;         const s16x4v r0 = __builtin_amdgcn_ds_read_tr16_b64_v4i16((LAS s16x4v*)vp);
;         const s16x4v r1 = __builtin_amdgcn_ds_read_tr16_b64_v4i16((LAS s16x4v*)(vp + 16 * KP));
;         const h16x4 v0 = __builtin_bit_cast(h16x4, r0), v1 = __builtin_bit_cast(h16x4, r1);
;         const h16x8 Vf = {v0[0], v0[1], v0[2], v0[3], v1[0], v1[1], v1[2], v1[3]};
;         O[nt] = __builtin_amdgcn_mfma_f32_16x16x32_f16(Vf, Pf, O[nt], 0, 0, 0);
;       }
;     }
;   }
;   __builtin_amdgcn_s_setprio(0);
	v_mfma_f32_16x16x32_f16 v[28:31], v[84:87], v[80:83], v[28:31]
	ds_read_b64_tr_b16 v[84:85], v205 offset:64064
	ds_read_b64_tr_b16 v[86:87], v206 offset:2624
	s_waitcnt lgkmcnt(0)
	v_mfma_f32_16x16x32_f16 v[36:39], v[84:87], v[80:83], v[36:39]
	ds_read_b64_tr_b16 v[84:85], v205 offset:64096
	ds_read_b64_tr_b16 v[86:87], v206 offset:2656
	v_mfma_f32_16x16x32_f16 v[32:35], v[88:91], v[80:83], v[32:35]
	s_waitcnt lgkmcnt(0)
	v_mfma_f32_16x16x32_f16 v[40:43], v[84:87], v[80:83], v[40:43]
	ds_read_b64_tr_b16 v[86:87], v207 offset:2560
	ds_read_b64_tr_b16 v[84:85], v207
	ds_read_b64_tr_b16 v[88:89], v207 offset:32
	v_cvt_pk_f16_f32 v83, v110, v2
	v_cvt_pk_f16_f32 v82, v108, v109
	v_cvt_pk_f16_f32 v81, v106, v107
	v_cvt_pk_f16_f32 v80, v104, v105
	ds_read_b64_tr_b16 v[90:91], v207 offset:2592
	s_waitcnt lgkmcnt(2)
	v_mfma_f32_16x16x32_f16 v[28:31], v[84:87], v[80:83], v[28:31]
	ds_read_b64_tr_b16 v[84:85], v207 offset:64
	ds_read_b64_tr_b16 v[86:87], v207 offset:2624
	s_waitcnt lgkmcnt(0)
	v_mfma_f32_16x16x32_f16 v[36:39], v[84:87], v[80:83], v[36:39]
	ds_read_b64_tr_b16 v[84:85], v207 offset:96
	ds_read_b64_tr_b16 v[86:87], v207 offset:2656
	v_mfma_f32_16x16x32_f16 v[32:35], v[88:91], v[80:83], v[32:35]
	s_waitcnt lgkmcnt(0)
	v_mfma_f32_16x16x32_f16 v[40:43], v[84:87], v[80:83], v[40:43]
	ds_read_b64_tr_b16 v[86:87], v208 offset:2560
	ds_read_b64_tr_b16 v[84:85], v208
	ds_read_b64_tr_b16 v[88:89], v208 offset:32
	v_cvt_pk_f16_f32 v83, v116, v117
	v_cvt_pk_f16_f32 v82, v114, v115
	v_cvt_pk_f16_f32 v81, v112, v113
	v_cvt_pk_f16_f32 v80, v3, v111
	ds_read_b64_tr_b16 v[90:91], v208 offset:2592
	s_waitcnt lgkmcnt(2)
	v_mfma_f32_16x16x32_f16 v[28:31], v[84:87], v[80:83], v[28:31]
	ds_read_b64_tr_b16 v[84:85], v208 offset:64
	ds_read_b64_tr_b16 v[86:87], v208 offset:2624
	s_waitcnt lgkmcnt(0)
	v_mfma_f32_16x16x32_f16 v[36:39], v[84:87], v[80:83], v[36:39]
	ds_read_b64_tr_b16 v[84:85], v208 offset:96
	ds_read_b64_tr_b16 v[86:87], v208 offset:2656
	s_waitcnt lgkmcnt(0)
	v_mfma_f32_16x16x32_f16 v[40:43], v[84:87], v[80:83], v[40:43]
	ds_read_b64_tr_b16 v[84:85], v208 offset:5120
	ds_read_b64_tr_b16 v[86:87], v208 offset:7680
	v_mfma_f32_16x16x32_f16 v[32:35], v[88:91], v[80:83], v[32:35]
	v_cvt_pk_f16_f32 v83, v124, v125
	v_cvt_pk_f16_f32 v82, v122, v123
	v_cvt_pk_f16_f32 v81, v120, v121
	v_cvt_pk_f16_f32 v80, v118, v119
	s_waitcnt lgkmcnt(0)
	s_nop 0
	v_mfma_f32_16x16x32_f16 v[28:31], v[84:87], v[80:83], v[28:31]
	ds_read_b64_tr_b16 v[84:85], v208 offset:5152
	ds_read_b64_tr_b16 v[86:87], v208 offset:7712
	s_waitcnt lgkmcnt(0)
	v_mfma_f32_16x16x32_f16 v[32:35], v[84:87], v[80:83], v[32:35]
	ds_read_b64_tr_b16 v[84:85], v208 offset:5184
	ds_read_b64_tr_b16 v[86:87], v208 offset:7744
	s_waitcnt lgkmcnt(0)
	v_mfma_f32_16x16x32_f16 v[36:39], v[84:87], v[80:83], v[36:39]
	ds_read_b64_tr_b16 v[84:85], v208 offset:5216
	ds_read_b64_tr_b16 v[86:87], v208 offset:7776
	s_waitcnt lgkmcnt(0)
	v_mfma_f32_16x16x32_f16 v[40:43], v[84:87], v[80:83], v[40:43]
.LBB0_1783:
	s_and_b64 vcc, exec, s[48:49]
	s_cbranch_vccz .LBB0_1426
	s_nop 0
	s_branch .LBB0_1426

; template <int MODE, int TM> ...
;     ...
;     float mx = -1e30f;
; #pragma unroll
;     for (int t = 0; t < 2; ++t) {
;       if (!(TM & (1 << t))) continue;
;       float mt = -1e30f;
; #pragma unroll
;       for (int kt = 0; kt < 4; ++kt)
; #pragma unroll
;         for (int j = 0; j < 4; ++j) mt = fmaxf(mt, S[t][kt][j]);
;       mx = fmaxf(mx, mt * sclc[t] + addc[t]);
;     }
;     mx = max4q(mx);
;     const float mn = fmaxf(st.m, mx);
;     const float corr = __builtin_amdgcn_exp2f(st.m - mn);
;     st.m = mn;
;     const float mm = fmaxf(mn, -1e20f);
;     float ls = 0.f;
; #pragma unroll
;     for (int t = 0; t < 2; ++t) {
;       if (!(TM & (1 << t))) continue;
;       const float am = addc[t] - mm;
; #pragma unroll
;       for (int kt = 0; kt < 4; ++kt) {
;         const f32x4 e = S[t][kt] * sclc[t] + am;
; #pragma unroll
;         for (int j = 0; j < 4; ++j) {
;           float pv = __builtin_amdgcn_exp2f(e[j]);
;           S[t][kt][j] = pv;
;           ls += pv;
;         }
;       }
;     }
;     st.l = st.l * corr + ls;
;     if (MODE != M_CMPA) {
; #pragma unroll
;       for (int nt = 0; nt < 4; ++nt) O[nt] *= corr;
;     }
;   }
;   if (MODE == M_CMPA) return;
;   __builtin_amdgcn_s_setprio(1);
; #pragma unroll
;   for (int t = 0; t < 2; ++t) {
;     if (!(TM & (1 << t))) continue;
;     const h16* Vt = t ? Vt1 : Vt0;
; #pragma unroll
;     for (int ks = 0; ks < 2; ++ks) {
;       h16x8 Pf;
; #pragma unroll
;       for (int i = 0; i < 4; ++i) { Pf[i] = (h16)S[t][2 * ks][i]; Pf[4 + i] = (h16)S[t][2 * ks + 1][i]; }
; #pragma unroll
;       for (int nt = 0; nt < 4; ++nt) {
;         const h16* vp = Vt + (ks * 32 + q4 * 4 + (col >> 2)) * KP + nt * 16 + 4 * (col & 3);
.LBB0_1819:
	s_or_b64 exec, exec, s[0:1]
	v_max3_f32 v0, v173, s67, v127
	v_max3_f32 v78, v111, s67, v110
	v_max3_f32 v0, v0, v121, v120
	v_max3_f32 v78, v78, v89, v88
	v_max3_f32 v0, v0, v123, v122
	v_max3_f32 v78, v78, v91, v90
	v_max3_f32 v0, v0, v117, v116
	v_max3_f32 v78, v78, v85, v84
	v_max3_f32 v0, v0, v119, v118
	v_max3_f32 v78, v78, v87, v86
	v_max3_f32 v0, v0, v113, v112
	v_max3_f32 v78, v78, v81, v80
	v_max3_f32 v0, v0, v115, v114
	v_max3_f32 v78, v78, v83, v82
	v_max3_f32 v0, v0, v109, v108
	v_max3_f32 v78, v78, v77, v76
	v_add_f32_e32 v0, 0, v0
	v_add_f32_e32 v78, 0, v78
	v_max3_f32 v0, v0, s67, v78
	v_mov_b32_e32 v78, v0
	s_nop 1
	v_permlane16_swap_b32_e32 v78, v0
	s_waitcnt lgkmcnt(0)
	v_max_f32_e32 v78, v78, v78
	v_max_f32_e32 v0, v0, v78
	v_mov_b32_e32 v78, v0
	s_nop 1
	v_permlane32_swap_b32_e32 v0, v78
	v_max3_f32 v126, v2, v0, v78
	v_max_f32_e32 v0, 0xe0ad78ec, v126
	v_add_f32_e64 v78, v173, -v0
	v_exp_f32_e32 v173, v78
	v_add_f32_e64 v79, v127, -v0
	v_exp_f32_e32 v188, v79
	v_add_f32_e64 v79, v121, -v0
	v_exp_f32_e32 v121, v79
	v_add_f32_e64 v79, v120, -v0
	v_exp_f32_e32 v120, v79
	v_add_f32_e64 v79, v123, -v0
	v_add_f32_e32 v78, 0, v173
	v_exp_f32_e32 v123, v79
	v_add_f32_e64 v79, v122, -v0
	v_add_f32_e32 v78, v188, v78
	v_exp_f32_e32 v122, v79
	v_add_f32_e64 v79, v117, -v0
	v_add_f32_e32 v78, v121, v78
	v_exp_f32_e32 v117, v79
	v_add_f32_e64 v79, v116, -v0
	v_add_f32_e32 v78, v120, v78
	v_exp_f32_e32 v116, v79
	v_add_f32_e64 v79, v119, -v0
	v_add_f32_e32 v78, v123, v78
	v_exp_f32_e32 v119, v79
	v_add_f32_e64 v79, v118, -v0
	v_add_f32_e32 v78, v122, v78
	v_exp_f32_e32 v118, v79
	v_add_f32_e64 v79, v113, -v0
	v_add_f32_e32 v78, v117, v78
	v_exp_f32_e32 v113, v79
	v_add_f32_e64 v79, v112, -v0
	v_add_f32_e32 v78, v116, v78
	v_exp_f32_e32 v112, v79
	v_add_f32_e64 v79, v115, -v0
	v_add_f32_e32 v78, v119, v78
	v_exp_f32_e32 v115, v79
	v_add_f32_e64 v79, v114, -v0
	v_add_f32_e32 v78, v118, v78
	v_exp_f32_e32 v114, v79
	v_add_f32_e64 v79, v109, -v0
	v_add_f32_e32 v78, v113, v78
	v_exp_f32_e32 v109, v79
	v_add_f32_e64 v79, v108, -v0
	v_add_f32_e32 v78, v112, v78
	v_exp_f32_e32 v108, v79
	v_add_f32_e64 v79, v111, -v0
	v_add_f32_e32 v78, v115, v78
	v_exp_f32_e32 v111, v79
	v_add_f32_e64 v79, v110, -v0
	v_add_f32_e32 v78, v114, v78
	v_exp_f32_e32 v110, v79
	v_add_f32_e64 v79, v89, -v0
	v_add_f32_e32 v78, v109, v78
	v_exp_f32_e32 v189, v79
	v_add_f32_e64 v79, v88, -v0
	v_add_f32_e32 v78, v108, v78
	v_exp_f32_e32 v243, v79
	v_add_f32_e64 v79, v91, -v0
	v_add_f32_e32 v78, v111, v78
	v_exp_f32_e32 v244, v79
	v_add_f32_e64 v79, v90, -v0
	v_add_f32_e32 v78, v110, v78
	v_exp_f32_e32 v245, v79
	v_add_f32_e64 v79, v85, -v0
	v_add_f32_e32 v78, v189, v78
	v_exp_f32_e32 v246, v79
	v_add_f32_e64 v79, v84, -v0
	v_add_f32_e32 v78, v243, v78
	v_exp_f32_e32 v247, v79
	v_add_f32_e64 v79, v87, -v0
	v_add_f32_e32 v78, v244, v78
	v_exp_f32_e32 v248, v79
	v_add_f32_e64 v79, v86, -v0
	v_add_f32_e32 v78, v245, v78
	v_exp_f32_e32 v249, v79
	v_add_f32_e64 v79, v81, -v0
	v_add_f32_e32 v78, v246, v78
	v_exp_f32_e32 v250, v79
	v_add_f32_e64 v79, v80, -v0
	v_add_f32_e32 v78, v247, v78
	v_exp_f32_e32 v251, v79
	v_add_f32_e64 v79, v83, -v0
	v_add_f32_e32 v78, v248, v78
	v_exp_f32_e32 v252, v79
	v_add_f32_e64 v79, v82, -v0
	v_add_f32_e32 v78, v249, v78
	v_exp_f32_e32 v253, v79
	v_add_f32_e64 v77, v77, -v0
	v_add_f32_e32 v78, v250, v78
	v_exp_f32_e32 v195, v77
	v_add_f32_e64 v0, v76, -v0
	v_sub_f32_e32 v2, v2, v126
	v_add_f32_e32 v78, v251, v78
	v_exp_f32_e32 v200, v0
	v_add_f32_e32 v78, v252, v78
	v_exp_f32_e32 v0, v2
	v_add_f32_e32 v2, v253, v78
	v_add_f32_e32 v2, v195, v2
	v_add_f32_e32 v127, v200, v2
	v_fmac_f32_e32 v127, v3, v0
	v_pk_mul_f32 v[78:79], v[94:95], v[0:1] op_sel_hi:[1,0]
	v_pk_mul_f32 v[76:77], v[92:93], v[0:1] op_sel_hi:[1,0]
	v_pk_mul_f32 v[82:83], v[98:99], v[0:1] op_sel_hi:[1,0]
	v_pk_mul_f32 v[80:81], v[96:97], v[0:1] op_sel_hi:[1,0]
	v_pk_mul_f32 v[86:87], v[102:103], v[0:1] op_sel_hi:[1,0]
	v_pk_mul_f32 v[84:85], v[100:101], v[0:1] op_sel_hi:[1,0]
	v_pk_mul_f32 v[90:91], v[106:107], v[0:1] op_sel_hi:[1,0]
	v_pk_mul_f32 v[88:89], v[104:105], v[0:1] op_sel_hi:[1,0]
	s_nop 0
	ds_read_b64_tr_b16 v[98:99], v206 offset:2560
	ds_read_b64_tr_b16 v[102:103], v206 offset:2592
	ds_read_b64_tr_b16 v[96:97], v205 offset:64000
	ds_read_b64_tr_b16 v[100:101], v205 offset:64032
	v_cvt_pk_f16_f32 v95, v117, v116
	v_cvt_pk_f16_f32 v94, v123, v122
	v_cvt_pk_f16_f32 v93, v121, v120
	v_cvt_pk_f16_f32 v92, v173, v188
	s_waitcnt lgkmcnt(1)
; #define LAS __attribute__((address_space(3)))
; template <int MODE, int TM> ...
;     ...
;   for (int t = 0; t < 2; ++t) {
;     if (!(TM & (1 << t))) continue;
;     const h16* Vt = t ? Vt1 : Vt0;
; #pragma unroll
;     for (int ks = 0; ks < 2; ++ks) {
;       h16x8 Pf;
; #pragma unroll
;       for (int i = 0; i < 4; ++i) { Pf[i] = (h16)S[t][2 * ks][i]; Pf[4 + i] = (h16)S[t][2 * ks + 1][i]; }
; #pragma unroll
;       for (int nt = 0; nt < 4; ++nt) {
;         const h16* vp = Vt + (ks * 32 + q4 * 4 + (col >> 2)) * KP + nt * 16 + 4 * (col & 3);
;         const s16x4v r0 = __builtin_amdgcn_ds_read_tr16_b64_v4i16((LAS s16x4v*)vp);
;         const s16x4v r1 = __builtin_amdgcn_ds_read_tr16_b64_v4i16((LAS s16x4v*)(vp + 16 * KP));
;         const h16x4 v0 = __builtin_bit_cast(h16x4, r0), v1 = __builtin_bit_cast(h16x4, r1);
;         const h16x8 Vf = {v0[0], v0[1], v0[2], v0[3], v1[0], v1[1], v1[2], v1[3]};
;         O[nt] = __builtin_amdgcn_mfma_f32_16x16x32_f16(Vf, Pf, O[nt], 0, 0, 0);
;       }
;     }
;   }
;   __builtin_amdgcn_s_setprio(0);
; template <int D, class LoadF, class StoreF, class CompF>
; __device__ __forceinline__ void pair_pipeline(int n, LoadF load, StoreF store, CompF comp) {
;     ...
;     for (int d = 0; d < D; ++d) {
;       const int i = i0 + d;
;       if (i < n) {
;         if (i + 1 < n) store(i + 1, r[(d + 1) % D]);
;         if (i + 1 + D < n) load(i + 1 + D, r[(d + 1) % D]);
;         comp(i);
;         __syncthreads();
;       }
	s_nop 0
	v_mfma_f32_16x16x32_f16 v[76:79], v[96:99], v[92:95], v[76:79]
	ds_read_b64_tr_b16 v[96:97], v205 offset:64064
	ds_read_b64_tr_b16 v[98:99], v206 offset:2624
	s_waitcnt lgkmcnt(0)
	v_mfma_f32_16x16x32_f16 v[84:87], v[96:99], v[92:95], v[84:87]
	ds_read_b64_tr_b16 v[96:97], v205 offset:64096
	ds_read_b64_tr_b16 v[98:99], v206 offset:2656
	v_mfma_f32_16x16x32_f16 v[80:83], v[100:103], v[92:95], v[80:83]
	s_waitcnt lgkmcnt(0)
	v_mfma_f32_16x16x32_f16 v[88:91], v[96:99], v[92:95], v[88:91]
	ds_read_b64_tr_b16 v[98:99], v207 offset:2560
	ds_read_b64_tr_b16 v[96:97], v207
	ds_read_b64_tr_b16 v[100:101], v207 offset:32
	v_cvt_pk_f16_f32 v95, v109, v108
	v_cvt_pk_f16_f32 v94, v115, v114
	v_cvt_pk_f16_f32 v93, v113, v112
	v_cvt_pk_f16_f32 v92, v119, v118
	ds_read_b64_tr_b16 v[102:103], v207 offset:2592
	s_waitcnt lgkmcnt(2)
	v_mfma_f32_16x16x32_f16 v[76:79], v[96:99], v[92:95], v[76:79]
	ds_read_b64_tr_b16 v[96:97], v207 offset:64
	ds_read_b64_tr_b16 v[98:99], v207 offset:2624
	s_waitcnt lgkmcnt(0)
	v_mfma_f32_16x16x32_f16 v[84:87], v[96:99], v[92:95], v[84:87]
	ds_read_b64_tr_b16 v[96:97], v207 offset:96
	ds_read_b64_tr_b16 v[98:99], v207 offset:2656
	v_mfma_f32_16x16x32_f16 v[80:83], v[100:103], v[92:95], v[80:83]
	s_waitcnt lgkmcnt(0)
	v_mfma_f32_16x16x32_f16 v[88:91], v[96:99], v[92:95], v[88:91]
	ds_read_b64_tr_b16 v[98:99], v208 offset:2560
	ds_read_b64_tr_b16 v[96:97], v208
	ds_read_b64_tr_b16 v[100:101], v208 offset:32
	v_cvt_pk_f16_f32 v95, v246, v247
	v_cvt_pk_f16_f32 v94, v244, v245
	v_cvt_pk_f16_f32 v93, v189, v243
	v_cvt_pk_f16_f32 v92, v111, v110
	ds_read_b64_tr_b16 v[102:103], v208 offset:2592
	s_waitcnt lgkmcnt(2)
	v_mfma_f32_16x16x32_f16 v[76:79], v[96:99], v[92:95], v[76:79]
	ds_read_b64_tr_b16 v[96:97], v208 offset:64
	ds_read_b64_tr_b16 v[98:99], v208 offset:2624
	s_waitcnt lgkmcnt(0)
	v_mfma_f32_16x16x32_f16 v[84:87], v[96:99], v[92:95], v[84:87]
	ds_read_b64_tr_b16 v[96:97], v208 offset:96
	ds_read_b64_tr_b16 v[98:99], v208 offset:2656
	s_waitcnt lgkmcnt(0)
	v_mfma_f32_16x16x32_f16 v[88:91], v[96:99], v[92:95], v[88:91]
	ds_read_b64_tr_b16 v[96:97], v208 offset:5120
	ds_read_b64_tr_b16 v[98:99], v208 offset:7680
	v_mfma_f32_16x16x32_f16 v[80:83], v[100:103], v[92:95], v[80:83]
	v_cvt_pk_f16_f32 v95, v195, v200
	v_cvt_pk_f16_f32 v94, v252, v253
	v_cvt_pk_f16_f32 v93, v250, v251
	v_cvt_pk_f16_f32 v92, v248, v249
	s_waitcnt lgkmcnt(0)
	s_nop 0
	v_mfma_f32_16x16x32_f16 v[76:79], v[96:99], v[92:95], v[76:79]
	ds_read_b64_tr_b16 v[96:97], v208 offset:5152
	ds_read_b64_tr_b16 v[98:99], v208 offset:7712
	s_waitcnt lgkmcnt(0)
	v_mfma_f32_16x16x32_f16 v[80:83], v[96:99], v[92:95], v[80:83]
	ds_read_b64_tr_b16 v[96:97], v208 offset:5184
	ds_read_b64_tr_b16 v[98:99], v208 offset:7744
	s_waitcnt lgkmcnt(0)
	v_mfma_f32_16x16x32_f16 v[84:87], v[96:99], v[92:95], v[84:87]
	ds_read_b64_tr_b16 v[96:97], v208 offset:5216
	ds_read_b64_tr_b16 v[98:99], v208 offset:7776
	s_waitcnt lgkmcnt(0)
	v_mfma_f32_16x16x32_f16 v[88:91], v[96:99], v[92:95], v[88:91]
.LBB0_1820:
	s_nop 0
	s_waitcnt lgkmcnt(0)
	s_barrier
	s_add_i32 s30, s30, 2
	s_cmp_lt_i32 s30, s28
	s_cbranch_scc0 .LBB0_2047

; template <int MODE, int TM> ...
;     ...
;   __builtin_amdgcn_s_setprio(1);
; #pragma unroll
;   for (int t = 0; t < 2; ++t) {
;     if (!(TM & (1 << t))) continue;
;     const h16* Ks = t ? Ks1 : Ks0;
; #pragma unroll
;     for (int kt = 0; kt < 4; ++kt) {
;       S[t][kt] = f32x4{0.f, 0.f, 0.f, 0.f};
; #pragma unroll
;       for (int ks = 0; ks < 2; ++ks) {
;         h16x8 Kf = *(const h16x8*)(Ks + (kt * 16 + col) * KP + ks * 32 + q4 * 8);
;         S[t][kt] = __builtin_amdgcn_mfma_f32_16x16x32_f16(Kf, Q[ks], S[t][kt], 0, 0, 0);
;       }
;     }
;   }
;   __builtin_amdgcn_s_setprio(0);
;   const float* bt = biasT + hd * 800;
;   float addc[2] = {0.f, 0.f}, sclc[2] = {1.f, 1.f};
; #pragma unroll
;   for (int t = 0; t < 2; ++t) {
;     if (!(TM & (1 << t))) continue;
;     const int kbase = kbase0 + 64 * t;
;     if (far[t]) {
;       const bool ok = (MODE == M_SEL) ? selbit[t] : true;
;       addc[t] = ok ? bt[799] : -1e30f;
;       sclc[t] = SCL2;
;     } else {
;       addc[t] = 0.f;
;       sclc[t] = 1.f;
;       const int kx0 = kbase + q4 * 4;
;       const int d0 = (DK == 16) ? tq - 31 - 16 * kx0 : tq - kx0;
; #pragma unroll
;       for (int kt = 0; kt < 4; ++kt)
; #pragma unroll
;         for (int j = 0; j < 4; ++j) {
;           const int dist = d0 - DK * (kt * 16 + j);
;           const int kx = kx0 + kt * 16 + j;
;           bool valid = dist >= 0;
;           if (MODE == M_WIN) valid = valid && dist < 512 && kx >= 0;
;           if (MODE == M_SEL) valid = valid && selbit[t];
;           if (DK == 16) valid = valid && kx < NCMP;
;           const int dc = dist < 0 ? 0 : (dist > 799 ? 799 : dist);
;           S[t][kt][j] = valid ? S[t][kt][j] * SCL2 + bt[dc] : -1e30f;
;         }
.LBB0_1833:
	s_lshl_b32 s0, s30, 1
	s_add_i32 s2, s0, s20
	s_lshl_b32 s3, s2, 6
	s_cmp_ge_i32 s0, s21
	s_nop 0
	ds_read_b128 v[112:115], v155 offset:12800
	ds_read_b128 v[108:111], v155 offset:12864
	s_mov_b64 s[0:1], -1
	v_or_b32_e32 v0, s3, v154
	s_cbranch_scc0 .LBB0_1867
	s_waitcnt lgkmcnt(1)
	v_mfma_f32_16x16x32_f16 v[92:95], v[112:115], v[4:7], 0
	ds_read_b128 v[96:99], v155 offset:15360
	ds_read_b128 v[116:119], v155 offset:17920
	s_waitcnt lgkmcnt(2)
	v_mfma_f32_16x16x32_f16 v[104:107], v[108:111], v[8:11], v[92:95]
	s_nop 3
	ds_read_b128 v[92:95], v155 offset:15424
	s_waitcnt lgkmcnt(2)
	v_mfma_f32_16x16x32_f16 v[96:99], v[96:99], v[4:7], 0
	s_waitcnt lgkmcnt(0)
	v_mfma_f32_16x16x32_f16 v[100:103], v[92:95], v[8:11], v[96:99]
	ds_read_b128 v[92:95], v155 offset:17984
	v_mfma_f32_16x16x32_f16 v[96:99], v[116:119], v[4:7], 0
	ds_read_b128 v[116:119], v155 offset:20480
	s_waitcnt lgkmcnt(1)
	v_mfma_f32_16x16x32_f16 v[96:99], v[92:95], v[8:11], v[96:99]
	ds_read_b128 v[92:95], v155 offset:20544
	s_waitcnt lgkmcnt(1)
	v_mfma_f32_16x16x32_f16 v[116:119], v[116:119], v[4:7], 0
	s_waitcnt lgkmcnt(0)
	v_mfma_f32_16x16x32_f16 v[92:95], v[92:95], v[8:11], v[116:119]
	s_nop 0
	v_sub_u32_e32 v2, v182, v0
	s_cmp_gt_i32 s2, -1
	v_cmp_gt_u32_e32 vcc, s76, v2
	s_cselect_b64 s[0:1], -1, 0
	s_and_b64 s[44:45], s[0:1], vcc
	v_mov_b32_e32 v3, 0xf149f2ca
	v_mov_b32_e32 v116, 0xf149f2ca
	s_and_saveexec_b64 s[0:1], s[44:45]
	s_cbranch_execz .LBB0_1836
	v_lshl_add_u32 v2, v2, 2, v157
	ds_read_b32 v116, v2

; template <int MODE, int TM> ...
;     ...
;   __builtin_amdgcn_s_setprio(1);
; #pragma unroll
;   for (int t = 0; t < 2; ++t) {
;     if (!(TM & (1 << t))) continue;
;     const h16* Ks = t ? Ks1 : Ks0;
; #pragma unroll
;     for (int kt = 0; kt < 4; ++kt) {
;     ...
;     float mx = -1e30f;
; #pragma unroll
;     for (int t = 0; t < 2; ++t) {
;       if (!(TM & (1 << t))) continue;
;       float mt = -1e30f;
; #pragma unroll
;       for (int kt = 0; kt < 4; ++kt)
; #pragma unroll
;         for (int j = 0; j < 4; ++j) mt = fmaxf(mt, S[t][kt][j]);
;       mx = fmaxf(mx, mt * sclc[t] + addc[t]);
;     }
;     mx = max4q(mx);
;     const float mn = fmaxf(st.m, mx);
;     const float corr = __builtin_amdgcn_exp2f(st.m - mn);
;     st.m = mn;
;     const float mm = fmaxf(mn, -1e20f);
;     float ls = 0.f;
; #pragma unroll
;     for (int t = 0; t < 2; ++t) {
;       if (!(TM & (1 << t))) continue;
;       const float am = addc[t] - mm;
; #pragma unroll
;       for (int kt = 0; kt < 4; ++kt) {
;         const f32x4 e = S[t][kt] * sclc[t] + am;
; #pragma unroll
;         for (int j = 0; j < 4; ++j) {
;           float pv = __builtin_amdgcn_exp2f(e[j]);
;           S[t][kt][j] = pv;
;           ls += pv;
;         }
;       }
;     }
;     st.l = st.l * corr + ls;
;     if (MODE != M_CMPA) {
; #pragma unroll
;       for (int nt = 0; nt < 4; ++nt) O[nt] *= corr;
;     }
;   }
;   if (MODE == M_CMPA) return;
;   __builtin_amdgcn_s_setprio(1);
; #pragma unroll
;   for (int t = 0; t < 2; ++t) {
;     if (!(TM & (1 << t))) continue;
;     const h16* Vt = t ? Vt1 : Vt0;
; #pragma unroll
;     for (int ks = 0; ks < 2; ++ks) {
;       h16x8 Pf;
; #pragma unroll
;       for (int i = 0; i < 4; ++i) { Pf[i] = (h16)S[t][2 * ks][i]; Pf[4 + i] = (h16)S[t][2 * ks + 1][i]; }
; #pragma unroll
;       for (int nt = 0; nt < 4; ++nt) {
;         const h16* vp = Vt + (ks * 32 + q4 * 4 + (col >> 2)) * KP + nt * 16 + 4 * (col & 3);
;         const s16x4v r0 = __builtin_amdgcn_ds_read_tr16_b64_v4i16((LAS s16x4v*)vp);
;         const s16x4v r1 = __builtin_amdgcn_ds_read_tr16_b64_v4i16((LAS s16x4v*)(vp + 16 * KP));
;         const h16x4 v0 = __builtin_bit_cast(h16x4, r0), v1 = __builtin_bit_cast(h16x4, r1);
;         const h16x8 Vf = {v0[0], v0[1], v0[2], v0[3], v1[0], v1[1], v1[2], v1[3]};
;         O[nt] = __builtin_amdgcn_mfma_f32_16x16x32_f16(Vf, Pf, O[nt], 0, 0, 0);
;       }
;     }
;   }
.LBB0_1866:
	s_or_b64 exec, exec, s[0:1]
	s_waitcnt lgkmcnt(0)
	v_fmac_f32_e32 v93, 0x3e38aa3b, v94
	v_max3_f32 v2, v116, s67, v3
	v_max3_f32 v2, v2, v105, v104
	v_max3_f32 v2, v2, v107, v106
	v_max3_f32 v2, v2, v101, v100
	v_max3_f32 v2, v2, v103, v102
	v_max3_f32 v2, v2, v97, v96
	v_max3_f32 v2, v2, v99, v98
	v_max3_f32 v2, v2, v93, v92
	v_add_f32_e32 v2, 0, v2
	v_max_f32_e32 v2, 0xf149f2ca, v2
	v_mov_b32_e32 v94, v2
	s_nop 1
	v_permlane16_swap_b32_e32 v94, v2
	s_waitcnt lgkmcnt(0)
	v_max_f32_e32 v94, v94, v94
	v_max_f32_e32 v2, v2, v94
	v_mov_b32_e32 v94, v2
	s_nop 1
	v_permlane32_swap_b32_e32 v2, v94
	v_max3_f32 v2, v126, v2, v94
	v_max_f32_e32 v95, 0xe0ad78ec, v2
	v_add_f32_e64 v116, v116, -v95
	v_add_f32_e64 v3, v3, -v95
	v_exp_f32_e32 v116, v116
	v_add_f32_e64 v105, v105, -v95
	v_exp_f32_e32 v120, v3
	v_add_f32_e64 v104, v104, -v95
	v_exp_f32_e32 v117, v105
	v_exp_f32_e32 v121, v104
	v_add_f32_e64 v104, v107, -v95
	v_add_f32_e32 v3, 0, v116
	v_exp_f32_e32 v118, v104
	v_add_f32_e64 v104, v106, -v95
	v_add_f32_e32 v3, v120, v3
	v_exp_f32_e32 v122, v104
	v_add_f32_e64 v101, v101, -v95
	v_add_f32_e32 v3, v117, v3
	v_exp_f32_e32 v119, v101
	v_add_f32_e64 v100, v100, -v95
	v_add_f32_e32 v3, v121, v3
	v_exp_f32_e32 v123, v100
	v_add_f32_e64 v100, v103, -v95
	v_add_f32_e32 v3, v118, v3
	v_exp_f32_e32 v173, v100
	v_add_f32_e64 v100, v102, -v95
	v_add_f32_e32 v3, v122, v3
	v_exp_f32_e32 v188, v100
	v_add_f32_e64 v97, v97, -v95
	v_add_f32_e32 v3, v119, v3
	v_exp_f32_e32 v189, v97
	v_add_f32_e64 v96, v96, -v95
	v_add_f32_e32 v3, v123, v3
	v_exp_f32_e32 v243, v96
	v_add_f32_e64 v96, v99, -v95
	v_add_f32_e32 v3, v173, v3
	v_exp_f32_e32 v248, v96
	v_add_f32_e64 v96, v98, -v95
	v_add_f32_e32 v3, v188, v3
	v_exp_f32_e32 v249, v96
	v_add_f32_e64 v93, v93, -v95
	v_add_f32_e32 v3, v189, v3
	v_exp_f32_e32 v250, v93
	v_add_f32_e64 v92, v92, -v95
	v_sub_f32_e32 v94, v126, v2
	v_add_f32_e32 v3, v243, v3
	v_exp_f32_e32 v251, v92
	v_add_f32_e32 v3, v248, v3
	v_exp_f32_e32 v104, v94
	v_add_f32_e32 v3, v249, v3
	v_add_f32_e32 v3, v250, v3
	v_add_f32_e32 v3, v251, v3
	v_fmac_f32_e32 v3, v127, v104
	v_pk_mul_f32 v[94:95], v[78:79], v[104:105] op_sel_hi:[1,0]
	v_pk_mul_f32 v[92:93], v[76:77], v[104:105] op_sel_hi:[1,0]
	v_pk_mul_f32 v[98:99], v[82:83], v[104:105] op_sel_hi:[1,0]
	v_pk_mul_f32 v[96:97], v[80:81], v[104:105] op_sel_hi:[1,0]
	v_pk_mul_f32 v[102:103], v[86:87], v[104:105] op_sel_hi:[1,0]
	v_pk_mul_f32 v[100:101], v[84:85], v[104:105] op_sel_hi:[1,0]
	v_pk_mul_f32 v[106:107], v[90:91], v[104:105] op_sel_hi:[1,0]
	v_pk_mul_f32 v[104:105], v[88:89], v[104:105] op_sel_hi:[1,0]
	s_nop 0
	v_cvt_pk_f16_f32 v119, v119, v123
	v_cvt_pk_f16_f32 v118, v118, v122
	v_cvt_pk_f16_f32 v117, v117, v121
	v_cvt_pk_f16_f32 v116, v116, v120
	ds_read_b64_tr_b16 v[122:123], v205 offset:25600
	ds_read_b64_tr_b16 v[120:121], v205 offset:23040
	ds_read_b64_tr_b16 v[244:245], v205 offset:23072
	s_waitcnt lgkmcnt(1)
	v_mfma_f32_16x16x32_f16 v[92:95], v[120:123], v[116:119], v[92:95]
	ds_read_b64_tr_b16 v[246:247], v205 offset:25632
	ds_read_b64_tr_b16 v[120:121], v205 offset:23104
	ds_read_b64_tr_b16 v[122:123], v205 offset:25664
	s_mov_b64 s[0:1], 0
	s_waitcnt lgkmcnt(0)
	v_mfma_f32_16x16x32_f16 v[100:103], v[120:123], v[116:119], v[100:103]
	ds_read_b64_tr_b16 v[120:121], v205 offset:23136
	ds_read_b64_tr_b16 v[122:123], v205 offset:25696
	s_waitcnt lgkmcnt(0)
	v_mfma_f32_16x16x32_f16 v[104:107], v[120:123], v[116:119], v[104:107]
	ds_read_b64_tr_b16 v[120:121], v205 offset:28160
	ds_read_b64_tr_b16 v[122:123], v205 offset:30720
	v_mfma_f32_16x16x32_f16 v[96:99], v[244:247], v[116:119], v[96:99]
	v_cvt_pk_f16_f32 v119, v250, v251
	v_cvt_pk_f16_f32 v118, v248, v249
	v_cvt_pk_f16_f32 v117, v189, v243
	v_cvt_pk_f16_f32 v116, v173, v188
	s_waitcnt lgkmcnt(0)
	s_nop 0
	v_mfma_f32_16x16x32_f16 v[92:95], v[120:123], v[116:119], v[92:95]
	ds_read_b64_tr_b16 v[120:121], v205 offset:28192
	ds_read_b64_tr_b16 v[122:123], v205 offset:30752
	s_waitcnt lgkmcnt(0)
	v_mfma_f32_16x16x32_f16 v[96:99], v[120:123], v[116:119], v[96:99]
	ds_read_b64_tr_b16 v[120:121], v205 offset:28224
	ds_read_b64_tr_b16 v[122:123], v205 offset:30784
	s_waitcnt lgkmcnt(0)
	v_mfma_f32_16x16x32_f16 v[100:103], v[120:123], v[116:119], v[100:103]
	ds_read_b64_tr_b16 v[120:121], v205 offset:28256
	ds_read_b64_tr_b16 v[122:123], v205 offset:30816
	s_waitcnt lgkmcnt(0)
	v_mfma_f32_16x16x32_f16 v[104:107], v[120:123], v[116:119], v[104:107]
.LBB0_1867:
	s_and_b64 vcc, exec, s[0:1]
	s_cbranch_vccz .LBB0_1933
	s_waitcnt lgkmcnt(1)
	v_mfma_f32_16x16x32_f16 v[92:95], v[112:115], v[4:7], 0
	ds_read_b128 v[96:99], v155 offset:15360
	ds_read_b128 v[100:103], v155 offset:17920
	ds_read_b128 v[244:247], v155 offset:38400
	s_waitcnt lgkmcnt(3)
	v_mfma_f32_16x16x32_f16 v[120:123], v[108:111], v[8:11], v[92:95]
	s_nop 2
	ds_read_b128 v[92:95], v155 offset:15424
	s_waitcnt lgkmcnt(3)
	v_mfma_f32_16x16x32_f16 v[96:99], v[96:99], v[4:7], 0
	s_waitcnt lgkmcnt(0)
	v_mfma_f32_16x16x32_f16 v[116:119], v[92:95], v[8:11], v[96:99]
	ds_read_b128 v[92:95], v155 offset:17984
	v_mfma_f32_16x16x32_f16 v[96:99], v[100:103], v[4:7], 0
	ds_read_b128 v[100:103], v155 offset:20480
	s_waitcnt lgkmcnt(1)
	v_mfma_f32_16x16x32_f16 v[112:115], v[92:95], v[8:11], v[96:99]
	ds_read_b128 v[92:95], v155 offset:20544
	s_waitcnt lgkmcnt(1)
	v_mfma_f32_16x16x32_f16 v[96:99], v[100:103], v[4:7], 0
	ds_read_b128 v[100:103], v155 offset:33280
	s_waitcnt lgkmcnt(1)
	v_mfma_f32_16x16x32_f16 v[108:111], v[92:95], v[8:11], v[96:99]
	ds_read_b128 v[92:95], v155 offset:33344
	s_waitcnt lgkmcnt(1)
	v_mfma_f32_16x16x32_f16 v[96:99], v[100:103], v[4:7], 0
	ds_read_b128 v[100:103], v155 offset:35840
	s_waitcnt lgkmcnt(1)
	v_mfma_f32_16x16x32_f16 v[104:107], v[92:95], v[8:11], v[96:99]
	ds_read_b128 v[92:95], v155 offset:35904
	s_waitcnt lgkmcnt(1)
	v_mfma_f32_16x16x32_f16 v[96:99], v[100:103], v[4:7], 0
	s_waitcnt lgkmcnt(0)
	v_mfma_f32_16x16x32_f16 v[100:103], v[92:95], v[8:11], v[96:99]
	ds_read_b128 v[92:95], v155 offset:38464
	v_mfma_f32_16x16x32_f16 v[96:99], v[244:247], v[4:7], 0
	ds_read_b128 v[244:247], v155 offset:40960
	s_waitcnt lgkmcnt(1)
	v_mfma_f32_16x16x32_f16 v[96:99], v[92:95], v[8:11], v[96:99]
	ds_read_b128 v[92:95], v155 offset:41024
	s_waitcnt lgkmcnt(1)
	v_mfma_f32_16x16x32_f16 v[244:247], v[244:247], v[4:7], 0
	s_waitcnt lgkmcnt(0)
	v_mfma_f32_16x16x32_f16 v[92:95], v[92:95], v[8:11], v[244:247]
	s_nop 0
	v_sub_u32_e32 v2, v182, v0
	s_cmp_gt_i32 s2, -1
	v_cmp_gt_u32_e32 vcc, s76, v2
	s_cselect_b64 s[0:1], -1, 0
	s_and_b64 s[2:3], s[0:1], vcc
	v_mov_b32_e32 v3, 0xf149f2ca
	v_mov_b32_e32 v173, 0xf149f2ca
	s_and_saveexec_b64 s[0:1], s[2:3]
	s_cbranch_execz .LBB0_1870
	v_lshl_add_u32 v2, v2, 2, v157
	ds_read_b32 v173, v2

; template <int MODE, int TM> ...
;     ...
;     float mx = -1e30f;
; #pragma unroll
;     for (int t = 0; t < 2; ++t) {
;       if (!(TM & (1 << t))) continue;
;       float mt = -1e30f;
; #pragma unroll
;       for (int kt = 0; kt < 4; ++kt)
; #pragma unroll
;         for (int j = 0; j < 4; ++j) mt = fmaxf(mt, S[t][kt][j]);
;       mx = fmaxf(mx, mt * sclc[t] + addc[t]);
;     }
;     mx = max4q(mx);
;     const float mn = fmaxf(st.m, mx);
;     const float corr = __builtin_amdgcn_exp2f(st.m - mn);
;     st.m = mn;
;     const float mm = fmaxf(mn, -1e20f);
;     float ls = 0.f;
; #pragma unroll
;     for (int t = 0; t < 2; ++t) {
;       if (!(TM & (1 << t))) continue;
;       const float am = addc[t] - mm;
; #pragma unroll
;       for (int kt = 0; kt < 4; ++kt) {
;         const f32x4 e = S[t][kt] * sclc[t] + am;
; #pragma unroll
;         for (int j = 0; j < 4; ++j) {
;           float pv = __builtin_amdgcn_exp2f(e[j]);
;           S[t][kt][j] = pv;
;           ls += pv;
;         }
;       }
;     }
;     st.l = st.l * corr + ls;
;     if (MODE != M_CMPA) {
; #pragma unroll
;       for (int nt = 0; nt < 4; ++nt) O[nt] *= corr;
;     }
;   }
;   if (MODE == M_CMPA) return;
;   __builtin_amdgcn_s_setprio(1);
; #pragma unroll
;   for (int t = 0; t < 2; ++t) {
;     if (!(TM & (1 << t))) continue;
;     const h16* Vt = t ? Vt1 : Vt0;
; #pragma unroll
;     for (int ks = 0; ks < 2; ++ks) {
;       h16x8 Pf;
; #pragma unroll
;       for (int i = 0; i < 4; ++i) { Pf[i] = (h16)S[t][2 * ks][i]; Pf[4 + i] = (h16)S[t][2 * ks + 1][i]; }
; #pragma unroll
;       for (int nt = 0; nt < 4; ++nt) {
;         const h16* vp = Vt + (ks * 32 + q4 * 4 + (col >> 2)) * KP + nt * 16 + 4 * (col & 3);
.LBB0_1932:
	s_or_b64 exec, exec, s[0:1]
	s_waitcnt lgkmcnt(0)
	v_fmac_f32_e32 v93, 0x3e38aa3b, v94
	v_max3_f32 v0, v173, s67, v3
	v_max3_f32 v2, v111, s67, v110
	v_max3_f32 v0, v0, v121, v120
	v_max3_f32 v2, v2, v105, v104
	v_max3_f32 v0, v0, v123, v122
	v_max3_f32 v2, v2, v107, v106
	v_max3_f32 v0, v0, v117, v116
	v_max3_f32 v2, v2, v101, v100
	v_max3_f32 v0, v0, v119, v118
	v_max3_f32 v2, v2, v103, v102
	v_max3_f32 v0, v0, v113, v112
	v_max3_f32 v2, v2, v97, v96
	v_max3_f32 v0, v0, v115, v114
	v_max3_f32 v2, v2, v99, v98
	v_max3_f32 v0, v0, v109, v108
	v_max3_f32 v2, v2, v93, v92
	v_add_f32_e32 v0, 0, v0
	v_add_f32_e32 v2, 0, v2
	v_max3_f32 v0, v0, s67, v2
	v_mov_b32_e32 v2, v0
	s_nop 1
	v_permlane16_swap_b32_e32 v2, v0
	s_waitcnt lgkmcnt(0)
	v_max_f32_e32 v2, v2, v2
	v_max_f32_e32 v0, v0, v2
	v_mov_b32_e32 v2, v0
	s_nop 1
	v_permlane32_swap_b32_e32 v0, v2
	v_max3_f32 v2, v126, v0, v2
	v_max_f32_e32 v0, 0xe0ad78ec, v2
	v_add_f32_e64 v94, v173, -v0
	v_exp_f32_e32 v173, v94
	v_add_f32_e64 v3, v3, -v0
	v_sub_f32_e32 v94, v126, v2
	v_exp_f32_e32 v126, v3
	v_add_f32_e64 v3, v121, -v0
	v_exp_f32_e32 v121, v3
	v_add_f32_e64 v3, v120, -v0
	v_add_f32_e32 v95, 0, v173
	v_exp_f32_e32 v120, v3
	v_add_f32_e64 v3, v123, -v0
	v_exp_f32_e32 v123, v3
	v_add_f32_e32 v3, v126, v95
	v_add_f32_e64 v95, v122, -v0
	v_exp_f32_e32 v122, v95
	v_add_f32_e64 v95, v117, -v0
	v_add_f32_e32 v3, v121, v3
	v_exp_f32_e32 v95, v95
	v_add_f32_e64 v116, v116, -v0
	v_add_f32_e32 v3, v120, v3
	v_exp_f32_e32 v116, v116
	v_add_f32_e64 v117, v119, -v0
	v_add_f32_e32 v3, v123, v3
	v_exp_f32_e32 v117, v117
	v_add_f32_e64 v118, v118, -v0
	v_add_f32_e32 v3, v122, v3
	v_exp_f32_e32 v118, v118
	v_add_f32_e64 v113, v113, -v0
	v_add_f32_e32 v3, v95, v3
	v_exp_f32_e32 v113, v113
	v_add_f32_e64 v112, v112, -v0
	v_add_f32_e32 v3, v116, v3
	v_exp_f32_e32 v112, v112
	v_add_f32_e64 v115, v115, -v0
	v_add_f32_e32 v3, v117, v3
	v_exp_f32_e32 v115, v115
	v_add_f32_e64 v114, v114, -v0
	v_add_f32_e32 v3, v118, v3
	v_exp_f32_e32 v114, v114
	v_add_f32_e64 v109, v109, -v0
	v_add_f32_e32 v3, v113, v3
	v_exp_f32_e32 v109, v109
	v_add_f32_e64 v108, v108, -v0
	v_add_f32_e32 v3, v112, v3
	v_exp_f32_e32 v108, v108
	v_add_f32_e64 v111, v111, -v0
	v_add_f32_e32 v3, v115, v3
	v_exp_f32_e32 v111, v111
	v_add_f32_e64 v110, v110, -v0
	v_add_f32_e32 v3, v114, v3
	v_exp_f32_e32 v110, v110
	v_add_f32_e64 v105, v105, -v0
	v_add_f32_e32 v3, v109, v3
	v_exp_f32_e32 v105, v105
	v_add_f32_e64 v104, v104, -v0
	v_add_f32_e32 v3, v108, v3
	v_exp_f32_e32 v104, v104
	v_add_f32_e64 v107, v107, -v0
	v_add_f32_e32 v3, v111, v3
	v_exp_f32_e32 v107, v107
	v_add_f32_e64 v106, v106, -v0
	v_add_f32_e32 v3, v110, v3
	v_exp_f32_e32 v106, v106
	v_add_f32_e64 v101, v101, -v0
	v_add_f32_e32 v3, v105, v3
	v_exp_f32_e32 v119, v101
	v_add_f32_e64 v100, v100, -v0
	v_add_f32_e32 v3, v104, v3
	v_exp_f32_e32 v188, v100
	v_add_f32_e64 v100, v103, -v0
	v_add_f32_e32 v3, v107, v3
	v_exp_f32_e32 v189, v100
	v_add_f32_e64 v100, v102, -v0
	v_add_f32_e32 v3, v106, v3
	v_exp_f32_e32 v243, v100
	v_add_f32_e64 v97, v97, -v0
	v_add_f32_e32 v3, v119, v3
	v_exp_f32_e32 v244, v97
	v_add_f32_e64 v96, v96, -v0
	v_add_f32_e32 v3, v188, v3
	v_exp_f32_e32 v245, v96
	v_add_f32_e64 v96, v99, -v0
	v_add_f32_e32 v3, v189, v3
	v_exp_f32_e32 v246, v96
	v_add_f32_e64 v96, v98, -v0
	v_add_f32_e32 v3, v243, v3
	v_exp_f32_e32 v247, v96
	v_add_f32_e64 v93, v93, -v0
	v_add_f32_e32 v3, v244, v3
	v_exp_f32_e32 v248, v93
	v_add_f32_e64 v0, v92, -v0
	v_add_f32_e32 v3, v245, v3
	v_exp_f32_e32 v249, v0
	v_add_f32_e32 v3, v246, v3
	v_exp_f32_e32 v0, v94
	v_add_f32_e32 v3, v247, v3
	v_add_f32_e32 v3, v248, v3
	v_add_f32_e32 v3, v249, v3
	v_fmac_f32_e32 v3, v127, v0
	v_pk_mul_f32 v[78:79], v[78:79], v[0:1] op_sel_hi:[1,0]
	v_pk_mul_f32 v[76:77], v[76:77], v[0:1] op_sel_hi:[1,0]
	v_pk_mul_f32 v[82:83], v[82:83], v[0:1] op_sel_hi:[1,0]
	v_pk_mul_f32 v[80:81], v[80:81], v[0:1] op_sel_hi:[1,0]
	v_pk_mul_f32 v[86:87], v[86:87], v[0:1] op_sel_hi:[1,0]
	v_pk_mul_f32 v[84:85], v[84:85], v[0:1] op_sel_hi:[1,0]
	v_pk_mul_f32 v[90:91], v[90:91], v[0:1] op_sel_hi:[1,0]
	v_pk_mul_f32 v[88:89], v[88:89], v[0:1] op_sel_hi:[1,0]
	s_nop 0
	ds_read_b64_tr_b16 v[98:99], v205 offset:25600
	ds_read_b64_tr_b16 v[96:97], v205 offset:23040
	ds_read_b64_tr_b16 v[100:101], v205 offset:23072
	v_cvt_pk_f16_f32 v95, v95, v116
	v_cvt_pk_f16_f32 v94, v123, v122
	v_cvt_pk_f16_f32 v93, v121, v120
	v_cvt_pk_f16_f32 v92, v173, v126
	ds_read_b64_tr_b16 v[102:103], v205 offset:25632
	s_waitcnt lgkmcnt(2)
; #define LAS __attribute__((address_space(3)))
; template <int MODE, int TM> ...
;     ...
;   for (int t = 0; t < 2; ++t) {
;     if (!(TM & (1 << t))) continue;
;     const h16* Vt = t ? Vt1 : Vt0;
; #pragma unroll
;     for (int ks = 0; ks < 2; ++ks) {
;       h16x8 Pf;
; #pragma unroll
;       for (int i = 0; i < 4; ++i) { Pf[i] = (h16)S[t][2 * ks][i]; Pf[4 + i] = (h16)S[t][2 * ks + 1][i]; }
; #pragma unroll
;       for (int nt = 0; nt < 4; ++nt) {
;         const h16* vp = Vt + (ks * 32 + q4 * 4 + (col >> 2)) * KP + nt * 16 + 4 * (col & 3);
;         const s16x4v r0 = __builtin_amdgcn_ds_read_tr16_b64_v4i16((LAS s16x4v*)vp);
;         const s16x4v r1 = __builtin_amdgcn_ds_read_tr16_b64_v4i16((LAS s16x4v*)(vp + 16 * KP));
;         const h16x4 v0 = __builtin_bit_cast(h16x4, r0), v1 = __builtin_bit_cast(h16x4, r1);
;         const h16x8 Vf = {v0[0], v0[1], v0[2], v0[3], v1[0], v1[1], v1[2], v1[3]};
;         O[nt] = __builtin_amdgcn_mfma_f32_16x16x32_f16(Vf, Pf, O[nt], 0, 0, 0);
;       }
;     }
;   }
;   __builtin_amdgcn_s_setprio(0);
;     ...
;       [&](int i, const h16x8 (&r)[4]) {
;         st_k(KSB(i, 0), srow, c8, r[0]); st_k(VTB(i, 0), srow, c8, r[1]); st_k(KSB(i, 1), srow, c8, r[2]); st_k(VTB(i, 1), srow, c8, r[3]); },
	v_mfma_f32_16x16x32_f16 v[76:79], v[96:99], v[92:95], v[76:79]
	ds_read_b64_tr_b16 v[96:97], v205 offset:23104
	ds_read_b64_tr_b16 v[98:99], v205 offset:25664
	s_waitcnt lgkmcnt(0)
	v_mfma_f32_16x16x32_f16 v[84:87], v[96:99], v[92:95], v[84:87]
	ds_read_b64_tr_b16 v[96:97], v205 offset:23136
	ds_read_b64_tr_b16 v[98:99], v205 offset:25696
	s_waitcnt lgkmcnt(0)
	v_mfma_f32_16x16x32_f16 v[88:91], v[96:99], v[92:95], v[88:91]
	ds_read_b64_tr_b16 v[96:97], v205 offset:28160
	ds_read_b64_tr_b16 v[98:99], v205 offset:30720
	v_mfma_f32_16x16x32_f16 v[80:83], v[100:103], v[92:95], v[80:83]
	v_cvt_pk_f16_f32 v95, v109, v108
	v_cvt_pk_f16_f32 v94, v115, v114
	v_cvt_pk_f16_f32 v93, v113, v112
	v_cvt_pk_f16_f32 v92, v117, v118
	s_waitcnt lgkmcnt(0)
	s_nop 0
	v_mfma_f32_16x16x32_f16 v[76:79], v[96:99], v[92:95], v[76:79]
	ds_read_b64_tr_b16 v[96:97], v205 offset:28192
	ds_read_b64_tr_b16 v[98:99], v205 offset:30752
	s_waitcnt lgkmcnt(0)
	v_mfma_f32_16x16x32_f16 v[80:83], v[96:99], v[92:95], v[80:83]
	ds_read_b64_tr_b16 v[96:97], v205 offset:28224
	ds_read_b64_tr_b16 v[98:99], v205 offset:30784
	s_waitcnt lgkmcnt(0)
	v_mfma_f32_16x16x32_f16 v[84:87], v[96:99], v[92:95], v[84:87]
	ds_read_b64_tr_b16 v[96:97], v205 offset:28256
	ds_read_b64_tr_b16 v[98:99], v205 offset:30816
	s_waitcnt lgkmcnt(0)
	v_mfma_f32_16x16x32_f16 v[88:91], v[96:99], v[92:95], v[88:91]
	ds_read_b64_tr_b16 v[96:97], v205 offset:43520
	ds_read_b64_tr_b16 v[98:99], v205 offset:46080
	v_cvt_pk_f16_f32 v95, v119, v188
	v_cvt_pk_f16_f32 v94, v107, v106
	v_cvt_pk_f16_f32 v93, v105, v104
	v_cvt_pk_f16_f32 v92, v111, v110
	v_cvt_pk_f16_f32 v107, v248, v249
	v_cvt_pk_f16_f32 v106, v246, v247
	s_waitcnt lgkmcnt(0)
	v_mfma_f32_16x16x32_f16 v[76:79], v[96:99], v[92:95], v[76:79]
	ds_read_b64_tr_b16 v[96:97], v205 offset:43552
	ds_read_b64_tr_b16 v[98:99], v205 offset:46112
	v_cvt_pk_f16_f32 v105, v244, v245
	v_cvt_pk_f16_f32 v104, v189, v243
	s_waitcnt lgkmcnt(0)
	v_mfma_f32_16x16x32_f16 v[80:83], v[96:99], v[92:95], v[80:83]
	ds_read_b64_tr_b16 v[96:97], v205 offset:43584
	ds_read_b64_tr_b16 v[98:99], v205 offset:46144
	s_waitcnt lgkmcnt(0)
	v_mfma_f32_16x16x32_f16 v[84:87], v[96:99], v[92:95], v[84:87]
	ds_read_b64_tr_b16 v[96:97], v205 offset:43616
	ds_read_b64_tr_b16 v[98:99], v205 offset:46176
	s_waitcnt lgkmcnt(0)
	v_mfma_f32_16x16x32_f16 v[88:91], v[96:99], v[92:95], v[88:91]
	ds_read_b64_tr_b16 v[92:93], v205 offset:48640
	ds_read_b64_tr_b16 v[94:95], v205 offset:51200
	s_waitcnt lgkmcnt(0)
	v_mfma_f32_16x16x32_f16 v[92:95], v[92:95], v[104:107], v[76:79]
	s_nop 2
	ds_read_b64_tr_b16 v[76:77], v205 offset:48672
	ds_read_b64_tr_b16 v[78:79], v205 offset:51232
	s_waitcnt lgkmcnt(0)
	v_mfma_f32_16x16x32_f16 v[96:99], v[76:79], v[104:107], v[80:83]
	ds_read_b64_tr_b16 v[76:77], v205 offset:48704
	ds_read_b64_tr_b16 v[78:79], v205 offset:51264
	s_waitcnt lgkmcnt(0)
	v_mfma_f32_16x16x32_f16 v[100:103], v[76:79], v[104:107], v[84:87]
	ds_read_b64_tr_b16 v[76:77], v205 offset:48736
	ds_read_b64_tr_b16 v[78:79], v205 offset:51296
	s_waitcnt lgkmcnt(0)
	v_mfma_f32_16x16x32_f16 v[104:107], v[76:79], v[104:107], v[88:91]
.LBB0_1933:
	s_nop 0
	s_andn2_b64 vcc, exec, s[42:43]
	s_waitcnt lgkmcnt(0)
	s_barrier
	s_cbranch_vccnz .LBB0_2045
	s_cmp_ge_i32 s30, s29
	s_cbranch_scc1 .LBB0_1936
	s_waitcnt vmcnt(0)
	ds_write_b128 v141, v[56:59] offset:12800
	ds_write_b128 v141, v[44:47] offset:23040
	ds_write_b128 v141, v[72:75] offset:33280
	ds_write_b128 v141, v[68:71] offset:43520

; template <int MODE, int TM> ...
;     ...
;   __builtin_amdgcn_s_setprio(1);
; #pragma unroll
;   for (int t = 0; t < 2; ++t) {
;     if (!(TM & (1 << t))) continue;
;     const h16* Ks = t ? Ks1 : Ks0;
; #pragma unroll
;     for (int kt = 0; kt < 4; ++kt) {
;       S[t][kt] = f32x4{0.f, 0.f, 0.f, 0.f};
; #pragma unroll
;       for (int ks = 0; ks < 2; ++ks) {
;         h16x8 Kf = *(const h16x8*)(Ks + (kt * 16 + col) * KP + ks * 32 + q4 * 8);
;         S[t][kt] = __builtin_amdgcn_mfma_f32_16x16x32_f16(Kf, Q[ks], S[t][kt], 0, 0, 0);
;       }
;     }
;   }
;   __builtin_amdgcn_s_setprio(0);
.LBB0_1946:
	s_lshl_b32 s0, s31, 1
	s_add_i32 s2, s0, s20
	s_lshl_b32 s3, s2, 6
	s_cmp_lt_i32 s0, s21
	s_nop 0
	ds_read_b128 v[112:115], v155 offset:53760
	ds_read_b128 v[108:111], v155 offset:53824
	s_mov_b64 s[0:1], -1
	v_or_b32_e32 v0, s3, v154
	s_cbranch_scc1 .LBB0_1980
	s_waitcnt lgkmcnt(1)
	v_mfma_f32_16x16x32_f16 v[76:79], v[112:115], v[4:7], 0
	ds_read_b128 v[80:83], v155 offset:56320
	ds_read_b128 v[116:119], v155 offset:58880
	s_waitcnt lgkmcnt(2)
	v_mfma_f32_16x16x32_f16 v[88:91], v[108:111], v[8:11], v[76:79]
	s_nop 3
	ds_read_b128 v[76:79], v155 offset:56384
	s_waitcnt lgkmcnt(2)
	v_mfma_f32_16x16x32_f16 v[80:83], v[80:83], v[4:7], 0
	s_waitcnt lgkmcnt(0)
	v_mfma_f32_16x16x32_f16 v[84:87], v[76:79], v[8:11], v[80:83]
	ds_read_b128 v[76:79], v155 offset:58944
	v_mfma_f32_16x16x32_f16 v[80:83], v[116:119], v[4:7], 0
	ds_read_b128 v[116:119], v155 offset:61440
	s_waitcnt lgkmcnt(1)
	v_mfma_f32_16x16x32_f16 v[80:83], v[76:79], v[8:11], v[80:83]
	ds_read_b128 v[76:79], v155 offset:61504
	s_waitcnt lgkmcnt(1)
	v_mfma_f32_16x16x32_f16 v[116:119], v[116:119], v[4:7], 0
	s_waitcnt lgkmcnt(0)
	v_mfma_f32_16x16x32_f16 v[76:79], v[76:79], v[8:11], v[116:119]
	s_nop 0
	s_nop 4
	v_sub_u32_e32 v118, v182, v0
	s_cmp_gt_i32 s2, -1
	v_cmp_gt_u32_e32 vcc, s76, v118
	s_cselect_b64 s[0:1], -1, 0
	s_and_b64 s[42:43], s[0:1], vcc
	v_mov_b32_e32 v116, 0xf149f2ca
	v_mov_b32_e32 v117, 0xf149f2ca
	s_and_saveexec_b64 s[0:1], s[42:43]
	s_cbranch_execz .LBB0_1949
	v_lshl_add_u32 v117, v118, 2, v157
	ds_read_b32 v117, v117
	s_waitcnt lgkmcnt(0)
	v_fmac_f32_e32 v117, 0x3e38aa3b, v88

; template <int MODE, int TM> ...
;     ...
;   __builtin_amdgcn_s_setprio(1);
; #pragma unroll
;   for (int t = 0; t < 2; ++t) {
;     if (!(TM & (1 << t))) continue;
;     const h16* Ks = t ? Ks1 : Ks0;
; #pragma unroll
;     for (int kt = 0; kt < 4; ++kt) {
;     ...
; #pragma unroll
;     for (int t = 0; t < 2; ++t) {
;       if (!(TM & (1 << t))) continue;
;       float mt = -1e30f;
; #pragma unroll
;       for (int kt = 0; kt < 4; ++kt)
; #pragma unroll
;         for (int j = 0; j < 4; ++j) mt = fmaxf(mt, S[t][kt][j]);
;       mx = fmaxf(mx, mt * sclc[t] + addc[t]);
;     }
;     mx = max4q(mx);
;     const float mn = fmaxf(st.m, mx);
;     const float corr = __builtin_amdgcn_exp2f(st.m - mn);
;     st.m = mn;
;     const float mm = fmaxf(mn, -1e20f);
;     float ls = 0.f;
; #pragma unroll
;     for (int t = 0; t < 2; ++t) {
;       if (!(TM & (1 << t))) continue;
;       const float am = addc[t] - mm;
; #pragma unroll
;       for (int kt = 0; kt < 4; ++kt) {
;         const f32x4 e = S[t][kt] * sclc[t] + am;
; #pragma unroll
;         for (int j = 0; j < 4; ++j) {
;           float pv = __builtin_amdgcn_exp2f(e[j]);
;           S[t][kt][j] = pv;
;           ls += pv;
;         }
;       }
;     }
;     st.l = st.l * corr + ls;
;     if (MODE != M_CMPA) {
; #pragma unroll
;       for (int nt = 0; nt < 4; ++nt) O[nt] *= corr;
;     }
;   }
;   if (MODE == M_CMPA) return;
;   __builtin_amdgcn_s_setprio(1);
; #pragma unroll
;   for (int t = 0; t < 2; ++t) {
;     if (!(TM & (1 << t))) continue;
;     const h16* Vt = t ? Vt1 : Vt0;
; #pragma unroll
;     for (int ks = 0; ks < 2; ++ks) {
;       h16x8 Pf;
; #pragma unroll
;       for (int i = 0; i < 4; ++i) { Pf[i] = (h16)S[t][2 * ks][i]; Pf[4 + i] = (h16)S[t][2 * ks + 1][i]; }
; #pragma unroll
;       for (int nt = 0; nt < 4; ++nt) {
;         const h16* vp = Vt + (ks * 32 + q4 * 4 + (col >> 2)) * KP + nt * 16 + 4 * (col & 3);
;         const s16x4v r0 = __builtin_amdgcn_ds_read_tr16_b64_v4i16((LAS s16x4v*)vp);
;         const s16x4v r1 = __builtin_amdgcn_ds_read_tr16_b64_v4i16((LAS s16x4v*)(vp + 16 * KP));
;         const h16x4 v0 = __builtin_bit_cast(h16x4, r0), v1 = __builtin_bit_cast(h16x4, r1);
;         const h16x8 Vf = {v0[0], v0[1], v0[2], v0[3], v1[0], v1[1], v1[2], v1[3]};
;         O[nt] = __builtin_amdgcn_mfma_f32_16x16x32_f16(Vf, Pf, O[nt], 0, 0, 0);
;       }
;     }
;   }
;   __builtin_amdgcn_s_setprio(0);
.LBB0_1979:
	s_or_b64 exec, exec, s[0:1]
	v_max3_f32 v78, v117, s67, v116
	v_max3_f32 v78, v78, v89, v88
	v_max3_f32 v78, v78, v91, v90
	v_max3_f32 v78, v78, v85, v84
	v_max3_f32 v78, v78, v87, v86
	v_max3_f32 v78, v78, v81, v80
	v_max3_f32 v78, v78, v83, v82
	v_max3_f32 v78, v78, v77, v76
	v_add_f32_e32 v78, 0, v78
	v_max_f32_e32 v78, 0xf149f2ca, v78
	v_mov_b32_e32 v79, v78
	s_nop 1
	v_permlane16_swap_b32_e32 v79, v78
	s_waitcnt lgkmcnt(0)
	v_max_f32_e32 v79, v79, v79
	v_max_f32_e32 v78, v78, v79
	v_mov_b32_e32 v79, v78
	s_nop 1
	v_permlane32_swap_b32_e32 v78, v79
	v_max3_f32 v126, v2, v78, v79
	v_max_f32_e32 v79, 0xe0ad78ec, v126
	v_add_f32_e64 v117, v117, -v79
	v_add_f32_e64 v116, v116, -v79
	v_exp_f32_e32 v120, v117
	v_exp_f32_e32 v116, v116
	v_add_f32_e64 v89, v89, -v79
	v_add_f32_e64 v88, v88, -v79
	v_exp_f32_e32 v117, v89
	v_add_f32_e32 v89, 0, v120
	v_exp_f32_e32 v121, v88
	v_add_f32_e64 v88, v91, -v79
	v_exp_f32_e32 v118, v88
	v_add_f32_e32 v88, v116, v89
	v_add_f32_e64 v89, v90, -v79
	v_exp_f32_e32 v122, v89
	v_add_f32_e64 v85, v85, -v79
	v_add_f32_e32 v88, v117, v88
	v_exp_f32_e32 v119, v85
	v_add_f32_e64 v84, v84, -v79
	v_add_f32_e32 v88, v121, v88
	v_exp_f32_e32 v123, v84
	v_add_f32_e64 v84, v87, -v79
	v_add_f32_e32 v88, v118, v88
	v_exp_f32_e32 v173, v84
	v_add_f32_e64 v85, v86, -v79
	v_add_f32_e32 v84, v122, v88
	v_exp_f32_e32 v188, v85
	v_add_f32_e64 v81, v81, -v79
	v_add_f32_e32 v84, v119, v84
	v_exp_f32_e32 v189, v81
	v_add_f32_e64 v80, v80, -v79
	v_add_f32_e32 v84, v123, v84
	v_exp_f32_e32 v243, v80
	v_add_f32_e64 v80, v83, -v79
	v_add_f32_e32 v84, v173, v84
	v_exp_f32_e32 v248, v80
	v_add_f32_e64 v81, v82, -v79
	v_add_f32_e32 v80, v188, v84
	v_exp_f32_e32 v249, v81
	v_add_f32_e64 v77, v77, -v79
	v_add_f32_e32 v80, v189, v80
	v_exp_f32_e32 v250, v77
	v_add_f32_e64 v76, v76, -v79
	v_sub_f32_e32 v78, v2, v126
	v_add_f32_e32 v80, v243, v80
	v_exp_f32_e32 v251, v76
	v_add_f32_e32 v80, v248, v80
	v_exp_f32_e32 v88, v78
	v_add_f32_e32 v76, v249, v80
	v_add_f32_e32 v76, v250, v76
	v_add_f32_e32 v127, v251, v76
	v_fmac_f32_e32 v127, v3, v88
	v_pk_mul_f32 v[78:79], v[94:95], v[88:89] op_sel_hi:[1,0]
	v_pk_mul_f32 v[76:77], v[92:93], v[88:89] op_sel_hi:[1,0]
	v_pk_mul_f32 v[82:83], v[98:99], v[88:89] op_sel_hi:[1,0]
	v_pk_mul_f32 v[80:81], v[96:97], v[88:89] op_sel_hi:[1,0]
	v_pk_mul_f32 v[86:87], v[102:103], v[88:89] op_sel_hi:[1,0]
	v_pk_mul_f32 v[84:85], v[100:101], v[88:89] op_sel_hi:[1,0]
	v_pk_mul_f32 v[90:91], v[106:107], v[88:89] op_sel_hi:[1,0]
	v_pk_mul_f32 v[88:89], v[104:105], v[88:89] op_sel_hi:[1,0]
	s_nop 0
	v_cvt_pk_f16_f32 v119, v119, v123
	v_cvt_pk_f16_f32 v118, v118, v122
	v_cvt_pk_f16_f32 v117, v117, v121
	v_cvt_pk_f16_f32 v116, v120, v116
	ds_read_b64_tr_b16 v[122:123], v206 offset:2560
	ds_read_b64_tr_b16 v[246:247], v206 offset:2592
	ds_read_b64_tr_b16 v[120:121], v205 offset:64000
	ds_read_b64_tr_b16 v[244:245], v205 offset:64032
	s_waitcnt lgkmcnt(1)
	v_mfma_f32_16x16x32_f16 v[76:79], v[120:123], v[116:119], v[76:79]
	ds_read_b64_tr_b16 v[120:121], v205 offset:64064
	ds_read_b64_tr_b16 v[122:123], v206 offset:2624
	s_mov_b64 s[0:1], 0
	s_waitcnt lgkmcnt(0)
	v_mfma_f32_16x16x32_f16 v[84:87], v[120:123], v[116:119], v[84:87]
	ds_read_b64_tr_b16 v[120:121], v205 offset:64096
	ds_read_b64_tr_b16 v[122:123], v206 offset:2656
	s_waitcnt lgkmcnt(0)
	v_mfma_f32_16x16x32_f16 v[88:91], v[120:123], v[116:119], v[88:91]
	ds_read_b64_tr_b16 v[120:121], v206 offset:5120
	ds_read_b64_tr_b16 v[122:123], v206 offset:7680
	v_mfma_f32_16x16x32_f16 v[80:83], v[244:247], v[116:119], v[80:83]
	v_cvt_pk_f16_f32 v119, v250, v251
	v_cvt_pk_f16_f32 v118, v248, v249
	v_cvt_pk_f16_f32 v117, v189, v243
	v_cvt_pk_f16_f32 v116, v173, v188
	s_waitcnt lgkmcnt(0)
	s_nop 0
	v_mfma_f32_16x16x32_f16 v[76:79], v[120:123], v[116:119], v[76:79]
	ds_read_b64_tr_b16 v[120:121], v206 offset:5152
	ds_read_b64_tr_b16 v[122:123], v206 offset:7712
	s_waitcnt lgkmcnt(0)
	v_mfma_f32_16x16x32_f16 v[80:83], v[120:123], v[116:119], v[80:83]
	ds_read_b64_tr_b16 v[120:121], v206 offset:5184
	ds_read_b64_tr_b16 v[122:123], v206 offset:7744
	s_waitcnt lgkmcnt(0)
	v_mfma_f32_16x16x32_f16 v[84:87], v[120:123], v[116:119], v[84:87]
	ds_read_b64_tr_b16 v[120:121], v206 offset:5216
	ds_read_b64_tr_b16 v[122:123], v206 offset:7776
	s_waitcnt lgkmcnt(0)
	v_mfma_f32_16x16x32_f16 v[88:91], v[120:123], v[116:119], v[88:91]
.LBB0_1980:
	s_and_b64 vcc, exec, s[0:1]
	s_cbranch_vccz .LBB0_1820
	s_waitcnt lgkmcnt(1)
	v_mfma_f32_16x16x32_f16 v[76:79], v[112:115], v[4:7], 0
	ds_read_b128 v[80:83], v155 offset:56320
	ds_read_b128 v[84:87], v155 offset:58880
	ds_read_b128 v[244:247], v202 offset:5120
	s_waitcnt lgkmcnt(3)
	v_mfma_f32_16x16x32_f16 v[120:123], v[108:111], v[8:11], v[76:79]
	s_nop 2
	ds_read_b128 v[76:79], v155 offset:56384
	s_waitcnt lgkmcnt(3)
	v_mfma_f32_16x16x32_f16 v[80:83], v[80:83], v[4:7], 0
	s_waitcnt lgkmcnt(0)
	v_mfma_f32_16x16x32_f16 v[116:119], v[76:79], v[8:11], v[80:83]
	ds_read_b128 v[76:79], v155 offset:58944
	v_mfma_f32_16x16x32_f16 v[80:83], v[84:87], v[4:7], 0
	ds_read_b128 v[84:87], v155 offset:61440
	s_waitcnt lgkmcnt(1)
	v_mfma_f32_16x16x32_f16 v[112:115], v[76:79], v[8:11], v[80:83]
	ds_read_b128 v[76:79], v155 offset:61504
	s_waitcnt lgkmcnt(1)
	v_mfma_f32_16x16x32_f16 v[80:83], v[84:87], v[4:7], 0
	ds_read_b128 v[84:87], v202
	s_waitcnt lgkmcnt(1)
	v_mfma_f32_16x16x32_f16 v[108:111], v[76:79], v[8:11], v[80:83]
	ds_read_b128 v[76:79], v202 offset:64
	s_waitcnt lgkmcnt(1)
	v_mfma_f32_16x16x32_f16 v[80:83], v[84:87], v[4:7], 0
	ds_read_b128 v[84:87], v202 offset:2560
	s_waitcnt lgkmcnt(1)
	v_mfma_f32_16x16x32_f16 v[88:91], v[76:79], v[8:11], v[80:83]
	ds_read_b128 v[76:79], v202 offset:2624
	s_waitcnt lgkmcnt(1)
	v_mfma_f32_16x16x32_f16 v[80:83], v[84:87], v[4:7], 0
	s_waitcnt lgkmcnt(0)
	v_mfma_f32_16x16x32_f16 v[84:87], v[76:79], v[8:11], v[80:83]
	ds_read_b128 v[76:79], v202 offset:5184
	v_mfma_f32_16x16x32_f16 v[80:83], v[244:247], v[4:7], 0
	ds_read_b128 v[244:247], v202 offset:7680
	s_waitcnt lgkmcnt(1)
	v_mfma_f32_16x16x32_f16 v[80:83], v[76:79], v[8:11], v[80:83]
	ds_read_b128 v[76:79], v202 offset:7744
	s_waitcnt lgkmcnt(1)
	v_mfma_f32_16x16x32_f16 v[244:247], v[244:247], v[4:7], 0
	s_waitcnt lgkmcnt(0)
	v_mfma_f32_16x16x32_f16 v[76:79], v[76:79], v[8:11], v[244:247]
	s_nop 0
	v_sub_u32_e32 v126, v182, v0
	s_cmp_gt_i32 s2, -1
	v_cmp_gt_u32_e32 vcc, s76, v126
	s_cselect_b64 s[0:1], -1, 0
	s_and_b64 s[2:3], s[0:1], vcc
	v_mov_b32_e32 v127, 0xf149f2ca
	v_mov_b32_e32 v173, 0xf149f2ca
	s_and_saveexec_b64 s[0:1], s[2:3]
	s_cbranch_execz .LBB0_1983
	v_lshl_add_u32 v126, v126, 2, v157
	ds_read_b32 v173, v126
	s_waitcnt lgkmcnt(0)
	v_fmac_f32_e32 v173, 0x3e38aa3b, v120

; __device__ __forceinline__ int fetch_unit(unsigned* ctr, int* slot) {
;   __syncthreads();
;   if (threadIdx.x == 0) *slot = (int)atomicAdd(ctr, 1u);
;   __syncthreads();
;   return *slot;
; }
;     ...
;     ColState st;
.LBB0_2053:
	s_setprio 0
	v_mov_b32_e32 v38, v145
	s_mov_b32 s3, 0
	s_mov_b32 s2, 0
	s_mov_b32 s8, 0
	s_barrier
	s_mov_b64 s[0:1], exec
	v_readlane_b32 s4, v254, 0
	v_readlane_b32 s5, v254, 1
	s_and_b64 s[4:5], s[0:1], s[4:5]
	s_mov_b64 exec, s[4:5]
	s_cbranch_execz .LBB0_2057
	s_mov_b64 s[6:7], exec
	v_mbcnt_lo_u32_b32 v0, s6, 0
	v_mbcnt_hi_u32_b32 v0, s7, v0
	v_cmp_eq_u32_e32 vcc, 0, v0
	s_and_saveexec_b64 s[4:5], vcc
	s_cbranch_execz .LBB0_2056
	s_bcnt1_i32_b64 s6, s[6:7]
	v_mov_b32_e32 v2, s6
	v_readlane_b32 s6, v255, 32
	v_readlane_b32 s7, v255, 33
	s_nop 4
	global_atomic_add v2, v1, v2, s[6:7] offset:256 sc0
